# s_setprio 1 raised before the pre-cluster barrier (first MFMA issues right after the first ladder wait)
# speedup vs baseline: 1.0030x; 1.0030x over previous
.LBB0_403:
	s_add_u32 s14, s4, 0x100
	s_addc_u32 s15, s5, 0
	s_add_i32 s38, 0, 0x10000
	v_add_u32_e32 v12, s38, v193
	ds_read_b128 v[0:3], v12
	ds_read_b128 v[8:11], v12 offset:2048
	ds_read_b128 v[4:7], v12 offset:1024
	ds_read_b128 v[12:15], v12 offset:3072
	s_cmp_eq_u32 s37, 12
	s_cselect_b32 s19, s9, s15
	s_cselect_b32 s18, s8, s14
	s_cselect_b32 s17, s11, s36
	s_cselect_b32 s16, s10, s7
	v_lshl_add_u64 v[190:191], s[4:5], 0, v[186:187]
	s_add_i32 m0, s23, 0xc000
	ds_read_b128 v[16:19], v206
	ds_read_b128 v[24:27], v206 offset:2048
	ds_read_b128 v[162:165], v206 offset:4096
	ds_read_b128 v[170:173], v206 offset:6144
	ds_read_b128 v[20:23], v206 offset:1024
	ds_read_b128 v[28:31], v206 offset:3072
	ds_read_b128 v[166:169], v206 offset:5120
	ds_read_b128 v[174:177], v206 offset:7168
	global_load_lds_dwordx4 v[190:191], off
	v_lshl_add_u64 v[190:191], s[4:5], 0, v[188:189]
	s_add_i32 m0, s23, 0xe000
	s_nop 0
	global_load_lds_dwordx4 v[190:191], off
	s_waitcnt lgkmcnt(8)
	s_setprio 1
	s_barrier
	s_waitcnt lgkmcnt(7)
	v_mfma_f32_16x16x32_f16 v[158:161], v[0:3], v[16:19], v[158:161]
	v_mfma_f32_16x16x32_f16 v[142:145], v[8:11], v[16:19], v[142:145]
	s_waitcnt lgkmcnt(6)
	v_mfma_f32_16x16x32_f16 v[150:153], v[0:3], v[24:27], v[150:153]
	v_mfma_f32_16x16x32_f16 v[134:137], v[8:11], v[24:27], v[134:137]
	s_waitcnt lgkmcnt(5)
	v_mfma_f32_16x16x32_f16 v[154:157], v[0:3], v[162:165], v[154:157]
	v_mfma_f32_16x16x32_f16 v[138:141], v[8:11], v[162:165], v[138:141]
	s_waitcnt lgkmcnt(4)
	v_mfma_f32_16x16x32_f16 v[146:149], v[0:3], v[170:173], v[146:149]
	v_mfma_f32_16x16x32_f16 v[130:133], v[8:11], v[170:173], v[130:133]
	s_waitcnt lgkmcnt(3)
	v_mfma_f32_16x16x32_f16 v[158:161], v[4:7], v[20:23], v[158:161]
	v_mfma_f32_16x16x32_f16 v[142:145], v[12:15], v[20:23], v[142:145]
	s_waitcnt lgkmcnt(2)
	v_mfma_f32_16x16x32_f16 v[150:153], v[4:7], v[28:31], v[150:153]
	v_mfma_f32_16x16x32_f16 v[134:137], v[12:15], v[28:31], v[134:137]
	s_waitcnt lgkmcnt(1)
	v_mfma_f32_16x16x32_f16 v[154:157], v[4:7], v[166:169], v[154:157]
	v_mfma_f32_16x16x32_f16 v[138:141], v[12:15], v[166:169], v[138:141]
	s_waitcnt lgkmcnt(0)
	v_mfma_f32_16x16x32_f16 v[146:149], v[4:7], v[174:177], v[146:149]
	v_mfma_f32_16x16x32_f16 v[130:133], v[12:15], v[174:177], v[130:133]
	s_setprio 0
	s_barrier
	s_add_i32 s39, 0, 0x14000
	s_add_i32 s4, s38, s22
	v_add_u32_e32 v32, s39, v193
	v_lshl_add_u64 v[190:191], s[16:17], 0, v[178:179]
	s_mov_b32 m0, s4
	ds_read_b128 v[208:211], v32
	ds_read_b128 v[216:219], v32 offset:2048
	ds_read_b128 v[212:215], v32 offset:1024
	ds_read_b128 v[230:233], v32 offset:3072
	global_load_lds_dwordx4 v[190:191], off
	v_lshl_add_u64 v[238:239], s[16:17], 0, v[180:181]
	s_add_i32 m0, s4, 0x2000
	s_nop 0
	global_load_lds_dwordx4 v[238:239], off
	s_setprio 1
	s_barrier
	s_waitcnt lgkmcnt(2)
	v_mfma_f32_16x16x32_f16 v[94:97], v[208:211], v[16:19], v[94:97]
	v_mfma_f32_16x16x32_f16 v[16:19], v[216:219], v[16:19], v[78:81]
	s_waitcnt lgkmcnt(0)
	v_mfma_f32_16x16x32_f16 v[94:97], v[212:215], v[20:23], v[94:97]
	v_mfma_f32_16x16x32_f16 v[16:19], v[230:233], v[20:23], v[16:19]
	v_mfma_f32_16x16x32_f16 v[20:23], v[208:211], v[24:27], v[86:89]
	v_mfma_f32_16x16x32_f16 v[24:27], v[216:219], v[24:27], v[70:73]
	v_mfma_f32_16x16x32_f16 v[70:73], v[216:219], v[162:165], v[74:77]
	v_mfma_f32_16x16x32_f16 v[74:77], v[230:233], v[166:169], v[70:73]
	v_mfma_f32_16x16x32_f16 v[70:73], v[208:211], v[170:173], v[82:85]
	v_mfma_f32_16x16x32_f16 v[66:69], v[216:219], v[170:173], v[66:69]
	v_mfma_f32_16x16x32_f16 v[20:23], v[212:215], v[28:31], v[20:23]
	v_mfma_f32_16x16x32_f16 v[24:27], v[230:233], v[28:31], v[24:27]
	v_mfma_f32_16x16x32_f16 v[28:31], v[208:211], v[162:165], v[90:93]
	v_mfma_f32_16x16x32_f16 v[82:85], v[212:215], v[174:177], v[70:73]
	v_mfma_f32_16x16x32_f16 v[66:69], v[230:233], v[174:177], v[66:69]
	v_mfma_f32_16x16x32_f16 v[28:31], v[212:215], v[166:169], v[28:31]
	s_setprio 0
	s_mov_b32 m0, s23
	v_lshl_add_u64 v[240:241], s[18:19], 0, v[178:179]
	s_barrier
	ds_read_b128 v[70:73], v206 offset:16384
	ds_read_b128 v[86:89], v206 offset:18432
	ds_read_b128 v[162:165], v206 offset:20480
	ds_read_b128 v[170:173], v206 offset:22528
	ds_read_b128 v[78:81], v206 offset:17408
	ds_read_b128 v[90:93], v206 offset:19456
	ds_read_b128 v[166:169], v206 offset:21504
	ds_read_b128 v[174:177], v206 offset:23552
	global_load_lds_dwordx4 v[240:241], off
	v_lshl_add_u64 v[242:243], s[18:19], 0, v[180:181]
	s_mov_b32 m0, s24
	s_nop 0
	global_load_lds_dwordx4 v[242:243], off
	s_setprio 1
	s_barrier
	s_waitcnt lgkmcnt(7)
	v_mfma_f32_16x16x32_f16 v[126:129], v[0:3], v[70:73], v[126:129]
	v_mfma_f32_16x16x32_f16 v[110:113], v[8:11], v[70:73], v[110:113]
	s_waitcnt lgkmcnt(6)
	v_mfma_f32_16x16x32_f16 v[118:121], v[0:3], v[86:89], v[118:121]
	v_mfma_f32_16x16x32_f16 v[102:105], v[8:11], v[86:89], v[102:105]
	s_waitcnt lgkmcnt(5)
	v_mfma_f32_16x16x32_f16 v[122:125], v[0:3], v[162:165], v[122:125]
	v_mfma_f32_16x16x32_f16 v[106:109], v[8:11], v[162:165], v[106:109]
	s_waitcnt lgkmcnt(3)
	v_mfma_f32_16x16x32_f16 v[0:3], v[0:3], v[170:173], v[114:117]
	v_mfma_f32_16x16x32_f16 v[126:129], v[4:7], v[78:81], v[126:129]
	s_waitcnt lgkmcnt(2)
	v_mfma_f32_16x16x32_f16 v[110:113], v[12:15], v[78:81], v[110:113]
	v_mfma_f32_16x16x32_f16 v[118:121], v[4:7], v[90:93], v[118:121]
	s_waitcnt lgkmcnt(1)
	v_mfma_f32_16x16x32_f16 v[102:105], v[12:15], v[90:93], v[102:105]
	v_mfma_f32_16x16x32_f16 v[122:125], v[4:7], v[166:169], v[122:125]
	s_waitcnt lgkmcnt(0)
	v_mfma_f32_16x16x32_f16 v[106:109], v[12:15], v[166:169], v[106:109]
	v_mfma_f32_16x16x32_f16 v[0:3], v[4:7], v[174:177], v[0:3]
	v_mfma_f32_16x16x32_f16 v[4:7], v[8:11], v[170:173], v[98:101]
	v_mfma_f32_16x16x32_f16 v[4:7], v[12:15], v[174:177], v[4:7]
	s_setprio 0
	s_barrier
	s_add_u32 s4, s16, 0x40000
	s_addc_u32 s5, s17, 0
	s_add_i32 s38, s39, s22
	v_lshl_add_u64 v[8:9], s[4:5], 0, v[178:179]
	s_mov_b32 m0, s38
	s_nop 0
	global_load_lds_dwordx4 v[8:9], off
	v_lshl_add_u64 v[8:9], s[4:5], 0, v[180:181]
	s_add_i32 m0, s38, 0x2000
	s_nop 0
	global_load_lds_dwordx4 v[8:9], off
	s_waitcnt vmcnt(6)
	s_setprio 1
	s_barrier
	v_mfma_f32_16x16x32_f16 v[12:15], v[216:219], v[70:73], v[46:49]
	v_mfma_f32_16x16x32_f16 v[46:49], v[208:211], v[86:89], v[54:57]
	v_mfma_f32_16x16x32_f16 v[54:57], v[212:215], v[90:93], v[46:49]
	v_mfma_f32_16x16x32_f16 v[46:49], v[208:211], v[162:165], v[58:61]
	v_mfma_f32_16x16x32_f16 v[38:41], v[216:219], v[86:89], v[38:41]
	v_mfma_f32_16x16x32_f16 v[58:61], v[212:215], v[166:169], v[46:49]
	v_mfma_f32_16x16x32_f16 v[42:45], v[216:219], v[162:165], v[42:45]
	v_mfma_f32_16x16x32_f16 v[46:49], v[208:211], v[170:173], v[50:53]
	v_mfma_f32_16x16x32_f16 v[34:37], v[216:219], v[170:173], v[34:37]
	v_mfma_f32_16x16x32_f16 v[8:11], v[208:211], v[70:73], v[62:65]
	v_mfma_f32_16x16x32_f16 v[38:41], v[230:233], v[90:93], v[38:41]
	v_mfma_f32_16x16x32_f16 v[42:45], v[230:233], v[166:169], v[42:45]
	v_mfma_f32_16x16x32_f16 v[50:53], v[212:215], v[174:177], v[46:49]
	v_mfma_f32_16x16x32_f16 v[34:37], v[230:233], v[174:177], v[34:37]
	v_mfma_f32_16x16x32_f16 v[8:11], v[212:215], v[78:81], v[8:11]
	v_mfma_f32_16x16x32_f16 v[12:15], v[230:233], v[78:81], v[12:15]
	s_setprio 0
	s_add_i32 s38, 0, 0x18000
	v_add_u32_e32 v32, s38, v193
	s_barrier
	ds_read_b128 v[46:49], v32
	ds_read_b128 v[62:65], v32 offset:1024
	ds_read_b128 v[98:101], v32 offset:2048
	ds_read_b128 v[162:165], v32 offset:3072
	s_add_u32 s4, s18, 0x40000
	s_addc_u32 s5, s19, 0
	s_mov_b32 m0, s25
	v_lshl_add_u64 v[86:87], s[4:5], 0, v[178:179]
	ds_read_b128 v[70:73], v206 offset:32768
	ds_read_b128 v[78:81], v206 offset:33792
	ds_read_b128 v[90:93], v206 offset:34816
	ds_read_b128 v[114:117], v206 offset:35840
	ds_read_b128 v[166:169], v206 offset:36864
	ds_read_b128 v[170:173], v206 offset:37888
	ds_read_b128 v[174:177], v206 offset:38912
	ds_read_b128 v[208:211], v206 offset:39936
	global_load_lds_dwordx4 v[86:87], off
	v_lshl_add_u64 v[86:87], s[4:5], 0, v[180:181]
	s_mov_b32 m0, s26
	s_nop 0
	global_load_lds_dwordx4 v[86:87], off
	s_waitcnt lgkmcnt(8)
	s_setprio 1
	s_barrier
	s_waitcnt lgkmcnt(6)
	v_mfma_f32_16x16x32_f16 v[86:89], v[46:49], v[70:73], v[158:161]
	v_mfma_f32_16x16x32_f16 v[158:161], v[62:65], v[78:81], v[86:89]
	v_mfma_f32_16x16x32_f16 v[86:89], v[98:101], v[70:73], v[142:145]
	v_mfma_f32_16x16x32_f16 v[142:145], v[162:165], v[78:81], v[86:89]
	s_waitcnt lgkmcnt(4)
	v_mfma_f32_16x16x32_f16 v[86:89], v[46:49], v[90:93], v[150:153]
	v_mfma_f32_16x16x32_f16 v[150:153], v[62:65], v[114:117], v[86:89]
	v_mfma_f32_16x16x32_f16 v[86:89], v[98:101], v[90:93], v[134:137]
	v_mfma_f32_16x16x32_f16 v[134:137], v[162:165], v[114:117], v[86:89]
	s_waitcnt lgkmcnt(2)
	v_mfma_f32_16x16x32_f16 v[86:89], v[46:49], v[166:169], v[154:157]
	v_mfma_f32_16x16x32_f16 v[154:157], v[62:65], v[170:173], v[86:89]
	v_mfma_f32_16x16x32_f16 v[86:89], v[98:101], v[166:169], v[138:141]
	v_mfma_f32_16x16x32_f16 v[138:141], v[162:165], v[170:173], v[86:89]
	s_waitcnt lgkmcnt(0)
	v_mfma_f32_16x16x32_f16 v[86:89], v[46:49], v[174:177], v[146:149]
	v_mfma_f32_16x16x32_f16 v[146:149], v[62:65], v[208:211], v[86:89]
	v_mfma_f32_16x16x32_f16 v[86:89], v[98:101], v[174:177], v[130:133]
	v_mfma_f32_16x16x32_f16 v[130:133], v[162:165], v[208:211], v[86:89]
	s_setprio 0
	s_barrier
	s_add_i32 s18, 0, 0x1c000
	s_add_i32 s4, s38, s22
	v_add_u32_e32 v32, s18, v193
	s_nop 1
	v_lshl_add_u64 v[86:87], v[190:191], 0, s[84:85]
	s_mov_b32 m0, s4
	ds_read_b128 v[212:215], v32
	ds_read_b128 v[230:233], v32 offset:2048
	ds_read_b128 v[216:219], v32 offset:1024
	ds_read_b128 v[234:237], v32 offset:3072
	global_load_lds_dwordx4 v[86:87], off
	v_lshl_add_u64 v[86:87], v[238:239], 0, s[84:85]
	s_add_i32 m0, s4, 0x2000
	s_nop 0
	global_load_lds_dwordx4 v[86:87], off
	s_setprio 1
	s_barrier
	s_waitcnt lgkmcnt(2)
	v_mfma_f32_16x16x32_f16 v[86:89], v[212:215], v[70:73], v[94:97]
	v_mfma_f32_16x16x32_f16 v[16:19], v[230:233], v[70:73], v[16:19]
	s_waitcnt lgkmcnt(0)
	v_mfma_f32_16x16x32_f16 v[94:97], v[216:219], v[78:81], v[86:89]
	v_mfma_f32_16x16x32_f16 v[78:81], v[234:237], v[78:81], v[16:19]
	v_mfma_f32_16x16x32_f16 v[16:19], v[212:215], v[90:93], v[20:23]
	v_mfma_f32_16x16x32_f16 v[86:89], v[216:219], v[114:117], v[16:19]
	v_mfma_f32_16x16x32_f16 v[16:19], v[230:233], v[90:93], v[24:27]
	v_mfma_f32_16x16x32_f16 v[70:73], v[234:237], v[114:117], v[16:19]
	v_mfma_f32_16x16x32_f16 v[16:19], v[212:215], v[166:169], v[28:31]
	v_mfma_f32_16x16x32_f16 v[90:93], v[216:219], v[170:173], v[16:19]
	v_mfma_f32_16x16x32_f16 v[16:19], v[230:233], v[166:169], v[74:77]
	v_mfma_f32_16x16x32_f16 v[74:77], v[234:237], v[170:173], v[16:19]
	v_mfma_f32_16x16x32_f16 v[16:19], v[212:215], v[174:177], v[82:85]
	v_mfma_f32_16x16x32_f16 v[82:85], v[216:219], v[208:211], v[16:19]
	v_mfma_f32_16x16x32_f16 v[16:19], v[230:233], v[174:177], v[66:69]
	v_mfma_f32_16x16x32_f16 v[66:69], v[234:237], v[208:211], v[16:19]
	s_setprio 0
	s_mov_b32 m0, s28
	v_lshl_add_u64 v[114:115], v[240:241], 0, s[84:85]
	s_barrier
	s_nop 2
	ds_read_b128 v[16:19], v206 offset:49152
	ds_read_b128 v[20:23], v206 offset:50176
	ds_read_b128 v[24:27], v206 offset:51200
	ds_read_b128 v[28:31], v206 offset:52224
	ds_read_b128 v[166:169], v206 offset:53248
	ds_read_b128 v[174:177], v206 offset:55296
	ds_read_b128 v[170:173], v206 offset:54272
	ds_read_b128 v[208:211], v206 offset:56320
	global_load_lds_dwordx4 v[114:115], off
	v_lshl_add_u64 v[114:115], v[242:243], 0, s[84:85]
	s_mov_b32 m0, s29
	s_nop 0
	global_load_lds_dwordx4 v[114:115], off
	s_setprio 1
	s_barrier
	s_waitcnt lgkmcnt(6)
	v_mfma_f32_16x16x32_f16 v[114:117], v[46:49], v[16:19], v[126:129]
	v_mfma_f32_16x16x32_f16 v[126:129], v[62:65], v[20:23], v[114:117]
	s_waitcnt lgkmcnt(4)
	v_mfma_f32_16x16x32_f16 v[114:117], v[46:49], v[24:27], v[118:121]
	v_mfma_f32_16x16x32_f16 v[118:121], v[62:65], v[28:31], v[114:117]
	s_waitcnt lgkmcnt(2)
	v_mfma_f32_16x16x32_f16 v[114:117], v[46:49], v[166:169], v[122:125]
	v_mfma_f32_16x16x32_f16 v[0:3], v[46:49], v[174:177], v[0:3]
	v_mfma_f32_16x16x32_f16 v[110:113], v[98:101], v[16:19], v[110:113]
	v_mfma_f32_16x16x32_f16 v[102:105], v[98:101], v[24:27], v[102:105]
	s_waitcnt lgkmcnt(1)
	v_mfma_f32_16x16x32_f16 v[122:125], v[62:65], v[170:173], v[114:117]
	v_mfma_f32_16x16x32_f16 v[106:109], v[98:101], v[166:169], v[106:109]
	s_waitcnt lgkmcnt(0)
	v_mfma_f32_16x16x32_f16 v[114:117], v[62:65], v[208:211], v[0:3]
	v_mfma_f32_16x16x32_f16 v[0:3], v[98:101], v[174:177], v[4:7]
	v_mfma_f32_16x16x32_f16 v[110:113], v[162:165], v[20:23], v[110:113]
	v_mfma_f32_16x16x32_f16 v[102:105], v[162:165], v[28:31], v[102:105]
	v_mfma_f32_16x16x32_f16 v[106:109], v[162:165], v[170:173], v[106:109]
	v_mfma_f32_16x16x32_f16 v[98:101], v[162:165], v[208:211], v[0:3]
	s_setprio 0
	s_barrier
	s_add_u32 s4, s16, 0x40080
	s_addc_u32 s5, s17, 0
	s_add_i32 s16, s18, s22
	v_lshl_add_u64 v[0:1], s[4:5], 0, v[178:179]
	s_mov_b32 m0, s16
	s_nop 0
	global_load_lds_dwordx4 v[0:1], off
	v_lshl_add_u64 v[0:1], s[4:5], 0, v[180:181]
	s_add_i32 m0, s16, 0x2000
	s_nop 0
	global_load_lds_dwordx4 v[0:1], off
	s_waitcnt vmcnt(6)
	s_setprio 1
	s_barrier
	v_mfma_f32_16x16x32_f16 v[0:3], v[212:215], v[16:19], v[8:11]
	v_mfma_f32_16x16x32_f16 v[62:65], v[216:219], v[20:23], v[0:3]
	v_mfma_f32_16x16x32_f16 v[0:3], v[230:233], v[16:19], v[12:15]
	v_mfma_f32_16x16x32_f16 v[46:49], v[234:237], v[20:23], v[0:3]
	v_mfma_f32_16x16x32_f16 v[0:3], v[212:215], v[24:27], v[54:57]
	v_mfma_f32_16x16x32_f16 v[54:57], v[216:219], v[28:31], v[0:3]
	v_mfma_f32_16x16x32_f16 v[0:3], v[230:233], v[24:27], v[38:41]
	v_mfma_f32_16x16x32_f16 v[38:41], v[234:237], v[28:31], v[0:3]
	v_mfma_f32_16x16x32_f16 v[0:3], v[212:215], v[166:169], v[58:61]
	v_mfma_f32_16x16x32_f16 v[58:61], v[216:219], v[170:173], v[0:3]
	v_mfma_f32_16x16x32_f16 v[0:3], v[230:233], v[166:169], v[42:45]
	v_mfma_f32_16x16x32_f16 v[42:45], v[234:237], v[170:173], v[0:3]
	v_mfma_f32_16x16x32_f16 v[0:3], v[212:215], v[174:177], v[50:53]
	v_mfma_f32_16x16x32_f16 v[50:53], v[216:219], v[208:211], v[0:3]
	v_mfma_f32_16x16x32_f16 v[0:3], v[230:233], v[174:177], v[34:37]
	v_mfma_f32_16x16x32_f16 v[34:37], v[234:237], v[208:211], v[0:3]
	s_setprio 0
	s_add_i32 s37, s37, 2
	s_add_u32 s7, s7, 0x100
	s_addc_u32 s36, s36, 0
	s_cmp_gt_u32 s37, 13
	s_mov_b64 s[4:5], s[14:15]
	s_barrier
	s_cbranch_scc0 .LBB0_403
	s_lshl_b32 s7, s34, 8
	s_cmp_lt_i32 s35, 28
	s_mov_b64 s[4:5], -1
	s_cbranch_scc0 .LBB0_431
	s_add_i32 s16, s7, s27
	v_or_b32_e32 v207, s16, v192
	s_cmp_gt_i32 s35, 3
	s_cbranch_scc0 .LBB0_411
	s_add_i32 s4, s35, -12
	s_cmp_gt_u32 s4, 7
	s_mov_b64 s[4:5], -1
	s_cbranch_scc0 .LBB0_408
	s_lshl_b32 s4, s35, 8
	s_add_i32 s5, s4, 0xfffffc00
	s_cmp_lt_u32 s35, 12
	s_cselect_b32 s4, s4, s5
	v_and_b32_e32 v10, 7, v220
	v_and_b32_e32 v11, 8, v220
	v_cmp_ne_u32_e32 vcc, 0, v11
	v_and_b32_e32 v12, 0x60, v194
	v_lshlrev_b32_e32 v12, 1, v12
	v_lshl_or_b32 v12, v11, 2, v12
	v_and_b32_e32 v13, 0x18, v194
	v_or_b32_e32 v12, v12, v13
	v_or_b32_e32 v32, s4, v12
	v_or_b32_e32 v14, s16, v10
	v_mov_b64_e32 v[4:5], s[70:71]
	v_mad_i64_i32 v[0:1], s[4:5], v14, s33, v[4:5]
	v_lshlrev_b64 v[6:7], 1, v[32:33]
	v_lshl_add_u64 v[16:17], v[0:1], 0, v[6:7]
	v_mov_b32_e32 v32, 0x30000
	v_lshl_add_u64 v[18:19], v[16:17], 0, v[32:33]
	v_lshl_add_u64 v[20:21], v[18:19], 0, v[32:33]
	v_lshl_add_u64 v[22:23], v[20:21], 0, v[32:33]
	v_mov_b32_e32 v8, 0x180000
	v_mov_b32_e32 v9, 0
	v_lshl_add_u64 v[24:25], v[16:17], 0, v[8:9]
	v_lshl_add_u64 v[26:27], v[24:25], 0, v[32:33]
	v_lshl_add_u64 v[28:29], v[26:27], 0, v[32:33]
	v_lshl_add_u64 v[30:31], v[28:29], 0, v[32:33]
	v_mov_b32_e32 v8, 0x18000
	v_cvt_pk_f16_f32 v158, v158, v159
	v_cvt_pk_f16_f32 v159, v160, v161
	v_cvt_pk_f16_f32 v160, v142, v143
	v_cvt_pk_f16_f32 v161, v144, v145
	v_cvt_pk_f16_f32 v94, v94, v95
	v_cvt_pk_f16_f32 v95, v96, v97
	v_cvt_pk_f16_f32 v96, v78, v79
	v_cvt_pk_f16_f32 v97, v80, v81
	v_mov_b32_dpp v0, v158 row_ror:8 row_mask:0xf bank_mask:0xf
	v_mov_b32_dpp v1, v159 row_ror:8 row_mask:0xf bank_mask:0xf
	v_mov_b32_dpp v2, v160 row_ror:8 row_mask:0xf bank_mask:0xf
	v_mov_b32_dpp v3, v161 row_ror:8 row_mask:0xf bank_mask:0xf
	v_mov_b32_dpp v4, v94 row_ror:8 row_mask:0xf bank_mask:0xf
	v_mov_b32_dpp v5, v95 row_ror:8 row_mask:0xf bank_mask:0xf
	v_mov_b32_dpp v6, v96 row_ror:8 row_mask:0xf bank_mask:0xf
	v_mov_b32_dpp v7, v97 row_ror:8 row_mask:0xf bank_mask:0xf
	v_cndmask_b32_e32 v158, v158, v4, vcc
	v_cndmask_b32_e32 v159, v159, v5, vcc
	v_cndmask_b32_e32 v160, v160, v6, vcc
	v_cndmask_b32_e32 v161, v161, v7, vcc
	v_cndmask_b32_e32 v94, v0, v94, vcc
	v_cndmask_b32_e32 v95, v1, v95, vcc
	v_cndmask_b32_e32 v96, v2, v96, vcc
	v_cndmask_b32_e32 v97, v3, v97, vcc
	v_lshl_add_u64 v[10:11], v[16:17], 0, v[8:9]
	global_store_dwordx4 v[16:17], v[158:161], off
	global_store_dwordx4 v[10:11], v[94:97], off
	v_cvt_pk_f16_f32 v150, v150, v151
	v_cvt_pk_f16_f32 v151, v152, v153
	v_cvt_pk_f16_f32 v152, v134, v135
	v_cvt_pk_f16_f32 v153, v136, v137
	v_cvt_pk_f16_f32 v86, v86, v87
	v_cvt_pk_f16_f32 v87, v88, v89
	v_cvt_pk_f16_f32 v88, v70, v71
	v_cvt_pk_f16_f32 v89, v72, v73
	v_mov_b32_dpp v0, v150 row_ror:8 row_mask:0xf bank_mask:0xf
	v_mov_b32_dpp v1, v151 row_ror:8 row_mask:0xf bank_mask:0xf
	v_mov_b32_dpp v2, v152 row_ror:8 row_mask:0xf bank_mask:0xf
	v_mov_b32_dpp v3, v153 row_ror:8 row_mask:0xf bank_mask:0xf
	v_mov_b32_dpp v4, v86 row_ror:8 row_mask:0xf bank_mask:0xf
	v_mov_b32_dpp v5, v87 row_ror:8 row_mask:0xf bank_mask:0xf
	v_mov_b32_dpp v6, v88 row_ror:8 row_mask:0xf bank_mask:0xf
	v_mov_b32_dpp v7, v89 row_ror:8 row_mask:0xf bank_mask:0xf
	v_cndmask_b32_e32 v150, v150, v4, vcc
	v_cndmask_b32_e32 v151, v151, v5, vcc
	v_cndmask_b32_e32 v152, v152, v6, vcc
	v_cndmask_b32_e32 v153, v153, v7, vcc
	v_cndmask_b32_e32 v86, v0, v86, vcc
	v_cndmask_b32_e32 v87, v1, v87, vcc
	v_cndmask_b32_e32 v88, v2, v88, vcc
	v_cndmask_b32_e32 v89, v3, v89, vcc
	v_lshl_add_u64 v[10:11], v[18:19], 0, v[8:9]
	global_store_dwordx4 v[18:19], v[150:153], off
	global_store_dwordx4 v[10:11], v[86:89], off
	v_cvt_pk_f16_f32 v154, v154, v155
	v_cvt_pk_f16_f32 v155, v156, v157
	v_cvt_pk_f16_f32 v156, v138, v139
	v_cvt_pk_f16_f32 v157, v140, v141
	v_cvt_pk_f16_f32 v90, v90, v91
	v_cvt_pk_f16_f32 v91, v92, v93
	v_cvt_pk_f16_f32 v92, v74, v75
	v_cvt_pk_f16_f32 v93, v76, v77
	v_mov_b32_dpp v0, v154 row_ror:8 row_mask:0xf bank_mask:0xf
	v_mov_b32_dpp v1, v155 row_ror:8 row_mask:0xf bank_mask:0xf
	v_mov_b32_dpp v2, v156 row_ror:8 row_mask:0xf bank_mask:0xf
	v_mov_b32_dpp v3, v157 row_ror:8 row_mask:0xf bank_mask:0xf
	v_mov_b32_dpp v4, v90 row_ror:8 row_mask:0xf bank_mask:0xf
	v_mov_b32_dpp v5, v91 row_ror:8 row_mask:0xf bank_mask:0xf
	v_mov_b32_dpp v6, v92 row_ror:8 row_mask:0xf bank_mask:0xf
	v_mov_b32_dpp v7, v93 row_ror:8 row_mask:0xf bank_mask:0xf
	v_cndmask_b32_e32 v154, v154, v4, vcc
	v_cndmask_b32_e32 v155, v155, v5, vcc
	v_cndmask_b32_e32 v156, v156, v6, vcc
	v_cndmask_b32_e32 v157, v157, v7, vcc
	v_cndmask_b32_e32 v90, v0, v90, vcc
	v_cndmask_b32_e32 v91, v1, v91, vcc
	v_cndmask_b32_e32 v92, v2, v92, vcc
	v_cndmask_b32_e32 v93, v3, v93, vcc
	v_lshl_add_u64 v[10:11], v[20:21], 0, v[8:9]
	global_store_dwordx4 v[20:21], v[154:157], off
	global_store_dwordx4 v[10:11], v[90:93], off
	v_cvt_pk_f16_f32 v146, v146, v147
	v_cvt_pk_f16_f32 v147, v148, v149
	v_cvt_pk_f16_f32 v148, v130, v131
	v_cvt_pk_f16_f32 v149, v132, v133
	v_cvt_pk_f16_f32 v82, v82, v83
	v_cvt_pk_f16_f32 v83, v84, v85
	v_cvt_pk_f16_f32 v84, v66, v67
	v_cvt_pk_f16_f32 v85, v68, v69
	v_mov_b32_dpp v0, v146 row_ror:8 row_mask:0xf bank_mask:0xf
	v_mov_b32_dpp v1, v147 row_ror:8 row_mask:0xf bank_mask:0xf
	v_mov_b32_dpp v2, v148 row_ror:8 row_mask:0xf bank_mask:0xf
	v_mov_b32_dpp v3, v149 row_ror:8 row_mask:0xf bank_mask:0xf
	v_mov_b32_dpp v4, v82 row_ror:8 row_mask:0xf bank_mask:0xf
	v_mov_b32_dpp v5, v83 row_ror:8 row_mask:0xf bank_mask:0xf
	v_mov_b32_dpp v6, v84 row_ror:8 row_mask:0xf bank_mask:0xf
	v_mov_b32_dpp v7, v85 row_ror:8 row_mask:0xf bank_mask:0xf
	v_cndmask_b32_e32 v146, v146, v4, vcc
	v_cndmask_b32_e32 v147, v147, v5, vcc
	v_cndmask_b32_e32 v148, v148, v6, vcc
	v_cndmask_b32_e32 v149, v149, v7, vcc
	v_cndmask_b32_e32 v82, v0, v82, vcc
	v_cndmask_b32_e32 v83, v1, v83, vcc
	v_cndmask_b32_e32 v84, v2, v84, vcc
	v_cndmask_b32_e32 v85, v3, v85, vcc
	v_lshl_add_u64 v[10:11], v[22:23], 0, v[8:9]
	global_store_dwordx4 v[22:23], v[146:149], off
	global_store_dwordx4 v[10:11], v[82:85], off
	v_cvt_pk_f16_f32 v126, v126, v127
	v_cvt_pk_f16_f32 v127, v128, v129
	v_cvt_pk_f16_f32 v128, v110, v111
	v_cvt_pk_f16_f32 v129, v112, v113
	v_cvt_pk_f16_f32 v62, v62, v63
	v_cvt_pk_f16_f32 v63, v64, v65
	v_cvt_pk_f16_f32 v64, v46, v47
	v_cvt_pk_f16_f32 v65, v48, v49
	v_mov_b32_dpp v0, v126 row_ror:8 row_mask:0xf bank_mask:0xf
	v_mov_b32_dpp v1, v127 row_ror:8 row_mask:0xf bank_mask:0xf
	v_mov_b32_dpp v2, v128 row_ror:8 row_mask:0xf bank_mask:0xf
	v_mov_b32_dpp v3, v129 row_ror:8 row_mask:0xf bank_mask:0xf
	v_mov_b32_dpp v4, v62 row_ror:8 row_mask:0xf bank_mask:0xf
	v_mov_b32_dpp v5, v63 row_ror:8 row_mask:0xf bank_mask:0xf
	v_mov_b32_dpp v6, v64 row_ror:8 row_mask:0xf bank_mask:0xf
	v_mov_b32_dpp v7, v65 row_ror:8 row_mask:0xf bank_mask:0xf
	v_cndmask_b32_e32 v126, v126, v4, vcc
	v_cndmask_b32_e32 v127, v127, v5, vcc
	v_cndmask_b32_e32 v128, v128, v6, vcc
	v_cndmask_b32_e32 v129, v129, v7, vcc
	v_cndmask_b32_e32 v62, v0, v62, vcc
	v_cndmask_b32_e32 v63, v1, v63, vcc
	v_cndmask_b32_e32 v64, v2, v64, vcc
	v_cndmask_b32_e32 v65, v3, v65, vcc
	v_lshl_add_u64 v[10:11], v[24:25], 0, v[8:9]
	global_store_dwordx4 v[24:25], v[126:129], off
	global_store_dwordx4 v[10:11], v[62:65], off
	v_cvt_pk_f16_f32 v118, v118, v119
	v_cvt_pk_f16_f32 v119, v120, v121
	v_cvt_pk_f16_f32 v120, v102, v103
	v_cvt_pk_f16_f32 v121, v104, v105
	v_cvt_pk_f16_f32 v54, v54, v55
	v_cvt_pk_f16_f32 v55, v56, v57
	v_cvt_pk_f16_f32 v56, v38, v39
	v_cvt_pk_f16_f32 v57, v40, v41
	v_mov_b32_dpp v0, v118 row_ror:8 row_mask:0xf bank_mask:0xf
	v_mov_b32_dpp v1, v119 row_ror:8 row_mask:0xf bank_mask:0xf
	v_mov_b32_dpp v2, v120 row_ror:8 row_mask:0xf bank_mask:0xf
	v_mov_b32_dpp v3, v121 row_ror:8 row_mask:0xf bank_mask:0xf
	v_mov_b32_dpp v4, v54 row_ror:8 row_mask:0xf bank_mask:0xf
	v_mov_b32_dpp v5, v55 row_ror:8 row_mask:0xf bank_mask:0xf
	v_mov_b32_dpp v6, v56 row_ror:8 row_mask:0xf bank_mask:0xf
	v_mov_b32_dpp v7, v57 row_ror:8 row_mask:0xf bank_mask:0xf
	v_cndmask_b32_e32 v118, v118, v4, vcc
	v_cndmask_b32_e32 v119, v119, v5, vcc
	v_cndmask_b32_e32 v120, v120, v6, vcc
	v_cndmask_b32_e32 v121, v121, v7, vcc
	v_cndmask_b32_e32 v54, v0, v54, vcc
	v_cndmask_b32_e32 v55, v1, v55, vcc
	v_cndmask_b32_e32 v56, v2, v56, vcc
	v_cndmask_b32_e32 v57, v3, v57, vcc
	v_lshl_add_u64 v[10:11], v[26:27], 0, v[8:9]
	global_store_dwordx4 v[26:27], v[118:121], off
	global_store_dwordx4 v[10:11], v[54:57], off
	v_cvt_pk_f16_f32 v122, v122, v123
	v_cvt_pk_f16_f32 v123, v124, v125
	v_cvt_pk_f16_f32 v124, v106, v107
	v_cvt_pk_f16_f32 v125, v108, v109
	v_cvt_pk_f16_f32 v58, v58, v59
	v_cvt_pk_f16_f32 v59, v60, v61
	v_cvt_pk_f16_f32 v60, v42, v43
	v_cvt_pk_f16_f32 v61, v44, v45
	v_mov_b32_dpp v0, v122 row_ror:8 row_mask:0xf bank_mask:0xf
	v_mov_b32_dpp v1, v123 row_ror:8 row_mask:0xf bank_mask:0xf
	v_mov_b32_dpp v2, v124 row_ror:8 row_mask:0xf bank_mask:0xf
	v_mov_b32_dpp v3, v125 row_ror:8 row_mask:0xf bank_mask:0xf
	v_mov_b32_dpp v4, v58 row_ror:8 row_mask:0xf bank_mask:0xf
	v_mov_b32_dpp v5, v59 row_ror:8 row_mask:0xf bank_mask:0xf
	v_mov_b32_dpp v6, v60 row_ror:8 row_mask:0xf bank_mask:0xf
	v_mov_b32_dpp v7, v61 row_ror:8 row_mask:0xf bank_mask:0xf
	v_cndmask_b32_e32 v122, v122, v4, vcc
	v_cndmask_b32_e32 v123, v123, v5, vcc
	v_cndmask_b32_e32 v124, v124, v6, vcc
	v_cndmask_b32_e32 v125, v125, v7, vcc
	v_cndmask_b32_e32 v58, v0, v58, vcc
	v_cndmask_b32_e32 v59, v1, v59, vcc
	v_cndmask_b32_e32 v60, v2, v60, vcc
	v_cndmask_b32_e32 v61, v3, v61, vcc
	v_lshl_add_u64 v[10:11], v[28:29], 0, v[8:9]
	global_store_dwordx4 v[28:29], v[122:125], off
	global_store_dwordx4 v[10:11], v[58:61], off
	v_cvt_pk_f16_f32 v114, v114, v115
	v_cvt_pk_f16_f32 v115, v116, v117
	v_cvt_pk_f16_f32 v116, v98, v99
	v_cvt_pk_f16_f32 v117, v100, v101
	v_cvt_pk_f16_f32 v50, v50, v51
	v_cvt_pk_f16_f32 v51, v52, v53
	v_cvt_pk_f16_f32 v52, v34, v35
	v_cvt_pk_f16_f32 v53, v36, v37
	v_mov_b32_dpp v0, v114 row_ror:8 row_mask:0xf bank_mask:0xf
	v_mov_b32_dpp v1, v115 row_ror:8 row_mask:0xf bank_mask:0xf
	v_mov_b32_dpp v2, v116 row_ror:8 row_mask:0xf bank_mask:0xf
	v_mov_b32_dpp v3, v117 row_ror:8 row_mask:0xf bank_mask:0xf
	v_mov_b32_dpp v4, v50 row_ror:8 row_mask:0xf bank_mask:0xf
	v_mov_b32_dpp v5, v51 row_ror:8 row_mask:0xf bank_mask:0xf
	v_mov_b32_dpp v6, v52 row_ror:8 row_mask:0xf bank_mask:0xf
	v_mov_b32_dpp v7, v53 row_ror:8 row_mask:0xf bank_mask:0xf
	v_cndmask_b32_e32 v114, v114, v4, vcc
	v_cndmask_b32_e32 v115, v115, v5, vcc
	v_cndmask_b32_e32 v116, v116, v6, vcc
	v_cndmask_b32_e32 v117, v117, v7, vcc
	v_cndmask_b32_e32 v50, v0, v50, vcc
	v_cndmask_b32_e32 v51, v1, v51, vcc
	v_cndmask_b32_e32 v52, v2, v52, vcc
	v_cndmask_b32_e32 v53, v3, v53, vcc
	v_lshl_add_u64 v[10:11], v[30:31], 0, v[8:9]
	global_store_dwordx4 v[30:31], v[114:117], off
	global_store_dwordx4 v[10:11], v[50:53], off
	s_mov_b64 s[4:5], 0

.LBB0_940:
	s_add_u32 s20, s14, 0x100
	s_addc_u32 s21, s15, 0
	s_add_i32 s40, 0, 0x10000
	v_add_u32_e32 v32, s40, v209
	ds_read_b128 v[132:135], v32
	ds_read_b128 v[140:143], v32 offset:2048
	ds_read_b128 v[136:139], v32 offset:1024
	ds_read_b128 v[144:147], v32 offset:3072
	s_cmp_eq_u32 s11, 12
	s_cselect_b32 s25, s17, s21
	s_cselect_b32 s24, s16, s20
	s_cselect_b32 s23, s19, s3
	s_cselect_b32 s22, s18, s1
	v_lshl_add_u64 v[34:35], s[14:15], 0, v[200:201]
	s_add_i32 m0, s30, 0xc000
	ds_read_b128 v[148:151], v211
	ds_read_b128 v[156:159], v211 offset:2048
	ds_read_b128 v[164:167], v211 offset:4096
	ds_read_b128 v[172:175], v211 offset:6144
	ds_read_b128 v[152:155], v211 offset:1024
	ds_read_b128 v[160:163], v211 offset:3072
	ds_read_b128 v[168:171], v211 offset:5120
	ds_read_b128 v[176:179], v211 offset:7168
	global_load_lds_dwordx4 v[34:35], off
	v_lshl_add_u64 v[34:35], s[14:15], 0, v[202:203]
	s_add_i32 m0, s30, 0xe000
	s_nop 0
	global_load_lds_dwordx4 v[34:35], off
	s_waitcnt lgkmcnt(8)
	s_setprio 1
	s_barrier
	s_waitcnt lgkmcnt(7)
	v_mfma_f32_16x16x32_f16 v[128:131], v[132:135], v[148:151], v[128:131]
	v_mfma_f32_16x16x32_f16 v[124:127], v[140:143], v[148:151], v[124:127]
	s_waitcnt lgkmcnt(6)
	v_mfma_f32_16x16x32_f16 v[120:123], v[132:135], v[156:159], v[120:123]
	v_mfma_f32_16x16x32_f16 v[116:119], v[140:143], v[156:159], v[116:119]
	s_waitcnt lgkmcnt(5)
	v_mfma_f32_16x16x32_f16 v[112:115], v[132:135], v[164:167], v[112:115]
	v_mfma_f32_16x16x32_f16 v[108:111], v[140:143], v[164:167], v[108:111]
	s_waitcnt lgkmcnt(4)
	v_mfma_f32_16x16x32_f16 v[104:107], v[132:135], v[172:175], v[104:107]
	v_mfma_f32_16x16x32_f16 v[100:103], v[140:143], v[172:175], v[100:103]
	s_waitcnt lgkmcnt(3)
	v_mfma_f32_16x16x32_f16 v[128:131], v[136:139], v[152:155], v[128:131]
	v_mfma_f32_16x16x32_f16 v[124:127], v[144:147], v[152:155], v[124:127]
	s_waitcnt lgkmcnt(2)
	v_mfma_f32_16x16x32_f16 v[120:123], v[136:139], v[160:163], v[120:123]
	v_mfma_f32_16x16x32_f16 v[116:119], v[144:147], v[160:163], v[116:119]
	s_waitcnt lgkmcnt(1)
	v_mfma_f32_16x16x32_f16 v[112:115], v[136:139], v[168:171], v[112:115]
	v_mfma_f32_16x16x32_f16 v[108:111], v[144:147], v[168:171], v[108:111]
	s_waitcnt lgkmcnt(0)
	v_mfma_f32_16x16x32_f16 v[104:107], v[136:139], v[176:179], v[104:107]
	v_mfma_f32_16x16x32_f16 v[100:103], v[144:147], v[176:179], v[100:103]
	s_setprio 0
	s_barrier
	s_add_i32 s41, 0, 0x14000
	s_add_i32 s14, s40, s29
	v_add_u32_e32 v32, s41, v209
	v_lshl_add_u64 v[204:205], s[22:23], 0, v[196:197]
	s_mov_b32 m0, s14
	ds_read_b128 v[180:183], v32
	ds_read_b128 v[188:191], v32 offset:2048
	ds_read_b128 v[184:187], v32 offset:1024
	ds_read_b128 v[192:195], v32 offset:3072
	global_load_lds_dwordx4 v[204:205], off
	v_lshl_add_u64 v[206:207], s[22:23], 0, v[198:199]
	s_add_i32 m0, s14, 0x2000
	s_nop 0
	global_load_lds_dwordx4 v[206:207], off
	s_setprio 1
	s_barrier
	s_waitcnt lgkmcnt(2)
	v_mfma_f32_16x16x32_f16 v[96:99], v[180:183], v[148:151], v[96:99]
	v_mfma_f32_16x16x32_f16 v[92:95], v[188:191], v[148:151], v[92:95]
	v_mfma_f32_16x16x32_f16 v[88:91], v[180:183], v[156:159], v[88:91]
	v_mfma_f32_16x16x32_f16 v[84:87], v[188:191], v[156:159], v[84:87]
	v_mfma_f32_16x16x32_f16 v[80:83], v[180:183], v[164:167], v[80:83]
	v_mfma_f32_16x16x32_f16 v[76:79], v[188:191], v[164:167], v[76:79]
	v_mfma_f32_16x16x32_f16 v[72:75], v[180:183], v[172:175], v[72:75]
	v_mfma_f32_16x16x32_f16 v[68:71], v[188:191], v[172:175], v[68:71]
	s_waitcnt lgkmcnt(0)
	v_mfma_f32_16x16x32_f16 v[96:99], v[184:187], v[152:155], v[96:99]
	v_mfma_f32_16x16x32_f16 v[92:95], v[192:195], v[152:155], v[92:95]
	v_mfma_f32_16x16x32_f16 v[88:91], v[184:187], v[160:163], v[88:91]
	v_mfma_f32_16x16x32_f16 v[84:87], v[192:195], v[160:163], v[84:87]
	v_mfma_f32_16x16x32_f16 v[80:83], v[184:187], v[168:171], v[80:83]
	v_mfma_f32_16x16x32_f16 v[76:79], v[192:195], v[168:171], v[76:79]
	v_mfma_f32_16x16x32_f16 v[72:75], v[184:187], v[176:179], v[72:75]
	v_mfma_f32_16x16x32_f16 v[68:71], v[192:195], v[176:179], v[68:71]
	s_setprio 0
	s_mov_b32 m0, s30
	v_lshl_add_u64 v[212:213], s[24:25], 0, v[196:197]
	s_barrier
	ds_read_b128 v[148:151], v211 offset:16384
	ds_read_b128 v[156:159], v211 offset:18432
	ds_read_b128 v[164:167], v211 offset:20480
	ds_read_b128 v[172:175], v211 offset:22528
	ds_read_b128 v[152:155], v211 offset:17408
	ds_read_b128 v[160:163], v211 offset:19456
	ds_read_b128 v[168:171], v211 offset:21504
	ds_read_b128 v[176:179], v211 offset:23552
	global_load_lds_dwordx4 v[212:213], off
	v_lshl_add_u64 v[214:215], s[24:25], 0, v[198:199]
	s_mov_b32 m0, s31
	s_nop 0
	global_load_lds_dwordx4 v[214:215], off
	s_setprio 1
	s_barrier
	s_waitcnt lgkmcnt(7)
	v_mfma_f32_16x16x32_f16 v[64:67], v[132:135], v[148:151], v[64:67]
	v_mfma_f32_16x16x32_f16 v[60:63], v[140:143], v[148:151], v[60:63]
	s_waitcnt lgkmcnt(6)
	v_mfma_f32_16x16x32_f16 v[56:59], v[132:135], v[156:159], v[56:59]
	v_mfma_f32_16x16x32_f16 v[52:55], v[140:143], v[156:159], v[52:55]
	s_waitcnt lgkmcnt(5)
	v_mfma_f32_16x16x32_f16 v[48:51], v[132:135], v[164:167], v[48:51]
	v_mfma_f32_16x16x32_f16 v[44:47], v[140:143], v[164:167], v[44:47]
	s_waitcnt lgkmcnt(4)
	v_mfma_f32_16x16x32_f16 v[40:43], v[132:135], v[172:175], v[40:43]
	v_mfma_f32_16x16x32_f16 v[34:37], v[140:143], v[172:175], v[36:39]
	s_waitcnt lgkmcnt(3)
	v_mfma_f32_16x16x32_f16 v[64:67], v[136:139], v[152:155], v[64:67]
	v_mfma_f32_16x16x32_f16 v[60:63], v[144:147], v[152:155], v[60:63]
	s_waitcnt lgkmcnt(2)
	v_mfma_f32_16x16x32_f16 v[56:59], v[136:139], v[160:163], v[56:59]
	v_mfma_f32_16x16x32_f16 v[52:55], v[144:147], v[160:163], v[52:55]
	s_waitcnt lgkmcnt(1)
	v_mfma_f32_16x16x32_f16 v[48:51], v[136:139], v[168:171], v[48:51]
	v_mfma_f32_16x16x32_f16 v[44:47], v[144:147], v[168:171], v[44:47]
	s_waitcnt lgkmcnt(0)
	v_mfma_f32_16x16x32_f16 v[40:43], v[136:139], v[176:179], v[40:43]
	v_mfma_f32_16x16x32_f16 v[34:37], v[144:147], v[176:179], v[34:37]
	s_setprio 0
	s_barrier
	s_add_u32 s14, s22, 0x40000
	s_addc_u32 s15, s23, 0
	s_add_i32 s40, s41, s29
	v_lshl_add_u64 v[38:39], s[14:15], 0, v[196:197]
	s_mov_b32 m0, s40
	s_nop 0
	global_load_lds_dwordx4 v[38:39], off
	v_lshl_add_u64 v[38:39], s[14:15], 0, v[198:199]
	s_add_i32 m0, s40, 0x2000
	s_nop 0
	global_load_lds_dwordx4 v[38:39], off
	s_waitcnt vmcnt(6)
	s_setprio 1
	s_barrier
	v_mfma_f32_16x16x32_f16 v[28:31], v[180:183], v[148:151], v[28:31]
	v_mfma_f32_16x16x32_f16 v[24:27], v[188:191], v[148:151], v[24:27]
	v_mfma_f32_16x16x32_f16 v[20:23], v[180:183], v[156:159], v[20:23]
	v_mfma_f32_16x16x32_f16 v[16:19], v[188:191], v[156:159], v[16:19]
	v_mfma_f32_16x16x32_f16 v[12:15], v[180:183], v[164:167], v[12:15]
	v_mfma_f32_16x16x32_f16 v[8:11], v[188:191], v[164:167], v[8:11]
	v_mfma_f32_16x16x32_f16 v[4:7], v[180:183], v[172:175], v[4:7]
	v_mfma_f32_16x16x32_f16 v[0:3], v[188:191], v[172:175], v[0:3]
	v_mfma_f32_16x16x32_f16 v[28:31], v[184:187], v[152:155], v[28:31]
	v_mfma_f32_16x16x32_f16 v[24:27], v[192:195], v[152:155], v[24:27]
	v_mfma_f32_16x16x32_f16 v[20:23], v[184:187], v[160:163], v[20:23]
	v_mfma_f32_16x16x32_f16 v[16:19], v[192:195], v[160:163], v[16:19]
	v_mfma_f32_16x16x32_f16 v[12:15], v[184:187], v[168:171], v[12:15]
	v_mfma_f32_16x16x32_f16 v[8:11], v[192:195], v[168:171], v[8:11]
	v_mfma_f32_16x16x32_f16 v[4:7], v[184:187], v[176:179], v[4:7]
	v_mfma_f32_16x16x32_f16 v[0:3], v[192:195], v[176:179], v[0:3]
	s_setprio 0
	s_add_i32 s40, 0, 0x18000
	v_add_u32_e32 v32, s40, v209
	s_barrier
	ds_read_b128 v[132:135], v32
	ds_read_b128 v[140:143], v32 offset:2048
	ds_read_b128 v[136:139], v32 offset:1024
	ds_read_b128 v[144:147], v32 offset:3072
	s_add_u32 s14, s24, 0x40000
	s_addc_u32 s15, s25, 0
	s_mov_b32 m0, s34
	v_lshl_add_u64 v[38:39], s[14:15], 0, v[196:197]
	ds_read_b128 v[148:151], v211 offset:32768
	ds_read_b128 v[156:159], v211 offset:34816
	ds_read_b128 v[164:167], v211 offset:36864
	ds_read_b128 v[172:175], v211 offset:38912
	ds_read_b128 v[152:155], v211 offset:33792
	ds_read_b128 v[160:163], v211 offset:35840
	ds_read_b128 v[168:171], v211 offset:37888
	ds_read_b128 v[176:179], v211 offset:39936
	global_load_lds_dwordx4 v[38:39], off
	v_lshl_add_u64 v[38:39], s[14:15], 0, v[198:199]
	s_mov_b32 m0, s35
	s_nop 0
	global_load_lds_dwordx4 v[38:39], off
	s_waitcnt lgkmcnt(8)
	s_setprio 1
	s_barrier
	s_waitcnt lgkmcnt(7)
	v_mfma_f32_16x16x32_f16 v[128:131], v[132:135], v[148:151], v[128:131]
	v_mfma_f32_16x16x32_f16 v[124:127], v[140:143], v[148:151], v[124:127]
	s_waitcnt lgkmcnt(6)
	v_mfma_f32_16x16x32_f16 v[120:123], v[132:135], v[156:159], v[120:123]
	v_mfma_f32_16x16x32_f16 v[116:119], v[140:143], v[156:159], v[116:119]
	s_waitcnt lgkmcnt(5)
	v_mfma_f32_16x16x32_f16 v[112:115], v[132:135], v[164:167], v[112:115]
	v_mfma_f32_16x16x32_f16 v[108:111], v[140:143], v[164:167], v[108:111]
	s_waitcnt lgkmcnt(4)
	v_mfma_f32_16x16x32_f16 v[104:107], v[132:135], v[172:175], v[104:107]
	v_mfma_f32_16x16x32_f16 v[100:103], v[140:143], v[172:175], v[100:103]
	s_waitcnt lgkmcnt(3)
	v_mfma_f32_16x16x32_f16 v[128:131], v[136:139], v[152:155], v[128:131]
	v_mfma_f32_16x16x32_f16 v[124:127], v[144:147], v[152:155], v[124:127]
	s_waitcnt lgkmcnt(2)
	v_mfma_f32_16x16x32_f16 v[120:123], v[136:139], v[160:163], v[120:123]
	v_mfma_f32_16x16x32_f16 v[116:119], v[144:147], v[160:163], v[116:119]
	s_waitcnt lgkmcnt(1)
	v_mfma_f32_16x16x32_f16 v[112:115], v[136:139], v[168:171], v[112:115]
	v_mfma_f32_16x16x32_f16 v[108:111], v[144:147], v[168:171], v[108:111]
	s_waitcnt lgkmcnt(0)
	v_mfma_f32_16x16x32_f16 v[104:107], v[136:139], v[176:179], v[104:107]
	v_mfma_f32_16x16x32_f16 v[100:103], v[144:147], v[176:179], v[100:103]
	s_setprio 0
	s_barrier
	s_add_i32 s24, 0, 0x1c000
	s_add_i32 s14, s40, s29
	v_add_u32_e32 v32, s24, v209
	v_lshl_add_u64 v[38:39], v[204:205], 0, s[84:85]
	s_mov_b32 m0, s14
	ds_read_b128 v[180:183], v32
	ds_read_b128 v[188:191], v32 offset:2048
	ds_read_b128 v[184:187], v32 offset:1024
	ds_read_b128 v[192:195], v32 offset:3072
	global_load_lds_dwordx4 v[38:39], off
	v_lshl_add_u64 v[38:39], v[206:207], 0, s[84:85]
	s_add_i32 m0, s14, 0x2000
	s_nop 0
	global_load_lds_dwordx4 v[38:39], off
	s_setprio 1
	s_barrier
	s_waitcnt lgkmcnt(2)
	v_mfma_f32_16x16x32_f16 v[96:99], v[180:183], v[148:151], v[96:99]
	v_mfma_f32_16x16x32_f16 v[92:95], v[188:191], v[148:151], v[92:95]
	v_mfma_f32_16x16x32_f16 v[88:91], v[180:183], v[156:159], v[88:91]
	v_mfma_f32_16x16x32_f16 v[84:87], v[188:191], v[156:159], v[84:87]
	v_mfma_f32_16x16x32_f16 v[80:83], v[180:183], v[164:167], v[80:83]
	v_mfma_f32_16x16x32_f16 v[76:79], v[188:191], v[164:167], v[76:79]
	v_mfma_f32_16x16x32_f16 v[72:75], v[180:183], v[172:175], v[72:75]
	v_mfma_f32_16x16x32_f16 v[68:71], v[188:191], v[172:175], v[68:71]
	s_waitcnt lgkmcnt(0)
	v_mfma_f32_16x16x32_f16 v[96:99], v[184:187], v[152:155], v[96:99]
	v_mfma_f32_16x16x32_f16 v[92:95], v[192:195], v[152:155], v[92:95]
	v_mfma_f32_16x16x32_f16 v[88:91], v[184:187], v[160:163], v[88:91]
	v_mfma_f32_16x16x32_f16 v[84:87], v[192:195], v[160:163], v[84:87]
	v_mfma_f32_16x16x32_f16 v[80:83], v[184:187], v[168:171], v[80:83]
	v_mfma_f32_16x16x32_f16 v[76:79], v[192:195], v[168:171], v[76:79]
	v_mfma_f32_16x16x32_f16 v[72:75], v[184:187], v[176:179], v[72:75]
	v_mfma_f32_16x16x32_f16 v[68:71], v[192:195], v[176:179], v[68:71]
	s_setprio 0
	s_mov_b32 m0, s36
	v_lshl_add_u64 v[38:39], v[212:213], 0, s[84:85]
	s_barrier
	ds_read_b128 v[148:151], v211 offset:49152
	ds_read_b128 v[156:159], v211 offset:51200
	ds_read_b128 v[164:167], v211 offset:53248
	ds_read_b128 v[172:175], v211 offset:55296
	ds_read_b128 v[152:155], v211 offset:50176
	ds_read_b128 v[160:163], v211 offset:52224
	ds_read_b128 v[168:171], v211 offset:54272
	ds_read_b128 v[176:179], v211 offset:56320
	global_load_lds_dwordx4 v[38:39], off
	v_lshl_add_u64 v[38:39], v[214:215], 0, s[84:85]
	s_mov_b32 m0, s37
	s_nop 0
	global_load_lds_dwordx4 v[38:39], off
	s_setprio 1
	s_barrier
	s_waitcnt lgkmcnt(7)
	v_mfma_f32_16x16x32_f16 v[64:67], v[132:135], v[148:151], v[64:67]
	v_mfma_f32_16x16x32_f16 v[60:63], v[140:143], v[148:151], v[60:63]
	s_waitcnt lgkmcnt(6)
	v_mfma_f32_16x16x32_f16 v[56:59], v[132:135], v[156:159], v[56:59]
	v_mfma_f32_16x16x32_f16 v[52:55], v[140:143], v[156:159], v[52:55]
	s_waitcnt lgkmcnt(5)
	v_mfma_f32_16x16x32_f16 v[48:51], v[132:135], v[164:167], v[48:51]
	v_mfma_f32_16x16x32_f16 v[44:47], v[140:143], v[164:167], v[44:47]
	s_waitcnt lgkmcnt(4)
	v_mfma_f32_16x16x32_f16 v[38:41], v[132:135], v[172:175], v[40:43]
	v_mfma_f32_16x16x32_f16 v[34:37], v[140:143], v[172:175], v[34:37]
	s_waitcnt lgkmcnt(3)
	v_mfma_f32_16x16x32_f16 v[64:67], v[136:139], v[152:155], v[64:67]
	v_mfma_f32_16x16x32_f16 v[60:63], v[144:147], v[152:155], v[60:63]
	s_waitcnt lgkmcnt(2)
	v_mfma_f32_16x16x32_f16 v[56:59], v[136:139], v[160:163], v[56:59]
	v_mfma_f32_16x16x32_f16 v[52:55], v[144:147], v[160:163], v[52:55]
	s_waitcnt lgkmcnt(1)
	v_mfma_f32_16x16x32_f16 v[48:51], v[136:139], v[168:171], v[48:51]
	v_mfma_f32_16x16x32_f16 v[44:47], v[144:147], v[168:171], v[44:47]
	s_waitcnt lgkmcnt(0)
	v_mfma_f32_16x16x32_f16 v[40:43], v[136:139], v[176:179], v[38:41]
	v_mfma_f32_16x16x32_f16 v[36:39], v[144:147], v[176:179], v[34:37]
	s_setprio 0
	s_barrier
	s_add_u32 s14, s22, 0x40080
	s_addc_u32 s15, s23, 0
	s_add_i32 s22, s24, s29
	v_lshl_add_u64 v[34:35], s[14:15], 0, v[196:197]
	s_mov_b32 m0, s22
	s_nop 0
	global_load_lds_dwordx4 v[34:35], off
	v_lshl_add_u64 v[34:35], s[14:15], 0, v[198:199]
	s_add_i32 m0, s22, 0x2000
	s_nop 0
	global_load_lds_dwordx4 v[34:35], off
	s_waitcnt vmcnt(6)
	s_setprio 1
	s_barrier
	v_mfma_f32_16x16x32_f16 v[28:31], v[180:183], v[148:151], v[28:31]
	v_mfma_f32_16x16x32_f16 v[24:27], v[188:191], v[148:151], v[24:27]
	v_mfma_f32_16x16x32_f16 v[20:23], v[180:183], v[156:159], v[20:23]
	v_mfma_f32_16x16x32_f16 v[16:19], v[188:191], v[156:159], v[16:19]
	v_mfma_f32_16x16x32_f16 v[12:15], v[180:183], v[164:167], v[12:15]
	v_mfma_f32_16x16x32_f16 v[8:11], v[188:191], v[164:167], v[8:11]
	v_mfma_f32_16x16x32_f16 v[4:7], v[180:183], v[172:175], v[4:7]
	v_mfma_f32_16x16x32_f16 v[0:3], v[188:191], v[172:175], v[0:3]
	v_mfma_f32_16x16x32_f16 v[28:31], v[184:187], v[152:155], v[28:31]
	v_mfma_f32_16x16x32_f16 v[24:27], v[192:195], v[152:155], v[24:27]
	v_mfma_f32_16x16x32_f16 v[20:23], v[184:187], v[160:163], v[20:23]
	v_mfma_f32_16x16x32_f16 v[16:19], v[192:195], v[160:163], v[16:19]
	v_mfma_f32_16x16x32_f16 v[12:15], v[184:187], v[168:171], v[12:15]
	v_mfma_f32_16x16x32_f16 v[8:11], v[192:195], v[168:171], v[8:11]
	v_mfma_f32_16x16x32_f16 v[4:7], v[184:187], v[176:179], v[4:7]
	v_mfma_f32_16x16x32_f16 v[0:3], v[192:195], v[176:179], v[0:3]
	s_setprio 0
	s_add_i32 s11, s11, 2
	s_add_u32 s1, s1, 0x100
	s_addc_u32 s3, s3, 0
	s_cmp_gt_u32 s11, 13
	s_mov_b64 s[14:15], s[20:21]
	s_barrier
	s_cbranch_scc0 .LBB0_940
	v_lshl_add_u32 v34, s12, 8, v208
	v_lshl_or_b32 v156, s10, 8, v210
	s_cmp_lg_u32 s13, 0
	s_cselect_b64 s[10:11], -1, 0
	s_cmp_eq_u32 s13, 0
	v_ashrrev_i32_e32 v157, 31, v156
	v_ashrrev_i32_e32 v35, 31, v34
	v_mad_i64_i32 v[158:159], s[12:13], v34, s33, 0
	v_or_b32_e32 v160, 16, v34
	v_or_b32_e32 v162, 32, v34
	v_or_b32_e32 v164, 48, v34
	s_cbranch_scc1 .LBB0_946
	v_lshl_add_u64 v[132:133], s[70:71], 0, v[158:159]
	v_lshlrev_b64 v[166:167], 1, v[156:157]
	v_lshl_add_u64 v[132:133], v[132:133], 0, v[166:167]
	s_mov_b64 s[16:17], 0x2800
	v_mov_b64_e32 v[168:169], s[70:71]
	s_movk_i32 s1, 0x2000
	v_lshl_add_u64 v[134:135], v[132:133], 0, s[16:17]
	v_mad_i64_i32 v[136:137], s[12:13], v160, s33, v[168:169]
	v_add_co_u32_e32 v132, vcc, s1, v132
	v_lshl_add_u64 v[136:137], v[136:137], 0, v[166:167]
	s_nop 0
	v_addc_co_u32_e32 v133, vcc, 0, v133, vcc
	v_lshl_add_u64 v[138:139], v[136:137], 0, s[16:17]
	v_mad_i64_i32 v[140:141], s[12:13], v162, s33, v[168:169]
	v_add_co_u32_e32 v136, vcc, s1, v136
	v_lshl_add_u64 v[140:141], v[140:141], 0, v[166:167]
	s_nop 0
	v_addc_co_u32_e32 v137, vcc, 0, v137, vcc
	v_mad_i64_i32 v[144:145], s[12:13], v164, s33, v[168:169]
	global_load_dwordx4 v[170:173], v[132:133], off offset:2048
	global_load_dwordx4 v[152:155], v[136:137], off offset:2048
	global_load_dwordx4 v[174:177], v[134:135], off offset:256
	global_load_dwordx4 v[148:151], v[138:139], off offset:256
	v_add_co_u32_e32 v132, vcc, s1, v140
	v_lshl_add_u64 v[144:145], v[144:145], 0, v[166:167]
	s_nop 0
	v_addc_co_u32_e32 v133, vcc, 0, v141, vcc
	v_add_co_u32_e32 v134, vcc, s1, v144
	v_lshl_add_u64 v[142:143], v[140:141], 0, s[16:17]
	s_nop 0
	v_addc_co_u32_e32 v135, vcc, 0, v145, vcc
	v_lshl_add_u64 v[178:179], v[144:145], 0, s[16:17]
	global_load_dwordx4 v[144:147], v[132:133], off offset:2048
	global_load_dwordx4 v[136:139], v[134:135], off offset:2048
	s_nop 0
	global_load_dwordx4 v[140:143], v[142:143], off offset:256
	s_nop 0
	global_load_dwordx4 v[132:135], v[178:179], off offset:256
	v_ashrrev_i32_e32 v161, 31, v160
	v_ashrrev_i32_e32 v163, 31, v162
	v_ashrrev_i32_e32 v165, 31, v164
	s_waitcnt vmcnt(0)
	v_cvt_f32_f16_e32 v32, v170
	v_cvt_f32_f16_sdwa v170, v170 dst_sel:DWORD dst_unused:UNUSED_PAD src0_sel:WORD_1
	v_lshlrev_b64 v[178:179], 11, v[34:35]
	v_readlane_b32 s14, v252, 9
	v_max_f32_e32 v32, 0xc1f00000, v32
	v_max_f32_e32 v35, 0xc1f00000, v170
	v_cvt_f32_f16_e32 v170, v171
	v_cvt_f32_f16_sdwa v171, v171 dst_sel:DWORD dst_unused:UNUSED_PAD src0_sel:WORD_1
	v_mul_f32_e32 v35, 0xbfb8aa3b, v35
	v_exp_f32_e32 v35, v35
	v_max_f32_e32 v170, 0xc1f00000, v170
	v_mul_f32_e32 v170, 0xbfb8aa3b, v170
	v_exp_f32_e32 v180, v170
	v_max_f32_e32 v170, 0xc1f00000, v171
	v_mul_f32_e32 v170, 0xbfb8aa3b, v170
	v_cvt_f32_f16_e32 v171, v172
	v_exp_f32_e32 v181, v170
	v_cvt_f32_f16_sdwa v170, v172 dst_sel:DWORD dst_unused:UNUSED_PAD src0_sel:WORD_1
	v_mul_f32_e32 v32, 0xbfb8aa3b, v32
	v_max_f32_e32 v171, 0xc1f00000, v171
	v_mul_f32_e32 v171, 0xbfb8aa3b, v171
	v_max_f32_e32 v170, 0xc1f00000, v170
	v_mul_f32_e32 v170, 0xbfb8aa3b, v170
	v_exp_f32_e32 v182, v171
	v_cvt_f32_f16_e32 v171, v173
	v_exp_f32_e32 v183, v170
	v_cvt_f32_f16_sdwa v170, v173 dst_sel:DWORD dst_unused:UNUSED_PAD src0_sel:WORD_1
	v_exp_f32_e32 v32, v32
	v_max_f32_e32 v171, 0xc1f00000, v171
	v_mul_f32_e32 v171, 0xbfb8aa3b, v171
	v_max_f32_e32 v170, 0xc1f00000, v170
	v_mul_f32_e32 v170, 0xbfb8aa3b, v170
	v_add_f32_e32 v35, 1.0, v35
	v_exp_f32_e32 v184, v171
	v_exp_f32_e32 v185, v170
	v_rcp_f32_e32 v170, v35
	v_add_f32_e32 v35, 1.0, v180
	v_rcp_f32_e32 v171, v35
	v_add_f32_e32 v35, 1.0, v181
	v_add_f32_e32 v32, 1.0, v32
	v_rcp_f32_e32 v172, v35
	v_add_f32_e32 v35, 1.0, v182
	v_rcp_f32_e32 v32, v32
	v_rcp_f32_e32 v173, v35
	v_add_f32_e32 v35, 1.0, v183
	v_rcp_f32_e32 v180, v35
	v_add_f32_e32 v35, 1.0, v184
	v_rcp_f32_e32 v181, v35
	v_mov_b32_e32 v182, v129
	v_mov_b32_e32 v183, v130
	v_pk_mul_f32 v[170:171], v[182:183], v[170:171]
	v_pk_mov_b32 v[182:183], v[130:131], v[124:125] op_sel:[1,0]
	v_add_f32_e32 v35, 1.0, v185
	v_fma_mixlo_f16 v32, v128, v32, 0
	v_cvt_pk_f16_f32 v171, v170, v171
	v_pk_mul_f32 v[172:173], v[182:183], v[172:173]
	v_rcp_f32_e32 v35, v35
	v_pack_b32_f16 v170, v32, v171
	v_cvt_pk_f16_f32 v32, v172, v173
	v_mov_b32_e32 v172, v125
	v_mov_b32_e32 v173, v126
	v_pk_mul_f32 v[172:173], v[172:173], v[180:181]
	v_readlane_b32 s15, v252, 10
	v_cvt_pk_f16_f32 v173, v172, v173
	v_alignbit_b32 v172, v173, v32, 16
	v_lshrrev_b32_e32 v173, 16, v173
	v_lshl_add_u64 v[178:179], s[14:15], 0, v[178:179]
	v_alignbit_b32 v171, v32, v171, 16
	v_fma_mixhi_f16 v173, v127, v35, 0
	v_lshl_add_u64 v[178:179], v[178:179], 0, v[166:167]
	global_store_dwordx4 v[178:179], v[170:173], off
	v_cvt_f32_f16_sdwa v35, v174 dst_sel:DWORD dst_unused:UNUSED_PAD src0_sel:WORD_1
	v_cvt_f32_f16_e32 v32, v174
	v_cvt_f32_f16_e32 v170, v175
	v_cvt_f32_f16_sdwa v171, v175 dst_sel:DWORD dst_unused:UNUSED_PAD src0_sel:WORD_1
	v_max_f32_e32 v35, 0xc1f00000, v35
	v_mul_f32_e32 v35, 0xbfb8aa3b, v35
	v_max_f32_e32 v170, 0xc1f00000, v170
	v_mul_f32_e32 v170, 0xbfb8aa3b, v170
	v_exp_f32_e32 v172, v170
	v_max_f32_e32 v170, 0xc1f00000, v171
	v_mul_f32_e32 v170, 0xbfb8aa3b, v170
	v_cvt_f32_f16_e32 v171, v176
	v_exp_f32_e32 v173, v170
	v_cvt_f32_f16_sdwa v170, v176 dst_sel:DWORD dst_unused:UNUSED_PAD src0_sel:WORD_1
	v_exp_f32_e32 v35, v35
	v_max_f32_e32 v171, 0xc1f00000, v171
	v_mul_f32_e32 v171, 0xbfb8aa3b, v171
	v_max_f32_e32 v170, 0xc1f00000, v170
	v_mul_f32_e32 v170, 0xbfb8aa3b, v170
	v_exp_f32_e32 v174, v171
	v_cvt_f32_f16_e32 v171, v177
	v_exp_f32_e32 v175, v170
	v_cvt_f32_f16_sdwa v170, v177 dst_sel:DWORD dst_unused:UNUSED_PAD src0_sel:WORD_1
	v_max_f32_e32 v32, 0xc1f00000, v32
	v_mul_f32_e32 v32, 0xbfb8aa3b, v32
	v_exp_f32_e32 v32, v32
	v_max_f32_e32 v171, 0xc1f00000, v171
	v_max_f32_e32 v170, 0xc1f00000, v170
	v_mul_f32_e32 v171, 0xbfb8aa3b, v171
	v_mul_f32_e32 v170, 0xbfb8aa3b, v170
	v_add_f32_e32 v35, 1.0, v35
	v_exp_f32_e32 v176, v171
	v_exp_f32_e32 v177, v170
	v_rcp_f32_e32 v170, v35
	v_add_f32_e32 v35, 1.0, v172
	v_rcp_f32_e32 v171, v35
	v_add_f32_e32 v35, 1.0, v173
	v_add_f32_e32 v32, 1.0, v32
	v_rcp_f32_e32 v172, v35
	v_add_f32_e32 v35, 1.0, v174
	v_rcp_f32_e32 v32, v32
	v_rcp_f32_e32 v173, v35
	v_add_f32_e32 v35, 1.0, v175
	v_rcp_f32_e32 v174, v35
	v_add_f32_e32 v35, 1.0, v176
	v_rcp_f32_e32 v175, v35
	v_add_f32_e32 v35, 1.0, v177
	v_mov_b32_e32 v176, v97
	v_mov_b32_e32 v177, v98
	v_pk_mul_f32 v[170:171], v[176:177], v[170:171]
	v_pk_mov_b32 v[176:177], v[98:99], v[92:93] op_sel:[1,0]
	v_fma_mixlo_f16 v32, v96, v32, 0
	v_cvt_pk_f16_f32 v171, v170, v171
	v_pk_mul_f32 v[172:173], v[176:177], v[172:173]
	v_rcp_f32_e32 v35, v35
	v_pack_b32_f16 v170, v32, v171
	v_cvt_pk_f16_f32 v32, v172, v173
	v_mov_b32_e32 v172, v93
	v_mov_b32_e32 v173, v94
	v_pk_mul_f32 v[172:173], v[172:173], v[174:175]
	v_alignbit_b32 v171, v32, v171, 16
	v_cvt_pk_f16_f32 v173, v172, v173
	v_alignbit_b32 v172, v173, v32, 16
	v_lshrrev_b32_e32 v173, 16, v173
	v_fma_mixhi_f16 v173, v95, v35, 0
	v_cvt_f32_f16_e32 v32, v152
	v_cvt_f32_f16_sdwa v35, v152 dst_sel:DWORD dst_unused:UNUSED_PAD src0_sel:WORD_1
	v_cvt_f32_f16_e32 v152, v153
	v_cvt_f32_f16_sdwa v153, v153 dst_sel:DWORD dst_unused:UNUSED_PAD src0_sel:WORD_1
	global_store_dwordx4 v[178:179], v[170:173], off offset:256
	v_max_f32_e32 v35, 0xc1f00000, v35
	v_max_f32_e32 v152, 0xc1f00000, v152
	v_mul_f32_e32 v152, 0xbfb8aa3b, v152
	v_lshlrev_b64 v[170:171], 11, v[160:161]
	v_exp_f32_e32 v161, v152
	v_max_f32_e32 v152, 0xc1f00000, v153
	v_mul_f32_e32 v152, 0xbfb8aa3b, v152
	v_cvt_f32_f16_e32 v153, v154
	v_exp_f32_e32 v172, v152
	v_cvt_f32_f16_sdwa v152, v154 dst_sel:DWORD dst_unused:UNUSED_PAD src0_sel:WORD_1
	v_mul_f32_e32 v35, 0xbfb8aa3b, v35
	v_max_f32_e32 v153, 0xc1f00000, v153
	v_mul_f32_e32 v153, 0xbfb8aa3b, v153
	v_max_f32_e32 v152, 0xc1f00000, v152
	v_mul_f32_e32 v152, 0xbfb8aa3b, v152
	v_exp_f32_e32 v173, v153
	v_cvt_f32_f16_e32 v153, v155
	v_exp_f32_e32 v174, v152
	v_cvt_f32_f16_sdwa v152, v155 dst_sel:DWORD dst_unused:UNUSED_PAD src0_sel:WORD_1
	v_exp_f32_e32 v35, v35
	v_max_f32_e32 v32, 0xc1f00000, v32
	v_mul_f32_e32 v32, 0xbfb8aa3b, v32
	v_exp_f32_e32 v32, v32
	v_max_f32_e32 v153, 0xc1f00000, v153
	v_max_f32_e32 v152, 0xc1f00000, v152
	v_mul_f32_e32 v153, 0xbfb8aa3b, v153
	v_mul_f32_e32 v152, 0xbfb8aa3b, v152
	v_add_f32_e32 v35, 1.0, v35
	v_exp_f32_e32 v175, v153
	v_exp_f32_e32 v176, v152
	v_rcp_f32_e32 v152, v35
	v_add_f32_e32 v35, 1.0, v161
	v_rcp_f32_e32 v153, v35
	v_add_f32_e32 v35, 1.0, v172
	v_add_f32_e32 v32, 1.0, v32
	v_rcp_f32_e32 v154, v35
	v_add_f32_e32 v35, 1.0, v173
	v_rcp_f32_e32 v32, v32
	v_rcp_f32_e32 v155, v35
	v_add_f32_e32 v35, 1.0, v174
	v_rcp_f32_e32 v172, v35
	v_add_f32_e32 v35, 1.0, v175
	v_rcp_f32_e32 v173, v35
	v_mov_b32_e32 v174, v121
	v_mov_b32_e32 v175, v122
	v_pk_mul_f32 v[152:153], v[174:175], v[152:153]
	v_pk_mov_b32 v[174:175], v[122:123], v[116:117] op_sel:[1,0]
	v_add_f32_e32 v35, 1.0, v176
	v_fma_mixlo_f16 v32, v120, v32, 0
	v_cvt_pk_f16_f32 v153, v152, v153
	v_pk_mul_f32 v[154:155], v[174:175], v[154:155]
	v_rcp_f32_e32 v35, v35
	v_pack_b32_f16 v152, v32, v153
	v_cvt_pk_f16_f32 v32, v154, v155
	v_mov_b32_e32 v154, v117
	v_mov_b32_e32 v155, v118
	v_pk_mul_f32 v[154:155], v[154:155], v[172:173]
	v_alignbit_b32 v153, v32, v153, 16
	v_cvt_pk_f16_f32 v155, v154, v155
	v_alignbit_b32 v154, v155, v32, 16
	v_lshrrev_b32_e32 v155, 16, v155
	v_fma_mixhi_f16 v155, v119, v35, 0
	v_cvt_f32_f16_e32 v32, v148
	v_cvt_f32_f16_sdwa v35, v148 dst_sel:DWORD dst_unused:UNUSED_PAD src0_sel:WORD_1
	v_cvt_f32_f16_e32 v148, v149
	v_cvt_f32_f16_sdwa v149, v149 dst_sel:DWORD dst_unused:UNUSED_PAD src0_sel:WORD_1
	v_lshl_add_u64 v[170:171], s[14:15], 0, v[170:171]
	v_lshl_add_u64 v[170:171], v[170:171], 0, v[166:167]
	v_max_f32_e32 v148, 0xc1f00000, v148
	v_mul_f32_e32 v148, 0xbfb8aa3b, v148
	global_store_dwordx4 v[170:171], v[152:155], off
	v_max_f32_e32 v35, 0xc1f00000, v35
	v_mul_f32_e32 v35, 0xbfb8aa3b, v35
	v_exp_f32_e32 v152, v148
	v_max_f32_e32 v148, 0xc1f00000, v149
	v_mul_f32_e32 v148, 0xbfb8aa3b, v148
	v_cvt_f32_f16_e32 v149, v150
	v_exp_f32_e32 v153, v148
	v_cvt_f32_f16_sdwa v148, v150 dst_sel:DWORD dst_unused:UNUSED_PAD src0_sel:WORD_1
	v_exp_f32_e32 v35, v35
	v_max_f32_e32 v149, 0xc1f00000, v149
	v_mul_f32_e32 v149, 0xbfb8aa3b, v149
	v_max_f32_e32 v148, 0xc1f00000, v148
	v_mul_f32_e32 v148, 0xbfb8aa3b, v148
	v_exp_f32_e32 v154, v149
	v_cvt_f32_f16_e32 v149, v151
	v_exp_f32_e32 v155, v148
	v_cvt_f32_f16_sdwa v148, v151 dst_sel:DWORD dst_unused:UNUSED_PAD src0_sel:WORD_1
	v_max_f32_e32 v32, 0xc1f00000, v32
	v_mul_f32_e32 v32, 0xbfb8aa3b, v32
	v_exp_f32_e32 v32, v32
	v_max_f32_e32 v149, 0xc1f00000, v149
	v_max_f32_e32 v148, 0xc1f00000, v148
	v_mul_f32_e32 v149, 0xbfb8aa3b, v149
	v_mul_f32_e32 v148, 0xbfb8aa3b, v148
	v_add_f32_e32 v35, 1.0, v35
	v_exp_f32_e32 v161, v149
	v_exp_f32_e32 v172, v148
	v_rcp_f32_e32 v148, v35
	v_add_f32_e32 v35, 1.0, v152
	v_rcp_f32_e32 v149, v35
	v_add_f32_e32 v35, 1.0, v153
	v_add_f32_e32 v32, 1.0, v32
	v_rcp_f32_e32 v150, v35
	v_add_f32_e32 v35, 1.0, v154
	v_rcp_f32_e32 v32, v32
	v_rcp_f32_e32 v151, v35
	v_add_f32_e32 v35, 1.0, v155
	v_rcp_f32_e32 v152, v35
	v_add_f32_e32 v35, 1.0, v161
	v_rcp_f32_e32 v153, v35
	v_mov_b32_e32 v154, v89
	v_mov_b32_e32 v155, v90
	v_pk_mul_f32 v[148:149], v[154:155], v[148:149]
	v_pk_mov_b32 v[154:155], v[90:91], v[84:85] op_sel:[1,0]
	v_add_f32_e32 v35, 1.0, v172
	v_fma_mixlo_f16 v32, v88, v32, 0
	v_cvt_pk_f16_f32 v149, v148, v149
	v_pk_mul_f32 v[150:151], v[154:155], v[150:151]
	v_rcp_f32_e32 v35, v35
	v_pack_b32_f16 v148, v32, v149
	v_cvt_pk_f16_f32 v32, v150, v151
	v_mov_b32_e32 v150, v85
	v_mov_b32_e32 v151, v86
	v_pk_mul_f32 v[150:151], v[150:151], v[152:153]
	v_alignbit_b32 v149, v32, v149, 16
	v_cvt_pk_f16_f32 v151, v150, v151
	v_alignbit_b32 v150, v151, v32, 16
	v_lshrrev_b32_e32 v151, 16, v151
	v_fma_mixhi_f16 v151, v87, v35, 0
	v_cvt_f32_f16_e32 v32, v144
	v_cvt_f32_f16_sdwa v35, v144 dst_sel:DWORD dst_unused:UNUSED_PAD src0_sel:WORD_1
	v_cvt_f32_f16_e32 v144, v145
	v_cvt_f32_f16_sdwa v145, v145 dst_sel:DWORD dst_unused:UNUSED_PAD src0_sel:WORD_1
	global_store_dwordx4 v[170:171], v[148:151], off offset:256
	v_max_f32_e32 v35, 0xc1f00000, v35
	v_max_f32_e32 v144, 0xc1f00000, v144
	v_mul_f32_e32 v144, 0xbfb8aa3b, v144
	v_exp_f32_e32 v150, v144
	v_max_f32_e32 v144, 0xc1f00000, v145
	v_mul_f32_e32 v144, 0xbfb8aa3b, v144
	v_cvt_f32_f16_e32 v145, v146
	v_exp_f32_e32 v151, v144
	v_cvt_f32_f16_sdwa v144, v146 dst_sel:DWORD dst_unused:UNUSED_PAD src0_sel:WORD_1
	v_mul_f32_e32 v35, 0xbfb8aa3b, v35
	v_max_f32_e32 v145, 0xc1f00000, v145
	v_mul_f32_e32 v145, 0xbfb8aa3b, v145
	v_max_f32_e32 v144, 0xc1f00000, v144
	v_mul_f32_e32 v144, 0xbfb8aa3b, v144
	v_exp_f32_e32 v152, v145
	v_cvt_f32_f16_e32 v145, v147
	v_exp_f32_e32 v153, v144
	v_cvt_f32_f16_sdwa v144, v147 dst_sel:DWORD dst_unused:UNUSED_PAD src0_sel:WORD_1
	v_exp_f32_e32 v35, v35
	v_max_f32_e32 v32, 0xc1f00000, v32
	v_mul_f32_e32 v32, 0xbfb8aa3b, v32
	v_exp_f32_e32 v32, v32
	v_max_f32_e32 v145, 0xc1f00000, v145
	v_max_f32_e32 v144, 0xc1f00000, v144
	v_mul_f32_e32 v145, 0xbfb8aa3b, v145
	v_mul_f32_e32 v144, 0xbfb8aa3b, v144
	v_add_f32_e32 v35, 1.0, v35
	v_exp_f32_e32 v154, v145
	v_exp_f32_e32 v155, v144
	v_rcp_f32_e32 v144, v35
	v_add_f32_e32 v35, 1.0, v150
	v_rcp_f32_e32 v145, v35
	v_add_f32_e32 v35, 1.0, v151
	v_add_f32_e32 v32, 1.0, v32
	v_rcp_f32_e32 v146, v35
	v_add_f32_e32 v35, 1.0, v152
	v_rcp_f32_e32 v32, v32
	v_rcp_f32_e32 v147, v35
	v_add_f32_e32 v35, 1.0, v153
	v_rcp_f32_e32 v150, v35
	v_add_f32_e32 v35, 1.0, v154
	v_rcp_f32_e32 v151, v35
	v_mov_b32_e32 v152, v113
	v_mov_b32_e32 v153, v114
	v_pk_mul_f32 v[144:145], v[152:153], v[144:145]
	v_pk_mov_b32 v[152:153], v[114:115], v[108:109] op_sel:[1,0]
	v_add_f32_e32 v35, 1.0, v155
	v_fma_mixlo_f16 v32, v112, v32, 0
	v_cvt_pk_f16_f32 v145, v144, v145
	v_pk_mul_f32 v[146:147], v[152:153], v[146:147]
	v_rcp_f32_e32 v35, v35
	v_pack_b32_f16 v144, v32, v145
	v_cvt_pk_f16_f32 v32, v146, v147
	v_mov_b32_e32 v146, v109
	v_mov_b32_e32 v147, v110
	v_pk_mul_f32 v[146:147], v[146:147], v[150:151]
	v_alignbit_b32 v145, v32, v145, 16
	v_cvt_pk_f16_f32 v147, v146, v147
	v_alignbit_b32 v146, v147, v32, 16
	v_lshrrev_b32_e32 v147, 16, v147
	v_fma_mixhi_f16 v147, v111, v35, 0
	v_cvt_f32_f16_e32 v32, v140
	v_cvt_f32_f16_sdwa v35, v140 dst_sel:DWORD dst_unused:UNUSED_PAD src0_sel:WORD_1
	v_cvt_f32_f16_e32 v140, v141
	v_cvt_f32_f16_sdwa v141, v141 dst_sel:DWORD dst_unused:UNUSED_PAD src0_sel:WORD_1
	v_lshlrev_b64 v[148:149], 11, v[162:163]
	v_lshl_add_u64 v[148:149], s[14:15], 0, v[148:149]
	v_max_f32_e32 v140, 0xc1f00000, v140
	v_lshl_add_u64 v[148:149], v[148:149], 0, v[166:167]
	v_mul_f32_e32 v140, 0xbfb8aa3b, v140
	global_store_dwordx4 v[148:149], v[144:147], off
	v_max_f32_e32 v35, 0xc1f00000, v35
	v_mul_f32_e32 v35, 0xbfb8aa3b, v35
	v_exp_f32_e32 v144, v140
	v_max_f32_e32 v140, 0xc1f00000, v141
	v_mul_f32_e32 v140, 0xbfb8aa3b, v140
	v_cvt_f32_f16_e32 v141, v142
	v_exp_f32_e32 v145, v140
	v_cvt_f32_f16_sdwa v140, v142 dst_sel:DWORD dst_unused:UNUSED_PAD src0_sel:WORD_1
	v_exp_f32_e32 v35, v35
	v_max_f32_e32 v141, 0xc1f00000, v141
	v_mul_f32_e32 v141, 0xbfb8aa3b, v141
	v_max_f32_e32 v140, 0xc1f00000, v140
	v_mul_f32_e32 v140, 0xbfb8aa3b, v140
	v_exp_f32_e32 v146, v141
	v_cvt_f32_f16_e32 v141, v143
	v_exp_f32_e32 v147, v140
	v_cvt_f32_f16_sdwa v140, v143 dst_sel:DWORD dst_unused:UNUSED_PAD src0_sel:WORD_1
	v_max_f32_e32 v32, 0xc1f00000, v32
	v_mul_f32_e32 v32, 0xbfb8aa3b, v32
	v_exp_f32_e32 v32, v32
	v_max_f32_e32 v141, 0xc1f00000, v141
	v_max_f32_e32 v140, 0xc1f00000, v140
	v_mul_f32_e32 v141, 0xbfb8aa3b, v141
	v_mul_f32_e32 v140, 0xbfb8aa3b, v140
	v_add_f32_e32 v35, 1.0, v35
	v_exp_f32_e32 v150, v141
	v_exp_f32_e32 v151, v140
	v_rcp_f32_e32 v140, v35
	v_add_f32_e32 v35, 1.0, v144
	v_rcp_f32_e32 v141, v35
	v_add_f32_e32 v35, 1.0, v145
	v_add_f32_e32 v32, 1.0, v32
	v_rcp_f32_e32 v142, v35
	v_add_f32_e32 v35, 1.0, v146
	v_rcp_f32_e32 v32, v32
	v_rcp_f32_e32 v143, v35
	v_add_f32_e32 v35, 1.0, v147
	v_rcp_f32_e32 v144, v35
	v_add_f32_e32 v35, 1.0, v150
	v_rcp_f32_e32 v145, v35
	v_mov_b32_e32 v146, v81
	v_mov_b32_e32 v147, v82
	v_pk_mul_f32 v[140:141], v[146:147], v[140:141]
	v_pk_mov_b32 v[146:147], v[82:83], v[76:77] op_sel:[1,0]
	v_add_f32_e32 v35, 1.0, v151
	v_fma_mixlo_f16 v32, v80, v32, 0
	v_cvt_pk_f16_f32 v141, v140, v141
	v_pk_mul_f32 v[142:143], v[146:147], v[142:143]
	v_rcp_f32_e32 v35, v35
	v_pack_b32_f16 v140, v32, v141
	v_cvt_pk_f16_f32 v32, v142, v143
	v_mov_b32_e32 v142, v77
	v_mov_b32_e32 v143, v78
	v_pk_mul_f32 v[142:143], v[142:143], v[144:145]
	v_alignbit_b32 v141, v32, v141, 16
	v_cvt_pk_f16_f32 v143, v142, v143
	v_alignbit_b32 v142, v143, v32, 16
	v_lshrrev_b32_e32 v143, 16, v143
	v_fma_mixhi_f16 v143, v79, v35, 0
	v_cvt_f32_f16_e32 v32, v136
	v_cvt_f32_f16_sdwa v35, v136 dst_sel:DWORD dst_unused:UNUSED_PAD src0_sel:WORD_1
	v_cvt_f32_f16_e32 v136, v137
	v_cvt_f32_f16_sdwa v137, v137 dst_sel:DWORD dst_unused:UNUSED_PAD src0_sel:WORD_1
	global_store_dwordx4 v[148:149], v[140:143], off offset:256
	v_max_f32_e32 v35, 0xc1f00000, v35
	v_max_f32_e32 v136, 0xc1f00000, v136
	v_mul_f32_e32 v136, 0xbfb8aa3b, v136
	v_exp_f32_e32 v142, v136
	v_max_f32_e32 v136, 0xc1f00000, v137
	v_mul_f32_e32 v136, 0xbfb8aa3b, v136
	v_cvt_f32_f16_e32 v137, v138
	v_exp_f32_e32 v143, v136
	v_cvt_f32_f16_sdwa v136, v138 dst_sel:DWORD dst_unused:UNUSED_PAD src0_sel:WORD_1
	v_mul_f32_e32 v35, 0xbfb8aa3b, v35
	v_max_f32_e32 v137, 0xc1f00000, v137
	v_mul_f32_e32 v137, 0xbfb8aa3b, v137
	v_max_f32_e32 v136, 0xc1f00000, v136
	v_mul_f32_e32 v136, 0xbfb8aa3b, v136
	v_exp_f32_e32 v144, v137
	v_cvt_f32_f16_e32 v137, v139
	v_exp_f32_e32 v145, v136
	v_cvt_f32_f16_sdwa v136, v139 dst_sel:DWORD dst_unused:UNUSED_PAD src0_sel:WORD_1
	v_exp_f32_e32 v35, v35
	v_max_f32_e32 v32, 0xc1f00000, v32
	v_mul_f32_e32 v32, 0xbfb8aa3b, v32
	v_exp_f32_e32 v32, v32
	v_max_f32_e32 v137, 0xc1f00000, v137
	v_max_f32_e32 v136, 0xc1f00000, v136
	v_mul_f32_e32 v137, 0xbfb8aa3b, v137
	v_mul_f32_e32 v136, 0xbfb8aa3b, v136
	v_add_f32_e32 v35, 1.0, v35
	v_exp_f32_e32 v146, v137
	v_exp_f32_e32 v147, v136
	v_rcp_f32_e32 v136, v35
	v_add_f32_e32 v35, 1.0, v142
	v_rcp_f32_e32 v137, v35
	v_add_f32_e32 v35, 1.0, v143
	v_add_f32_e32 v32, 1.0, v32
	v_rcp_f32_e32 v138, v35
	v_add_f32_e32 v35, 1.0, v144
	v_rcp_f32_e32 v32, v32
	v_rcp_f32_e32 v139, v35
	v_add_f32_e32 v35, 1.0, v145
	v_rcp_f32_e32 v142, v35
	v_add_f32_e32 v35, 1.0, v146
	v_rcp_f32_e32 v143, v35
	v_mov_b32_e32 v144, v105
	v_mov_b32_e32 v145, v106
	v_pk_mul_f32 v[136:137], v[144:145], v[136:137]
	v_pk_mov_b32 v[144:145], v[106:107], v[100:101] op_sel:[1,0]
	v_add_f32_e32 v35, 1.0, v147
	v_fma_mixlo_f16 v32, v104, v32, 0
	v_cvt_pk_f16_f32 v137, v136, v137
	v_pk_mul_f32 v[138:139], v[144:145], v[138:139]
	v_rcp_f32_e32 v35, v35
	v_pack_b32_f16 v136, v32, v137
	v_cvt_pk_f16_f32 v32, v138, v139
	v_mov_b32_e32 v138, v101
	v_mov_b32_e32 v139, v102
	v_pk_mul_f32 v[138:139], v[138:139], v[142:143]
	v_alignbit_b32 v137, v32, v137, 16
	v_cvt_pk_f16_f32 v139, v138, v139
	v_alignbit_b32 v138, v139, v32, 16
	v_lshrrev_b32_e32 v139, 16, v139
	v_fma_mixhi_f16 v139, v103, v35, 0
	v_cvt_f32_f16_e32 v32, v132
	v_cvt_f32_f16_sdwa v35, v132 dst_sel:DWORD dst_unused:UNUSED_PAD src0_sel:WORD_1
	v_cvt_f32_f16_e32 v132, v133
	v_cvt_f32_f16_sdwa v133, v133 dst_sel:DWORD dst_unused:UNUSED_PAD src0_sel:WORD_1
	v_lshlrev_b64 v[140:141], 11, v[164:165]
	v_lshl_add_u64 v[140:141], s[14:15], 0, v[140:141]
	v_max_f32_e32 v132, 0xc1f00000, v132
	v_lshl_add_u64 v[140:141], v[140:141], 0, v[166:167]
	v_mul_f32_e32 v132, 0xbfb8aa3b, v132
	global_store_dwordx4 v[140:141], v[136:139], off
	v_max_f32_e32 v35, 0xc1f00000, v35
	v_mul_f32_e32 v35, 0xbfb8aa3b, v35
	v_exp_f32_e32 v136, v132
	v_max_f32_e32 v132, 0xc1f00000, v133
	v_mul_f32_e32 v132, 0xbfb8aa3b, v132
	v_cvt_f32_f16_e32 v133, v134
	v_exp_f32_e32 v137, v132
	v_cvt_f32_f16_sdwa v132, v134 dst_sel:DWORD dst_unused:UNUSED_PAD src0_sel:WORD_1
	v_exp_f32_e32 v35, v35
	v_max_f32_e32 v133, 0xc1f00000, v133
	v_mul_f32_e32 v133, 0xbfb8aa3b, v133
	v_max_f32_e32 v132, 0xc1f00000, v132
	v_mul_f32_e32 v132, 0xbfb8aa3b, v132
	v_exp_f32_e32 v138, v133
	v_cvt_f32_f16_e32 v133, v135
	v_exp_f32_e32 v139, v132
	v_cvt_f32_f16_sdwa v132, v135 dst_sel:DWORD dst_unused:UNUSED_PAD src0_sel:WORD_1
	v_max_f32_e32 v32, 0xc1f00000, v32
	v_mul_f32_e32 v32, 0xbfb8aa3b, v32
	v_exp_f32_e32 v32, v32
	v_max_f32_e32 v133, 0xc1f00000, v133
	v_max_f32_e32 v132, 0xc1f00000, v132
	v_mul_f32_e32 v133, 0xbfb8aa3b, v133
	v_mul_f32_e32 v132, 0xbfb8aa3b, v132
	v_add_f32_e32 v35, 1.0, v35
	v_exp_f32_e32 v142, v133
	v_exp_f32_e32 v143, v132
	v_rcp_f32_e32 v132, v35
	v_add_f32_e32 v35, 1.0, v136
	v_rcp_f32_e32 v133, v35
	v_add_f32_e32 v35, 1.0, v137
	v_add_f32_e32 v32, 1.0, v32
	v_rcp_f32_e32 v134, v35
	v_add_f32_e32 v35, 1.0, v138
	v_rcp_f32_e32 v32, v32
	v_rcp_f32_e32 v135, v35
	v_add_f32_e32 v35, 1.0, v139
	v_rcp_f32_e32 v136, v35
	v_add_f32_e32 v35, 1.0, v142
	v_rcp_f32_e32 v137, v35
	v_mov_b32_e32 v138, v73
	v_mov_b32_e32 v139, v74
	v_pk_mul_f32 v[132:133], v[138:139], v[132:133]
	v_pk_mov_b32 v[138:139], v[74:75], v[68:69] op_sel:[1,0]
	v_add_f32_e32 v35, 1.0, v143
	v_fma_mixlo_f16 v32, v72, v32, 0
	v_cvt_pk_f16_f32 v133, v132, v133
	v_pk_mul_f32 v[134:135], v[138:139], v[134:135]
	v_rcp_f32_e32 v35, v35
	v_pack_b32_f16 v132, v32, v133
	v_cvt_pk_f16_f32 v32, v134, v135
	v_mov_b32_e32 v134, v69
	v_mov_b32_e32 v135, v70
	v_pk_mul_f32 v[134:135], v[134:135], v[136:137]
	v_alignbit_b32 v133, v32, v133, 16
	v_cvt_pk_f16_f32 v135, v134, v135
	v_alignbit_b32 v134, v135, v32, 16
	v_lshrrev_b32_e32 v135, 16, v135
	v_fma_mixhi_f16 v135, v71, v35, 0
	global_store_dwordx4 v[140:141], v[132:135], off offset:256
	v_add_u32_e32 v184, 0x80, v34
	s_nop 0
	v_mad_i64_i32 v[132:133], s[12:13], v184, s33, v[168:169]
	v_lshl_add_u64 v[132:133], v[132:133], 0, v[166:167]
	v_add_u32_e32 v174, 0x90, v34
	v_lshl_add_u64 v[134:135], v[132:133], 0, s[16:17]
	v_mad_i64_i32 v[136:137], s[12:13], v174, s33, v[168:169]
	v_add_co_u32_e32 v132, vcc, s1, v132
	v_lshl_add_u64 v[136:137], v[136:137], 0, v[166:167]
	v_add_u32_e32 v172, 0xa0, v34
	v_addc_co_u32_e32 v133, vcc, 0, v133, vcc
	v_lshl_add_u64 v[138:139], v[136:137], 0, s[16:17]
	v_mad_i64_i32 v[140:141], s[12:13], v172, s33, v[168:169]
	v_add_co_u32_e32 v136, vcc, s1, v136
	v_lshl_add_u64 v[140:141], v[140:141], 0, v[166:167]
	v_add_u32_e32 v170, 0xb0, v34
	v_addc_co_u32_e32 v137, vcc, 0, v137, vcc
	v_mad_i64_i32 v[144:145], s[12:13], v170, s33, v[168:169]
	global_load_dwordx4 v[176:179], v[132:133], off offset:2048
	global_load_dwordx4 v[152:155], v[136:137], off offset:2048
	global_load_dwordx4 v[180:183], v[134:135], off offset:256
	global_load_dwordx4 v[148:151], v[138:139], off offset:256
	v_add_co_u32_e32 v132, vcc, s1, v140
	v_lshl_add_u64 v[144:145], v[144:145], 0, v[166:167]
	s_nop 0
	v_addc_co_u32_e32 v133, vcc, 0, v141, vcc
	v_add_co_u32_e32 v134, vcc, s1, v144
	v_lshl_add_u64 v[142:143], v[140:141], 0, s[16:17]
	s_nop 0
	v_addc_co_u32_e32 v135, vcc, 0, v145, vcc
	v_lshl_add_u64 v[168:169], v[144:145], 0, s[16:17]
	global_load_dwordx4 v[144:147], v[132:133], off offset:2048
	global_load_dwordx4 v[136:139], v[134:135], off offset:2048
	s_nop 0
	global_load_dwordx4 v[140:143], v[142:143], off offset:256
	s_nop 0
	global_load_dwordx4 v[132:135], v[168:169], off offset:256
	v_ashrrev_i32_e32 v185, 31, v184
	v_ashrrev_i32_e32 v175, 31, v174
	v_ashrrev_i32_e32 v173, 31, v172
	v_ashrrev_i32_e32 v171, 31, v170
	s_waitcnt vmcnt(0)
	v_cvt_f32_f16_e32 v32, v176
	v_cvt_f32_f16_sdwa v35, v176 dst_sel:DWORD dst_unused:UNUSED_PAD src0_sel:WORD_1
	v_cvt_f32_f16_sdwa v176, v178 dst_sel:DWORD dst_unused:UNUSED_PAD src0_sel:WORD_1
	v_cvt_f32_f16_e32 v161, v177
	v_cvt_f32_f16_sdwa v163, v177 dst_sel:DWORD dst_unused:UNUSED_PAD src0_sel:WORD_1
	v_cvt_f32_f16_e32 v165, v178
	v_max_f32_e32 v176, 0xc1f00000, v176
	v_max_f32_e32 v35, 0xc1f00000, v35
	v_mul_f32_e32 v176, 0xbfb8aa3b, v176
	v_lshlrev_b64 v[168:169], 11, v[184:185]
	v_mul_f32_e32 v35, 0xbfb8aa3b, v35
	v_max_f32_e32 v161, 0xc1f00000, v161
	v_cvt_f32_f16_e32 v177, v179
	v_exp_f32_e32 v184, v176
	v_cvt_f32_f16_sdwa v176, v179 dst_sel:DWORD dst_unused:UNUSED_PAD src0_sel:WORD_1
	v_exp_f32_e32 v35, v35
	v_mul_f32_e32 v161, 0xbfb8aa3b, v161
	v_max_f32_e32 v163, 0xc1f00000, v163
	v_max_f32_e32 v32, 0xc1f00000, v32
	v_exp_f32_e32 v161, v161
	v_mul_f32_e32 v163, 0xbfb8aa3b, v163
	v_max_f32_e32 v165, 0xc1f00000, v165
	v_mul_f32_e32 v32, 0xbfb8aa3b, v32
	v_exp_f32_e32 v163, v163
	v_mul_f32_e32 v165, 0xbfb8aa3b, v165
	v_exp_f32_e32 v32, v32
	v_exp_f32_e32 v165, v165
	v_max_f32_e32 v177, 0xc1f00000, v177
	v_max_f32_e32 v176, 0xc1f00000, v176
	v_mul_f32_e32 v177, 0xbfb8aa3b, v177
	v_mul_f32_e32 v176, 0xbfb8aa3b, v176
	v_add_f32_e32 v35, 1.0, v35
	v_exp_f32_e32 v185, v177
	v_exp_f32_e32 v186, v176
	v_rcp_f32_e32 v176, v35
	v_add_f32_e32 v35, 1.0, v161
	v_rcp_f32_e32 v177, v35
	v_add_f32_e32 v35, 1.0, v163
	v_add_f32_e32 v32, 1.0, v32
	v_rcp_f32_e32 v178, v35
	v_add_f32_e32 v35, 1.0, v165
	v_rcp_f32_e32 v32, v32
	v_rcp_f32_e32 v179, v35
	v_add_f32_e32 v35, 1.0, v184
	v_rcp_f32_e32 v184, v35
	v_add_f32_e32 v35, 1.0, v185
	v_rcp_f32_e32 v185, v35
	v_add_f32_e32 v35, 1.0, v186
	v_mov_b32_e32 v186, v65
	v_mov_b32_e32 v187, v66
	v_pk_mul_f32 v[176:177], v[186:187], v[176:177]
	v_pk_mov_b32 v[186:187], v[66:67], v[60:61] op_sel:[1,0]
	v_fma_mixlo_f16 v32, v64, v32, 0
	v_cvt_pk_f16_f32 v161, v176, v177
	v_pk_mul_f32 v[178:179], v[186:187], v[178:179]
	v_rcp_f32_e32 v35, v35
	v_pack_b32_f16 v176, v32, v161
	v_cvt_pk_f16_f32 v32, v178, v179
	v_mov_b32_e32 v178, v61
	v_mov_b32_e32 v179, v62
	v_pk_mul_f32 v[178:179], v[178:179], v[184:185]
	v_alignbit_b32 v177, v32, v161, 16
	v_cvt_pk_f16_f32 v161, v178, v179
	v_lshrrev_b32_e32 v179, 16, v161
	v_lshl_add_u64 v[168:169], s[14:15], 0, v[168:169]
	v_alignbit_b32 v178, v161, v32, 16
	v_fma_mixhi_f16 v179, v63, v35, 0
	v_lshl_add_u64 v[168:169], v[168:169], 0, v[166:167]
	global_store_dwordx4 v[168:169], v[176:179], off
	v_cvt_f32_f16_sdwa v35, v180 dst_sel:DWORD dst_unused:UNUSED_PAD src0_sel:WORD_1
	v_cvt_f32_f16_e32 v161, v181
	v_cvt_f32_f16_sdwa v176, v182 dst_sel:DWORD dst_unused:UNUSED_PAD src0_sel:WORD_1
	v_cvt_f32_f16_sdwa v163, v181 dst_sel:DWORD dst_unused:UNUSED_PAD src0_sel:WORD_1
	v_cvt_f32_f16_e32 v32, v180
	v_cvt_f32_f16_e32 v165, v182
	v_max_f32_e32 v176, 0xc1f00000, v176
	v_max_f32_e32 v35, 0xc1f00000, v35
	v_mul_f32_e32 v176, 0xbfb8aa3b, v176
	v_mul_f32_e32 v35, 0xbfb8aa3b, v35
	v_max_f32_e32 v161, 0xc1f00000, v161
	v_cvt_f32_f16_e32 v177, v183
	v_exp_f32_e32 v180, v176
	v_cvt_f32_f16_sdwa v176, v183 dst_sel:DWORD dst_unused:UNUSED_PAD src0_sel:WORD_1
	v_exp_f32_e32 v35, v35
	v_mul_f32_e32 v161, 0xbfb8aa3b, v161
	v_max_f32_e32 v163, 0xc1f00000, v163
	v_max_f32_e32 v32, 0xc1f00000, v32
	v_exp_f32_e32 v161, v161
	v_mul_f32_e32 v163, 0xbfb8aa3b, v163
	v_max_f32_e32 v165, 0xc1f00000, v165
	v_mul_f32_e32 v32, 0xbfb8aa3b, v32
	v_exp_f32_e32 v163, v163
	v_mul_f32_e32 v165, 0xbfb8aa3b, v165
	v_exp_f32_e32 v32, v32
	v_exp_f32_e32 v165, v165
	v_max_f32_e32 v177, 0xc1f00000, v177
	v_max_f32_e32 v176, 0xc1f00000, v176
	v_mul_f32_e32 v177, 0xbfb8aa3b, v177
	v_mul_f32_e32 v176, 0xbfb8aa3b, v176
	v_add_f32_e32 v35, 1.0, v35
	v_exp_f32_e32 v181, v177
	v_exp_f32_e32 v182, v176
	v_rcp_f32_e32 v176, v35
	v_add_f32_e32 v35, 1.0, v161
	v_rcp_f32_e32 v177, v35
	v_add_f32_e32 v35, 1.0, v163
	v_add_f32_e32 v32, 1.0, v32
	v_rcp_f32_e32 v178, v35
	v_add_f32_e32 v35, 1.0, v165
	v_rcp_f32_e32 v32, v32
	v_rcp_f32_e32 v179, v35
	v_add_f32_e32 v35, 1.0, v180
	v_rcp_f32_e32 v180, v35
	v_add_f32_e32 v35, 1.0, v181
	v_rcp_f32_e32 v181, v35
	v_add_f32_e32 v35, 1.0, v182
	v_mov_b32_e32 v182, v29
	v_mov_b32_e32 v183, v30
	v_pk_mul_f32 v[176:177], v[182:183], v[176:177]
	v_pk_mov_b32 v[182:183], v[30:31], v[24:25] op_sel:[1,0]
	v_fma_mixlo_f16 v32, v28, v32, 0
	v_cvt_pk_f16_f32 v161, v176, v177
	v_pk_mul_f32 v[178:179], v[182:183], v[178:179]
	v_rcp_f32_e32 v35, v35
	v_pack_b32_f16 v176, v32, v161
	v_cvt_pk_f16_f32 v32, v178, v179
	v_mov_b32_e32 v178, v25
	v_mov_b32_e32 v179, v26
	v_pk_mul_f32 v[178:179], v[178:179], v[180:181]
	v_alignbit_b32 v177, v32, v161, 16
	v_cvt_pk_f16_f32 v161, v178, v179
	v_lshrrev_b32_e32 v179, 16, v161
	v_alignbit_b32 v178, v161, v32, 16
	v_fma_mixhi_f16 v179, v27, v35, 0
	v_cvt_f32_f16_e32 v32, v152
	v_cvt_f32_f16_sdwa v35, v152 dst_sel:DWORD dst_unused:UNUSED_PAD src0_sel:WORD_1
	v_cvt_f32_f16_e32 v152, v153
	v_cvt_f32_f16_sdwa v153, v153 dst_sel:DWORD dst_unused:UNUSED_PAD src0_sel:WORD_1
	global_store_dwordx4 v[168:169], v[176:179], off offset:256
	v_max_f32_e32 v35, 0xc1f00000, v35
	v_max_f32_e32 v152, 0xc1f00000, v152
	v_mul_f32_e32 v152, 0xbfb8aa3b, v152
	v_exp_f32_e32 v161, v152
	v_max_f32_e32 v152, 0xc1f00000, v153
	v_mul_f32_e32 v152, 0xbfb8aa3b, v152
	v_cvt_f32_f16_e32 v153, v154
	v_exp_f32_e32 v163, v152
	v_cvt_f32_f16_sdwa v152, v154 dst_sel:DWORD dst_unused:UNUSED_PAD src0_sel:WORD_1
	v_lshlrev_b64 v[168:169], 11, v[174:175]
	v_max_f32_e32 v153, 0xc1f00000, v153
	v_mul_f32_e32 v153, 0xbfb8aa3b, v153
	v_max_f32_e32 v152, 0xc1f00000, v152
	v_mul_f32_e32 v152, 0xbfb8aa3b, v152
	v_mul_f32_e32 v35, 0xbfb8aa3b, v35
	v_exp_f32_e32 v165, v153
	v_cvt_f32_f16_e32 v153, v155
	v_exp_f32_e32 v174, v152
	v_cvt_f32_f16_sdwa v152, v155 dst_sel:DWORD dst_unused:UNUSED_PAD src0_sel:WORD_1
	v_exp_f32_e32 v35, v35
	v_max_f32_e32 v32, 0xc1f00000, v32
	v_mul_f32_e32 v32, 0xbfb8aa3b, v32
	v_exp_f32_e32 v32, v32
	v_max_f32_e32 v153, 0xc1f00000, v153
	v_max_f32_e32 v152, 0xc1f00000, v152
	v_mul_f32_e32 v153, 0xbfb8aa3b, v153
	v_mul_f32_e32 v152, 0xbfb8aa3b, v152
	v_add_f32_e32 v35, 1.0, v35
	v_exp_f32_e32 v175, v153
	v_exp_f32_e32 v176, v152
	v_rcp_f32_e32 v152, v35
	v_add_f32_e32 v35, 1.0, v161
	v_rcp_f32_e32 v153, v35
	v_add_f32_e32 v35, 1.0, v163
	v_add_f32_e32 v32, 1.0, v32
	v_rcp_f32_e32 v154, v35
	v_add_f32_e32 v35, 1.0, v165
	v_rcp_f32_e32 v32, v32
	v_rcp_f32_e32 v155, v35
	v_add_f32_e32 v35, 1.0, v174
	v_rcp_f32_e32 v174, v35
	v_add_f32_e32 v35, 1.0, v175
	v_rcp_f32_e32 v175, v35
	v_add_f32_e32 v35, 1.0, v176
	v_mov_b32_e32 v176, v57
	v_mov_b32_e32 v177, v58
	v_pk_mul_f32 v[152:153], v[176:177], v[152:153]
	v_pk_mov_b32 v[176:177], v[58:59], v[52:53] op_sel:[1,0]
	v_fma_mixlo_f16 v32, v56, v32, 0
	v_cvt_pk_f16_f32 v153, v152, v153
	v_pk_mul_f32 v[154:155], v[176:177], v[154:155]
	v_rcp_f32_e32 v35, v35
	v_pack_b32_f16 v152, v32, v153
	v_cvt_pk_f16_f32 v32, v154, v155
	v_mov_b32_e32 v154, v53
	v_mov_b32_e32 v155, v54
	v_pk_mul_f32 v[154:155], v[154:155], v[174:175]
	v_alignbit_b32 v153, v32, v153, 16
	v_cvt_pk_f16_f32 v155, v154, v155
	v_alignbit_b32 v154, v155, v32, 16
	v_lshrrev_b32_e32 v155, 16, v155
	v_fma_mixhi_f16 v155, v55, v35, 0
	v_cvt_f32_f16_e32 v32, v148
	v_cvt_f32_f16_sdwa v35, v148 dst_sel:DWORD dst_unused:UNUSED_PAD src0_sel:WORD_1
	v_cvt_f32_f16_e32 v148, v149
	v_cvt_f32_f16_sdwa v149, v149 dst_sel:DWORD dst_unused:UNUSED_PAD src0_sel:WORD_1
	v_lshl_add_u64 v[168:169], s[14:15], 0, v[168:169]
	v_lshl_add_u64 v[168:169], v[168:169], 0, v[166:167]
	v_max_f32_e32 v148, 0xc1f00000, v148
	v_mul_f32_e32 v148, 0xbfb8aa3b, v148
	global_store_dwordx4 v[168:169], v[152:155], off
	v_max_f32_e32 v35, 0xc1f00000, v35
	v_mul_f32_e32 v35, 0xbfb8aa3b, v35
	v_exp_f32_e32 v152, v148
	v_max_f32_e32 v148, 0xc1f00000, v149
	v_mul_f32_e32 v148, 0xbfb8aa3b, v148
	v_cvt_f32_f16_e32 v149, v150
	v_exp_f32_e32 v153, v148
	v_cvt_f32_f16_sdwa v148, v150 dst_sel:DWORD dst_unused:UNUSED_PAD src0_sel:WORD_1
	v_exp_f32_e32 v35, v35
	v_max_f32_e32 v149, 0xc1f00000, v149
	v_mul_f32_e32 v149, 0xbfb8aa3b, v149
	v_max_f32_e32 v148, 0xc1f00000, v148
	v_mul_f32_e32 v148, 0xbfb8aa3b, v148
	v_exp_f32_e32 v154, v149
	v_cvt_f32_f16_e32 v149, v151
	v_exp_f32_e32 v155, v148
	v_cvt_f32_f16_sdwa v148, v151 dst_sel:DWORD dst_unused:UNUSED_PAD src0_sel:WORD_1
	v_max_f32_e32 v32, 0xc1f00000, v32
	v_mul_f32_e32 v32, 0xbfb8aa3b, v32
	v_exp_f32_e32 v32, v32
	v_max_f32_e32 v149, 0xc1f00000, v149
	v_max_f32_e32 v148, 0xc1f00000, v148
	v_mul_f32_e32 v149, 0xbfb8aa3b, v149
	v_mul_f32_e32 v148, 0xbfb8aa3b, v148
	v_add_f32_e32 v35, 1.0, v35
	v_exp_f32_e32 v161, v149
	v_exp_f32_e32 v163, v148
	v_rcp_f32_e32 v148, v35
	v_add_f32_e32 v35, 1.0, v152
	v_rcp_f32_e32 v149, v35
	v_add_f32_e32 v35, 1.0, v153
	v_add_f32_e32 v32, 1.0, v32
	v_rcp_f32_e32 v150, v35
	v_add_f32_e32 v35, 1.0, v154
	v_rcp_f32_e32 v32, v32
	v_rcp_f32_e32 v151, v35
	v_add_f32_e32 v35, 1.0, v155
	v_rcp_f32_e32 v152, v35
	v_add_f32_e32 v35, 1.0, v161
	v_rcp_f32_e32 v153, v35
	v_mov_b32_e32 v154, v21
	v_mov_b32_e32 v155, v22
	v_pk_mul_f32 v[148:149], v[154:155], v[148:149]
	v_pk_mov_b32 v[154:155], v[22:23], v[16:17] op_sel:[1,0]
	v_add_f32_e32 v35, 1.0, v163
	v_fma_mixlo_f16 v32, v20, v32, 0
	v_cvt_pk_f16_f32 v149, v148, v149
	v_pk_mul_f32 v[150:151], v[154:155], v[150:151]
	v_rcp_f32_e32 v35, v35
	v_pack_b32_f16 v148, v32, v149
	v_cvt_pk_f16_f32 v32, v150, v151
	v_mov_b32_e32 v150, v17
	v_mov_b32_e32 v151, v18
	v_pk_mul_f32 v[150:151], v[150:151], v[152:153]
	v_alignbit_b32 v149, v32, v149, 16
	v_cvt_pk_f16_f32 v151, v150, v151
	v_alignbit_b32 v150, v151, v32, 16
	v_lshrrev_b32_e32 v151, 16, v151
	v_fma_mixhi_f16 v151, v19, v35, 0
	v_cvt_f32_f16_e32 v32, v144
	v_cvt_f32_f16_sdwa v35, v144 dst_sel:DWORD dst_unused:UNUSED_PAD src0_sel:WORD_1
	v_cvt_f32_f16_e32 v144, v145
	v_cvt_f32_f16_sdwa v145, v145 dst_sel:DWORD dst_unused:UNUSED_PAD src0_sel:WORD_1
	global_store_dwordx4 v[168:169], v[148:151], off offset:256
	v_max_f32_e32 v35, 0xc1f00000, v35
	v_max_f32_e32 v144, 0xc1f00000, v144
	v_mul_f32_e32 v144, 0xbfb8aa3b, v144
	v_exp_f32_e32 v150, v144
	v_max_f32_e32 v144, 0xc1f00000, v145
	v_mul_f32_e32 v144, 0xbfb8aa3b, v144
	v_cvt_f32_f16_e32 v145, v146
	v_exp_f32_e32 v151, v144
	v_cvt_f32_f16_sdwa v144, v146 dst_sel:DWORD dst_unused:UNUSED_PAD src0_sel:WORD_1
	v_mul_f32_e32 v35, 0xbfb8aa3b, v35
	v_max_f32_e32 v145, 0xc1f00000, v145
	v_mul_f32_e32 v145, 0xbfb8aa3b, v145
	v_max_f32_e32 v144, 0xc1f00000, v144
	v_mul_f32_e32 v144, 0xbfb8aa3b, v144
	v_exp_f32_e32 v152, v145
	v_cvt_f32_f16_e32 v145, v147
	v_exp_f32_e32 v153, v144
	v_cvt_f32_f16_sdwa v144, v147 dst_sel:DWORD dst_unused:UNUSED_PAD src0_sel:WORD_1
	v_exp_f32_e32 v35, v35
	v_max_f32_e32 v32, 0xc1f00000, v32
	v_mul_f32_e32 v32, 0xbfb8aa3b, v32
	v_exp_f32_e32 v32, v32
	v_max_f32_e32 v145, 0xc1f00000, v145
	v_max_f32_e32 v144, 0xc1f00000, v144
	v_mul_f32_e32 v145, 0xbfb8aa3b, v145
	v_mul_f32_e32 v144, 0xbfb8aa3b, v144
	v_add_f32_e32 v35, 1.0, v35
	v_exp_f32_e32 v154, v145
	v_exp_f32_e32 v155, v144
	v_rcp_f32_e32 v144, v35
	v_add_f32_e32 v35, 1.0, v150
	v_rcp_f32_e32 v145, v35
	v_add_f32_e32 v35, 1.0, v151
	v_add_f32_e32 v32, 1.0, v32
	v_rcp_f32_e32 v146, v35
	v_add_f32_e32 v35, 1.0, v152
	v_rcp_f32_e32 v32, v32
	v_rcp_f32_e32 v147, v35
	v_add_f32_e32 v35, 1.0, v153
	v_rcp_f32_e32 v150, v35
	v_add_f32_e32 v35, 1.0, v154
	v_rcp_f32_e32 v151, v35
	v_mov_b32_e32 v152, v49
	v_mov_b32_e32 v153, v50
	v_pk_mul_f32 v[144:145], v[152:153], v[144:145]
	v_pk_mov_b32 v[152:153], v[50:51], v[44:45] op_sel:[1,0]
	v_add_f32_e32 v35, 1.0, v155
	v_fma_mixlo_f16 v32, v48, v32, 0
	v_cvt_pk_f16_f32 v145, v144, v145
	v_pk_mul_f32 v[146:147], v[152:153], v[146:147]
	v_rcp_f32_e32 v35, v35
	v_pack_b32_f16 v144, v32, v145
	v_cvt_pk_f16_f32 v32, v146, v147
	v_mov_b32_e32 v146, v45
	v_mov_b32_e32 v147, v46
	v_pk_mul_f32 v[146:147], v[146:147], v[150:151]
	v_alignbit_b32 v145, v32, v145, 16
	v_cvt_pk_f16_f32 v147, v146, v147
	v_alignbit_b32 v146, v147, v32, 16
	v_lshrrev_b32_e32 v147, 16, v147
	v_fma_mixhi_f16 v147, v47, v35, 0
	v_cvt_f32_f16_e32 v32, v140
	v_cvt_f32_f16_sdwa v35, v140 dst_sel:DWORD dst_unused:UNUSED_PAD src0_sel:WORD_1
	v_cvt_f32_f16_e32 v140, v141
	v_cvt_f32_f16_sdwa v141, v141 dst_sel:DWORD dst_unused:UNUSED_PAD src0_sel:WORD_1
	v_lshlrev_b64 v[148:149], 11, v[172:173]
	v_lshl_add_u64 v[148:149], s[14:15], 0, v[148:149]
	v_max_f32_e32 v140, 0xc1f00000, v140
	v_lshl_add_u64 v[148:149], v[148:149], 0, v[166:167]
	v_mul_f32_e32 v140, 0xbfb8aa3b, v140
	global_store_dwordx4 v[148:149], v[144:147], off
	v_max_f32_e32 v35, 0xc1f00000, v35
	v_mul_f32_e32 v35, 0xbfb8aa3b, v35
	v_exp_f32_e32 v144, v140
	v_max_f32_e32 v140, 0xc1f00000, v141
	v_mul_f32_e32 v140, 0xbfb8aa3b, v140
	v_cvt_f32_f16_e32 v141, v142
	v_exp_f32_e32 v145, v140
	v_cvt_f32_f16_sdwa v140, v142 dst_sel:DWORD dst_unused:UNUSED_PAD src0_sel:WORD_1
	v_exp_f32_e32 v35, v35
	v_max_f32_e32 v141, 0xc1f00000, v141
	v_mul_f32_e32 v141, 0xbfb8aa3b, v141
	v_max_f32_e32 v140, 0xc1f00000, v140
	v_mul_f32_e32 v140, 0xbfb8aa3b, v140
	v_exp_f32_e32 v146, v141
	v_cvt_f32_f16_e32 v141, v143
	v_exp_f32_e32 v147, v140
	v_cvt_f32_f16_sdwa v140, v143 dst_sel:DWORD dst_unused:UNUSED_PAD src0_sel:WORD_1
	v_max_f32_e32 v32, 0xc1f00000, v32
	v_mul_f32_e32 v32, 0xbfb8aa3b, v32
	v_exp_f32_e32 v32, v32
	v_max_f32_e32 v141, 0xc1f00000, v141
	v_max_f32_e32 v140, 0xc1f00000, v140
	v_mul_f32_e32 v141, 0xbfb8aa3b, v141
	v_mul_f32_e32 v140, 0xbfb8aa3b, v140
	v_add_f32_e32 v35, 1.0, v35
	v_exp_f32_e32 v150, v141
	v_exp_f32_e32 v151, v140
	v_rcp_f32_e32 v140, v35
	v_add_f32_e32 v35, 1.0, v144
	v_rcp_f32_e32 v141, v35
	v_add_f32_e32 v35, 1.0, v145
	v_add_f32_e32 v32, 1.0, v32
	v_rcp_f32_e32 v142, v35
	v_add_f32_e32 v35, 1.0, v146
	v_rcp_f32_e32 v32, v32
	v_rcp_f32_e32 v143, v35
	v_add_f32_e32 v35, 1.0, v147
	v_rcp_f32_e32 v144, v35
	v_add_f32_e32 v35, 1.0, v150
	v_rcp_f32_e32 v145, v35
	v_mov_b32_e32 v146, v13
	v_mov_b32_e32 v147, v14
	v_pk_mul_f32 v[140:141], v[146:147], v[140:141]
	v_pk_mov_b32 v[146:147], v[14:15], v[8:9] op_sel:[1,0]
	v_add_f32_e32 v35, 1.0, v151
	v_fma_mixlo_f16 v32, v12, v32, 0
	v_cvt_pk_f16_f32 v141, v140, v141
	v_pk_mul_f32 v[142:143], v[146:147], v[142:143]
	v_rcp_f32_e32 v35, v35
	v_pack_b32_f16 v140, v32, v141
	v_cvt_pk_f16_f32 v32, v142, v143
	v_mov_b32_e32 v142, v9
	v_mov_b32_e32 v143, v10
	v_pk_mul_f32 v[142:143], v[142:143], v[144:145]
	v_alignbit_b32 v141, v32, v141, 16
	v_cvt_pk_f16_f32 v143, v142, v143
	v_alignbit_b32 v142, v143, v32, 16
	v_lshrrev_b32_e32 v143, 16, v143
	v_fma_mixhi_f16 v143, v11, v35, 0
	v_cvt_f32_f16_e32 v32, v136
	v_cvt_f32_f16_sdwa v35, v136 dst_sel:DWORD dst_unused:UNUSED_PAD src0_sel:WORD_1
	v_cvt_f32_f16_e32 v136, v137
	v_cvt_f32_f16_sdwa v137, v137 dst_sel:DWORD dst_unused:UNUSED_PAD src0_sel:WORD_1
	global_store_dwordx4 v[148:149], v[140:143], off offset:256
	v_max_f32_e32 v35, 0xc1f00000, v35
	v_max_f32_e32 v136, 0xc1f00000, v136
	v_mul_f32_e32 v136, 0xbfb8aa3b, v136
	v_exp_f32_e32 v142, v136
	v_max_f32_e32 v136, 0xc1f00000, v137
	v_mul_f32_e32 v136, 0xbfb8aa3b, v136
	v_cvt_f32_f16_e32 v137, v138
	v_exp_f32_e32 v143, v136
	v_cvt_f32_f16_sdwa v136, v138 dst_sel:DWORD dst_unused:UNUSED_PAD src0_sel:WORD_1
	v_mul_f32_e32 v35, 0xbfb8aa3b, v35
	v_max_f32_e32 v137, 0xc1f00000, v137
	v_mul_f32_e32 v137, 0xbfb8aa3b, v137
	v_max_f32_e32 v136, 0xc1f00000, v136
	v_mul_f32_e32 v136, 0xbfb8aa3b, v136
	v_exp_f32_e32 v144, v137
	v_cvt_f32_f16_e32 v137, v139
	v_exp_f32_e32 v145, v136
	v_cvt_f32_f16_sdwa v136, v139 dst_sel:DWORD dst_unused:UNUSED_PAD src0_sel:WORD_1
	v_exp_f32_e32 v35, v35
	v_max_f32_e32 v32, 0xc1f00000, v32
	v_mul_f32_e32 v32, 0xbfb8aa3b, v32
	v_exp_f32_e32 v32, v32
	v_max_f32_e32 v137, 0xc1f00000, v137
	v_max_f32_e32 v136, 0xc1f00000, v136
	v_mul_f32_e32 v137, 0xbfb8aa3b, v137
	v_mul_f32_e32 v136, 0xbfb8aa3b, v136
	v_add_f32_e32 v35, 1.0, v35
	v_exp_f32_e32 v146, v137
	v_exp_f32_e32 v147, v136
	v_rcp_f32_e32 v136, v35
	v_add_f32_e32 v35, 1.0, v142
	v_rcp_f32_e32 v137, v35
	v_add_f32_e32 v35, 1.0, v143
	v_add_f32_e32 v32, 1.0, v32
	v_rcp_f32_e32 v138, v35
	v_add_f32_e32 v35, 1.0, v144
	v_rcp_f32_e32 v32, v32
	v_rcp_f32_e32 v139, v35
	v_add_f32_e32 v35, 1.0, v145
	v_rcp_f32_e32 v142, v35
	v_add_f32_e32 v35, 1.0, v146
	v_rcp_f32_e32 v143, v35
	v_mov_b32_e32 v144, v41
	v_mov_b32_e32 v145, v42
	v_pk_mul_f32 v[136:137], v[144:145], v[136:137]
	v_pk_mov_b32 v[144:145], v[42:43], v[36:37] op_sel:[1,0]
	v_add_f32_e32 v35, 1.0, v147
	v_fma_mixlo_f16 v32, v40, v32, 0
	v_cvt_pk_f16_f32 v137, v136, v137
	v_pk_mul_f32 v[138:139], v[144:145], v[138:139]
	v_rcp_f32_e32 v35, v35
	v_pack_b32_f16 v136, v32, v137
	v_cvt_pk_f16_f32 v32, v138, v139
	v_mov_b32_e32 v138, v37
	v_mov_b32_e32 v139, v38
	v_pk_mul_f32 v[138:139], v[138:139], v[142:143]
	v_alignbit_b32 v137, v32, v137, 16
	v_cvt_pk_f16_f32 v139, v138, v139
	v_alignbit_b32 v138, v139, v32, 16
	v_lshrrev_b32_e32 v139, 16, v139
	v_fma_mixhi_f16 v139, v39, v35, 0
	v_cvt_f32_f16_e32 v32, v132
	v_cvt_f32_f16_sdwa v35, v132 dst_sel:DWORD dst_unused:UNUSED_PAD src0_sel:WORD_1
	v_cvt_f32_f16_e32 v132, v133
	v_cvt_f32_f16_sdwa v133, v133 dst_sel:DWORD dst_unused:UNUSED_PAD src0_sel:WORD_1
	v_lshlrev_b64 v[140:141], 11, v[170:171]
	v_lshl_add_u64 v[140:141], s[14:15], 0, v[140:141]
	v_max_f32_e32 v132, 0xc1f00000, v132
	v_lshl_add_u64 v[140:141], v[140:141], 0, v[166:167]
	v_mul_f32_e32 v132, 0xbfb8aa3b, v132
	global_store_dwordx4 v[140:141], v[136:139], off
	v_max_f32_e32 v35, 0xc1f00000, v35
	v_mul_f32_e32 v35, 0xbfb8aa3b, v35
	v_exp_f32_e32 v136, v132
	v_max_f32_e32 v132, 0xc1f00000, v133
	v_mul_f32_e32 v132, 0xbfb8aa3b, v132
	v_cvt_f32_f16_e32 v133, v134
	v_exp_f32_e32 v137, v132
	v_cvt_f32_f16_sdwa v132, v134 dst_sel:DWORD dst_unused:UNUSED_PAD src0_sel:WORD_1
	v_exp_f32_e32 v35, v35
	v_max_f32_e32 v133, 0xc1f00000, v133
	v_mul_f32_e32 v133, 0xbfb8aa3b, v133
	v_max_f32_e32 v132, 0xc1f00000, v132
	v_mul_f32_e32 v132, 0xbfb8aa3b, v132
	v_exp_f32_e32 v138, v133
	v_cvt_f32_f16_e32 v133, v135
	v_exp_f32_e32 v139, v132
	v_cvt_f32_f16_sdwa v132, v135 dst_sel:DWORD dst_unused:UNUSED_PAD src0_sel:WORD_1
	v_max_f32_e32 v32, 0xc1f00000, v32
	v_mul_f32_e32 v32, 0xbfb8aa3b, v32
	v_exp_f32_e32 v32, v32
	v_max_f32_e32 v133, 0xc1f00000, v133
	v_max_f32_e32 v132, 0xc1f00000, v132
	v_mul_f32_e32 v133, 0xbfb8aa3b, v133
	v_mul_f32_e32 v132, 0xbfb8aa3b, v132
	v_add_f32_e32 v35, 1.0, v35
	v_exp_f32_e32 v142, v133
	v_exp_f32_e32 v143, v132
	v_rcp_f32_e32 v132, v35
	v_add_f32_e32 v35, 1.0, v136
	v_rcp_f32_e32 v133, v35
	v_add_f32_e32 v35, 1.0, v137
	v_add_f32_e32 v32, 1.0, v32
	v_rcp_f32_e32 v134, v35
	v_add_f32_e32 v35, 1.0, v138
	v_rcp_f32_e32 v32, v32
	v_rcp_f32_e32 v135, v35
	v_add_f32_e32 v35, 1.0, v139
	v_rcp_f32_e32 v136, v35
	v_add_f32_e32 v35, 1.0, v142
	v_rcp_f32_e32 v137, v35
	v_mov_b32_e32 v138, v5
	v_mov_b32_e32 v139, v6
	v_pk_mul_f32 v[132:133], v[138:139], v[132:133]
	v_pk_mov_b32 v[138:139], v[6:7], v[0:1] op_sel:[1,0]
	v_add_f32_e32 v35, 1.0, v143
	v_fma_mixlo_f16 v32, v4, v32, 0
	v_cvt_pk_f16_f32 v133, v132, v133
	v_pk_mul_f32 v[134:135], v[138:139], v[134:135]
	v_rcp_f32_e32 v35, v35
	v_pack_b32_f16 v132, v32, v133
	v_cvt_pk_f16_f32 v32, v134, v135
	v_mov_b32_e32 v134, v1
	v_mov_b32_e32 v135, v2
	v_pk_mul_f32 v[134:135], v[134:135], v[136:137]
	v_alignbit_b32 v133, v32, v133, 16
	v_cvt_pk_f16_f32 v135, v134, v135
	v_alignbit_b32 v134, v135, v32, 16
	v_lshrrev_b32_e32 v135, 16, v135
	v_fma_mixhi_f16 v135, v3, v35, 0
	global_store_dwordx4 v[140:141], v[132:135], off offset:256
	s_cbranch_execnz .LBB0_944

.LBB0_958:
	s_add_u32 s12, s10, 0x100
	s_addc_u32 s13, s11, 0
	s_add_i32 s38, 0, 0x10000
	v_add_u32_e32 v142, s38, v196
	ds_read_b128 v[122:125], v142
	ds_read_b128 v[138:141], v142 offset:2048
	ds_read_b128 v[130:133], v142 offset:1024
	ds_read_b128 v[142:145], v142 offset:3072
	s_cmp_eq_u32 s37, 12
	s_cselect_b32 s17, s7, s13
	s_cselect_b32 s16, s6, s12
	s_cselect_b32 s15, s9, s36
	s_cselect_b32 s14, s8, s35
	v_lshl_add_u64 v[230:231], s[10:11], 0, v[188:189]
	s_add_i32 m0, s21, 0xc000
	ds_read_b128 v[146:149], v198
	ds_read_b128 v[192:195], v198 offset:2048
	ds_read_b128 v[204:207], v198 offset:4096
	ds_read_b128 v[212:215], v198 offset:6144
	ds_read_b128 v[150:153], v198 offset:1024
	ds_read_b128 v[200:203], v198 offset:3072
	ds_read_b128 v[208:211], v198 offset:5120
	ds_read_b128 v[216:219], v198 offset:7168
	global_load_lds_dwordx4 v[230:231], off
	v_lshl_add_u64 v[230:231], s[10:11], 0, v[190:191]
	s_add_i32 m0, s21, 0xe000
	s_nop 0
	global_load_lds_dwordx4 v[230:231], off
	s_waitcnt lgkmcnt(8)
	s_setprio 1
	s_barrier
	s_waitcnt lgkmcnt(7)
	v_mfma_f32_16x16x32_f16 v[134:137], v[122:125], v[146:149], v[134:137]
	v_mfma_f32_16x16x32_f16 v[126:129], v[138:141], v[146:149], v[126:129]
	s_waitcnt lgkmcnt(6)
	v_mfma_f32_16x16x32_f16 v[110:113], v[122:125], v[192:195], v[110:113]
	v_mfma_f32_16x16x32_f16 v[106:109], v[138:141], v[192:195], v[106:109]
	s_waitcnt lgkmcnt(5)
	v_mfma_f32_16x16x32_f16 v[94:97], v[122:125], v[204:207], v[94:97]
	v_mfma_f32_16x16x32_f16 v[90:93], v[138:141], v[204:207], v[90:93]
	s_waitcnt lgkmcnt(4)
	v_mfma_f32_16x16x32_f16 v[78:81], v[122:125], v[212:215], v[78:81]
	v_mfma_f32_16x16x32_f16 v[74:77], v[138:141], v[212:215], v[74:77]
	s_waitcnt lgkmcnt(3)
	v_mfma_f32_16x16x32_f16 v[134:137], v[130:133], v[150:153], v[134:137]
	v_mfma_f32_16x16x32_f16 v[126:129], v[142:145], v[150:153], v[126:129]
	s_waitcnt lgkmcnt(2)
	v_mfma_f32_16x16x32_f16 v[110:113], v[130:133], v[200:203], v[110:113]
	v_mfma_f32_16x16x32_f16 v[106:109], v[142:145], v[200:203], v[106:109]
	s_waitcnt lgkmcnt(1)
	v_mfma_f32_16x16x32_f16 v[94:97], v[130:133], v[208:211], v[94:97]
	v_mfma_f32_16x16x32_f16 v[90:93], v[142:145], v[208:211], v[90:93]
	s_waitcnt lgkmcnt(0)
	v_mfma_f32_16x16x32_f16 v[78:81], v[130:133], v[216:219], v[78:81]
	v_mfma_f32_16x16x32_f16 v[74:77], v[142:145], v[216:219], v[74:77]
	s_setprio 0
	s_barrier
	s_add_i32 s39, 0, 0x14000
	s_add_i32 s10, s38, s20
	v_add_u32_e32 v199, s39, v196
	v_lshl_add_u64 v[246:247], s[14:15], 0, v[32:33]
	s_mov_b32 m0, s10
	ds_read_b128 v[230:233], v199
	ds_read_b128 v[238:241], v199 offset:2048
	ds_read_b128 v[234:237], v199 offset:1024
	ds_read_b128 v[242:245], v199 offset:3072
	global_load_lds_dwordx4 v[246:247], off
	v_lshl_add_u64 v[248:249], s[14:15], 0, v[154:155]
	s_add_i32 m0, s10, 0x2000
	s_nop 0
	global_load_lds_dwordx4 v[248:249], off
	s_setprio 1
	s_barrier
	s_waitcnt lgkmcnt(2)
	v_mfma_f32_16x16x32_f16 v[118:121], v[230:233], v[146:149], v[118:121]
	v_mfma_f32_16x16x32_f16 v[114:117], v[238:241], v[146:149], v[114:117]
	v_mfma_f32_16x16x32_f16 v[102:105], v[230:233], v[192:195], v[102:105]
	v_mfma_f32_16x16x32_f16 v[98:101], v[238:241], v[192:195], v[98:101]
	v_mfma_f32_16x16x32_f16 v[86:89], v[230:233], v[204:207], v[86:89]
	v_mfma_f32_16x16x32_f16 v[82:85], v[238:241], v[204:207], v[82:85]
	v_mfma_f32_16x16x32_f16 v[70:73], v[230:233], v[212:215], v[70:73]
	v_mfma_f32_16x16x32_f16 v[66:69], v[238:241], v[212:215], v[66:69]
	s_waitcnt lgkmcnt(0)
	v_mfma_f32_16x16x32_f16 v[118:121], v[234:237], v[150:153], v[118:121]
	v_mfma_f32_16x16x32_f16 v[114:117], v[242:245], v[150:153], v[114:117]
	v_mfma_f32_16x16x32_f16 v[102:105], v[234:237], v[200:203], v[102:105]
	v_mfma_f32_16x16x32_f16 v[98:101], v[242:245], v[200:203], v[98:101]
	v_mfma_f32_16x16x32_f16 v[86:89], v[234:237], v[208:211], v[86:89]
	v_mfma_f32_16x16x32_f16 v[82:85], v[242:245], v[208:211], v[82:85]
	v_mfma_f32_16x16x32_f16 v[70:73], v[234:237], v[216:219], v[70:73]
	v_mfma_f32_16x16x32_f16 v[66:69], v[242:245], v[216:219], v[66:69]
	s_setprio 0
	s_mov_b32 m0, s21
	v_lshl_add_u64 v[228:229], s[16:17], 0, v[32:33]
	s_barrier
	ds_read_b128 v[146:149], v198 offset:16384
	ds_read_b128 v[192:195], v198 offset:18432
	ds_read_b128 v[204:207], v198 offset:20480
	ds_read_b128 v[212:215], v198 offset:22528
	ds_read_b128 v[150:153], v198 offset:17408
	ds_read_b128 v[200:203], v198 offset:19456
	ds_read_b128 v[208:211], v198 offset:21504
	ds_read_b128 v[216:219], v198 offset:23552
	global_load_lds_dwordx4 v[228:229], off
	v_lshl_add_u64 v[222:223], s[16:17], 0, v[154:155]
	s_mov_b32 m0, s22
	s_nop 0
	global_load_lds_dwordx4 v[222:223], off
	s_setprio 1
	s_barrier
	s_waitcnt lgkmcnt(7)
	v_mfma_f32_16x16x32_f16 v[62:65], v[122:125], v[146:149], v[62:65]
	v_mfma_f32_16x16x32_f16 v[58:61], v[138:141], v[146:149], v[58:61]
	s_waitcnt lgkmcnt(6)
	v_mfma_f32_16x16x32_f16 v[46:49], v[122:125], v[192:195], v[46:49]
	v_mfma_f32_16x16x32_f16 v[42:45], v[138:141], v[192:195], v[42:45]
	s_waitcnt lgkmcnt(5)
	v_mfma_f32_16x16x32_f16 v[28:31], v[122:125], v[204:207], v[28:31]
	v_mfma_f32_16x16x32_f16 v[24:27], v[138:141], v[204:207], v[24:27]
	s_waitcnt lgkmcnt(4)
	v_mfma_f32_16x16x32_f16 v[12:15], v[122:125], v[212:215], v[12:15]
	v_mfma_f32_16x16x32_f16 v[8:11], v[138:141], v[212:215], v[8:11]
	s_waitcnt lgkmcnt(3)
	v_mfma_f32_16x16x32_f16 v[62:65], v[130:133], v[150:153], v[62:65]
	v_mfma_f32_16x16x32_f16 v[58:61], v[142:145], v[150:153], v[58:61]
	s_waitcnt lgkmcnt(2)
	v_mfma_f32_16x16x32_f16 v[46:49], v[130:133], v[200:203], v[46:49]
	v_mfma_f32_16x16x32_f16 v[42:45], v[142:145], v[200:203], v[42:45]
	s_waitcnt lgkmcnt(1)
	v_mfma_f32_16x16x32_f16 v[28:31], v[130:133], v[208:211], v[28:31]
	v_mfma_f32_16x16x32_f16 v[24:27], v[142:145], v[208:211], v[24:27]
	s_waitcnt lgkmcnt(0)
	v_mfma_f32_16x16x32_f16 v[12:15], v[130:133], v[216:219], v[12:15]
	v_mfma_f32_16x16x32_f16 v[8:11], v[142:145], v[216:219], v[8:11]
	s_setprio 0
	s_barrier
	s_add_u32 s10, s14, 0x40000
	s_addc_u32 s11, s15, 0
	s_add_i32 s38, s39, s20
	v_lshl_add_u64 v[122:123], s[10:11], 0, v[32:33]
	s_mov_b32 m0, s38
	s_nop 0
	global_load_lds_dwordx4 v[122:123], off
	v_lshl_add_u64 v[122:123], s[10:11], 0, v[154:155]
	s_add_i32 m0, s38, 0x2000
	s_nop 0
	global_load_lds_dwordx4 v[122:123], off
	s_waitcnt vmcnt(6)
	s_setprio 1
	s_barrier
	v_mfma_f32_16x16x32_f16 v[54:57], v[230:233], v[146:149], v[54:57]
	v_mfma_f32_16x16x32_f16 v[50:53], v[238:241], v[146:149], v[50:53]
	v_mfma_f32_16x16x32_f16 v[38:41], v[230:233], v[192:195], v[38:41]
	v_mfma_f32_16x16x32_f16 v[34:37], v[238:241], v[192:195], v[34:37]
	v_mfma_f32_16x16x32_f16 v[20:23], v[230:233], v[204:207], v[20:23]
	v_mfma_f32_16x16x32_f16 v[16:19], v[238:241], v[204:207], v[16:19]
	v_mfma_f32_16x16x32_f16 v[4:7], v[230:233], v[212:215], v[4:7]
	v_mfma_f32_16x16x32_f16 v[0:3], v[238:241], v[212:215], v[0:3]
	v_mfma_f32_16x16x32_f16 v[54:57], v[234:237], v[150:153], v[54:57]
	v_mfma_f32_16x16x32_f16 v[50:53], v[242:245], v[150:153], v[50:53]
	v_mfma_f32_16x16x32_f16 v[38:41], v[234:237], v[200:203], v[38:41]
	v_mfma_f32_16x16x32_f16 v[34:37], v[242:245], v[200:203], v[34:37]
	v_mfma_f32_16x16x32_f16 v[20:23], v[234:237], v[208:211], v[20:23]
	v_mfma_f32_16x16x32_f16 v[16:19], v[242:245], v[208:211], v[16:19]
	v_mfma_f32_16x16x32_f16 v[4:7], v[234:237], v[216:219], v[4:7]
	v_mfma_f32_16x16x32_f16 v[0:3], v[242:245], v[216:219], v[0:3]
	s_setprio 0
	s_add_i32 s38, 0, 0x18000
	v_add_u32_e32 v142, s38, v196
	s_barrier
	ds_read_b128 v[122:125], v142
	ds_read_b128 v[138:141], v142 offset:2048
	ds_read_b128 v[130:133], v142 offset:1024
	ds_read_b128 v[142:145], v142 offset:3072
	s_add_u32 s10, s16, 0x40000
	s_addc_u32 s11, s17, 0
	s_mov_b32 m0, s23
	v_lshl_add_u64 v[230:231], s[10:11], 0, v[32:33]
	ds_read_b128 v[146:149], v198 offset:32768
	ds_read_b128 v[192:195], v198 offset:34816
	ds_read_b128 v[204:207], v198 offset:36864
	ds_read_b128 v[212:215], v198 offset:38912
	ds_read_b128 v[150:153], v198 offset:33792
	ds_read_b128 v[200:203], v198 offset:35840
	ds_read_b128 v[208:211], v198 offset:37888
	ds_read_b128 v[216:219], v198 offset:39936
	global_load_lds_dwordx4 v[230:231], off
	v_lshl_add_u64 v[230:231], s[10:11], 0, v[154:155]
	s_mov_b32 m0, s24
	s_nop 0
	global_load_lds_dwordx4 v[230:231], off
	s_waitcnt lgkmcnt(8)
	s_setprio 1
	s_barrier
	s_waitcnt lgkmcnt(7)
	v_mfma_f32_16x16x32_f16 v[134:137], v[122:125], v[146:149], v[134:137]
	v_mfma_f32_16x16x32_f16 v[126:129], v[138:141], v[146:149], v[126:129]
	s_waitcnt lgkmcnt(6)
	v_mfma_f32_16x16x32_f16 v[110:113], v[122:125], v[192:195], v[110:113]
	v_mfma_f32_16x16x32_f16 v[106:109], v[138:141], v[192:195], v[106:109]
	s_waitcnt lgkmcnt(5)
	v_mfma_f32_16x16x32_f16 v[94:97], v[122:125], v[204:207], v[94:97]
	v_mfma_f32_16x16x32_f16 v[90:93], v[138:141], v[204:207], v[90:93]
	s_waitcnt lgkmcnt(4)
	v_mfma_f32_16x16x32_f16 v[78:81], v[122:125], v[212:215], v[78:81]
	v_mfma_f32_16x16x32_f16 v[74:77], v[138:141], v[212:215], v[74:77]
	s_waitcnt lgkmcnt(3)
	v_mfma_f32_16x16x32_f16 v[134:137], v[130:133], v[150:153], v[134:137]
	v_mfma_f32_16x16x32_f16 v[126:129], v[142:145], v[150:153], v[126:129]
	s_waitcnt lgkmcnt(2)
	v_mfma_f32_16x16x32_f16 v[110:113], v[130:133], v[200:203], v[110:113]
	v_mfma_f32_16x16x32_f16 v[106:109], v[142:145], v[200:203], v[106:109]
	s_waitcnt lgkmcnt(1)
	v_mfma_f32_16x16x32_f16 v[94:97], v[130:133], v[208:211], v[94:97]
	v_mfma_f32_16x16x32_f16 v[90:93], v[142:145], v[208:211], v[90:93]
	s_waitcnt lgkmcnt(0)
	v_mfma_f32_16x16x32_f16 v[78:81], v[130:133], v[216:219], v[78:81]
	v_mfma_f32_16x16x32_f16 v[74:77], v[142:145], v[216:219], v[74:77]
	s_setprio 0
	s_barrier
	s_add_i32 s16, 0, 0x1c000
	s_add_i32 s10, s38, s20
	v_add_u32_e32 v199, s16, v196
	v_lshl_add_u64 v[246:247], v[246:247], 0, s[84:85]
	s_mov_b32 m0, s10
	ds_read_b128 v[230:233], v199
	ds_read_b128 v[238:241], v199 offset:2048
	ds_read_b128 v[234:237], v199 offset:1024
	ds_read_b128 v[242:245], v199 offset:3072
	global_load_lds_dwordx4 v[246:247], off
	v_lshl_add_u64 v[246:247], v[248:249], 0, s[84:85]
	s_add_i32 m0, s10, 0x2000
	s_nop 0
	global_load_lds_dwordx4 v[246:247], off
	s_setprio 1
	s_barrier
	s_waitcnt lgkmcnt(2)
	v_mfma_f32_16x16x32_f16 v[118:121], v[230:233], v[146:149], v[118:121]
	v_mfma_f32_16x16x32_f16 v[114:117], v[238:241], v[146:149], v[114:117]
	v_mfma_f32_16x16x32_f16 v[102:105], v[230:233], v[192:195], v[102:105]
	v_mfma_f32_16x16x32_f16 v[98:101], v[238:241], v[192:195], v[98:101]
	v_mfma_f32_16x16x32_f16 v[86:89], v[230:233], v[204:207], v[86:89]
	v_mfma_f32_16x16x32_f16 v[82:85], v[238:241], v[204:207], v[82:85]
	v_mfma_f32_16x16x32_f16 v[70:73], v[230:233], v[212:215], v[70:73]
	v_mfma_f32_16x16x32_f16 v[66:69], v[238:241], v[212:215], v[66:69]
	s_waitcnt lgkmcnt(0)
	v_mfma_f32_16x16x32_f16 v[118:121], v[234:237], v[150:153], v[118:121]
	v_mfma_f32_16x16x32_f16 v[114:117], v[242:245], v[150:153], v[114:117]
	v_mfma_f32_16x16x32_f16 v[102:105], v[234:237], v[200:203], v[102:105]
	v_mfma_f32_16x16x32_f16 v[98:101], v[242:245], v[200:203], v[98:101]
	v_mfma_f32_16x16x32_f16 v[86:89], v[234:237], v[208:211], v[86:89]
	v_mfma_f32_16x16x32_f16 v[82:85], v[242:245], v[208:211], v[82:85]
	v_mfma_f32_16x16x32_f16 v[70:73], v[234:237], v[216:219], v[70:73]
	v_mfma_f32_16x16x32_f16 v[66:69], v[242:245], v[216:219], v[66:69]
	s_setprio 0
	s_mov_b32 m0, s25
	v_lshl_add_u64 v[228:229], v[228:229], 0, s[84:85]
	s_barrier
	ds_read_b128 v[146:149], v198 offset:49152
	ds_read_b128 v[192:195], v198 offset:51200
	ds_read_b128 v[204:207], v198 offset:53248
	ds_read_b128 v[212:215], v198 offset:55296
	ds_read_b128 v[150:153], v198 offset:50176
	ds_read_b128 v[200:203], v198 offset:52224
	ds_read_b128 v[208:211], v198 offset:54272
	ds_read_b128 v[216:219], v198 offset:56320
	global_load_lds_dwordx4 v[228:229], off
	v_lshl_add_u64 v[222:223], v[222:223], 0, s[84:85]
	s_mov_b32 m0, s27
	s_nop 0
	global_load_lds_dwordx4 v[222:223], off
	s_setprio 1
	s_barrier
	s_waitcnt lgkmcnt(7)
	v_mfma_f32_16x16x32_f16 v[62:65], v[122:125], v[146:149], v[62:65]
	v_mfma_f32_16x16x32_f16 v[58:61], v[138:141], v[146:149], v[58:61]
	s_waitcnt lgkmcnt(6)
	v_mfma_f32_16x16x32_f16 v[46:49], v[122:125], v[192:195], v[46:49]
	v_mfma_f32_16x16x32_f16 v[42:45], v[138:141], v[192:195], v[42:45]
	s_waitcnt lgkmcnt(5)
	v_mfma_f32_16x16x32_f16 v[28:31], v[122:125], v[204:207], v[28:31]
	v_mfma_f32_16x16x32_f16 v[24:27], v[138:141], v[204:207], v[24:27]
	s_waitcnt lgkmcnt(4)
	v_mfma_f32_16x16x32_f16 v[12:15], v[122:125], v[212:215], v[12:15]
	v_mfma_f32_16x16x32_f16 v[8:11], v[138:141], v[212:215], v[8:11]
	s_waitcnt lgkmcnt(3)
	v_mfma_f32_16x16x32_f16 v[62:65], v[130:133], v[150:153], v[62:65]
	v_mfma_f32_16x16x32_f16 v[58:61], v[142:145], v[150:153], v[58:61]
	s_waitcnt lgkmcnt(2)
	v_mfma_f32_16x16x32_f16 v[46:49], v[130:133], v[200:203], v[46:49]
	v_mfma_f32_16x16x32_f16 v[42:45], v[142:145], v[200:203], v[42:45]
	s_waitcnt lgkmcnt(1)
	v_mfma_f32_16x16x32_f16 v[28:31], v[130:133], v[208:211], v[28:31]
	v_mfma_f32_16x16x32_f16 v[24:27], v[142:145], v[208:211], v[24:27]
	s_waitcnt lgkmcnt(0)
	v_mfma_f32_16x16x32_f16 v[12:15], v[130:133], v[216:219], v[12:15]
	v_mfma_f32_16x16x32_f16 v[8:11], v[142:145], v[216:219], v[8:11]
	s_setprio 0
	s_barrier
	s_add_u32 s10, s14, 0x40080
	s_addc_u32 s11, s15, 0
	s_add_i32 s14, s16, s20
	v_lshl_add_u64 v[122:123], s[10:11], 0, v[32:33]
	s_mov_b32 m0, s14
	s_nop 0
	global_load_lds_dwordx4 v[122:123], off
	v_lshl_add_u64 v[122:123], s[10:11], 0, v[154:155]
	s_add_i32 m0, s14, 0x2000
	s_nop 0
	global_load_lds_dwordx4 v[122:123], off
	s_waitcnt vmcnt(6)
	s_setprio 1
	s_barrier
	v_mfma_f32_16x16x32_f16 v[54:57], v[230:233], v[146:149], v[54:57]
	v_mfma_f32_16x16x32_f16 v[50:53], v[238:241], v[146:149], v[50:53]
	v_mfma_f32_16x16x32_f16 v[38:41], v[230:233], v[192:195], v[38:41]
	v_mfma_f32_16x16x32_f16 v[34:37], v[238:241], v[192:195], v[34:37]
	v_mfma_f32_16x16x32_f16 v[20:23], v[230:233], v[204:207], v[20:23]
	v_mfma_f32_16x16x32_f16 v[16:19], v[238:241], v[204:207], v[16:19]
	v_mfma_f32_16x16x32_f16 v[4:7], v[230:233], v[212:215], v[4:7]
	v_mfma_f32_16x16x32_f16 v[0:3], v[238:241], v[212:215], v[0:3]
	v_mfma_f32_16x16x32_f16 v[54:57], v[234:237], v[150:153], v[54:57]
	v_mfma_f32_16x16x32_f16 v[50:53], v[242:245], v[150:153], v[50:53]
	v_mfma_f32_16x16x32_f16 v[38:41], v[234:237], v[200:203], v[38:41]
	v_mfma_f32_16x16x32_f16 v[34:37], v[242:245], v[200:203], v[34:37]
	v_mfma_f32_16x16x32_f16 v[20:23], v[234:237], v[208:211], v[20:23]
	v_mfma_f32_16x16x32_f16 v[16:19], v[242:245], v[208:211], v[16:19]
	v_mfma_f32_16x16x32_f16 v[4:7], v[234:237], v[216:219], v[4:7]
	v_mfma_f32_16x16x32_f16 v[0:3], v[242:245], v[216:219], v[0:3]
	s_setprio 0
	s_add_i32 s37, s37, 2
	s_add_u32 s35, s35, 0x100
	s_addc_u32 s36, s36, 0
	s_cmp_gt_u32 s37, 13
	s_mov_b64 s[10:11], s[12:13]
	s_barrier
	s_cbranch_scc0 .LBB0_958
	s_cmp_eq_u32 s34, 2
	s_movk_i32 s6, 0x2800
	v_lshl_or_b32 v122, s31, 8, v197
	s_cselect_b32 s6, 0x2000, s6
	s_mov_b32 s7, 0x23a3c000
	s_cselect_b32 s8, s7, 0x23abc000
	s_add_u32 s6, s70, s6
	v_ashrrev_i32_e32 v123, 31, v122
	s_addc_u32 s7, s71, 0
	v_lshlrev_b64 v[192:193], 1, v[122:123]
	v_lshl_add_u64 v[194:195], s[6:7], 0, v[192:193]
	v_lshl_add_u64 v[122:123], v[194:195], 0, v[156:157]
	v_lshl_add_u64 v[124:125], v[194:195], 0, v[158:159]
	v_lshl_add_u64 v[130:131], v[194:195], 0, v[160:161]
	v_lshl_add_u64 v[208:209], v[194:195], 0, v[162:163]
	global_load_dwordx4 v[200:203], v[122:123], off
	global_load_dwordx4 v[204:207], v[122:123], off offset:256
	global_load_dwordx4 v[150:153], v[124:125], off
	global_load_dwordx4 v[146:149], v[124:125], off offset:256
	global_load_dwordx4 v[142:145], v[130:131], off
	global_load_dwordx4 v[138:141], v[130:131], off offset:256
	s_nop 0
	global_load_dwordx4 v[130:133], v[208:209], off
	global_load_dwordx4 v[122:125], v[208:209], off offset:256
	v_readlane_b32 s36, v252, 26
	v_readlane_b32 s42, v252, 32
	v_readlane_b32 s43, v252, 33
	s_add_u32 s6, s42, s8
	s_addc_u32 s7, s43, 0
	v_readlane_b32 s37, v252, 27
	v_readlane_b32 s38, v252, 28
	v_readlane_b32 s39, v252, 29
	v_readlane_b32 s40, v252, 30
	v_readlane_b32 s41, v252, 31
	v_lshl_add_u64 v[192:193], s[6:7], 0, v[192:193]
	s_waitcnt vmcnt(0)
	v_cvt_f32_f16_e32 v199, v200
	v_cvt_f32_f16_sdwa v200, v200 dst_sel:DWORD dst_unused:UNUSED_PAD src0_sel:WORD_1
	v_cvt_f32_f16_e32 v210, v201
	v_lshl_add_u64 v[208:209], v[192:193], 0, v[164:165]
	v_max_f32_e32 v199, 0xc1f00000, v199
	v_mul_f32_e32 v199, 0xbfb8aa3b, v199
	v_exp_f32_e32 v199, v199
	v_max_f32_e32 v200, 0xc1f00000, v200
	v_max_f32_e32 v210, 0xc1f00000, v210
	v_mul_f32_e32 v200, 0xbfb8aa3b, v200
	v_add_f32_e32 v199, 1.0, v199
	v_rcp_f32_e32 v199, v199
	v_exp_f32_e32 v200, v200
	v_mul_f32_e32 v210, 0xbfb8aa3b, v210
	v_exp_f32_e32 v211, v210
	v_fma_mixlo_f16 v199, v134, v199, 0
	v_add_f32_e32 v134, 1.0, v200
	v_rcp_f32_e32 v210, v134
	v_add_f32_e32 v134, 1.0, v211
	v_cvt_f32_f16_sdwa v200, v201 dst_sel:DWORD dst_unused:UNUSED_PAD src0_sel:WORD_1
	v_rcp_f32_e32 v211, v134
	v_mov_b32_e32 v134, v135
	v_mov_b32_e32 v135, v136
	v_cvt_f32_f16_e32 v136, v202
	v_max_f32_e32 v200, 0xc1f00000, v200
	v_mul_f32_e32 v200, 0xbfb8aa3b, v200
	v_exp_f32_e32 v200, v200
	v_max_f32_e32 v136, 0xc1f00000, v136
	v_mul_f32_e32 v136, 0xbfb8aa3b, v136
	v_exp_f32_e32 v136, v136
	v_pk_mul_f32 v[134:135], v[134:135], v[210:211]
	s_nop 0
	v_cvt_pk_f16_f32 v135, v134, v135
	v_add_f32_e32 v134, 1.0, v200
	v_rcp_f32_e32 v200, v134
	v_add_f32_e32 v134, 1.0, v136
	v_rcp_f32_e32 v201, v134
	v_pk_mov_b32 v[136:137], v[136:137], v[126:127] op_sel:[1,0]
	v_cvt_f32_f16_sdwa v126, v202 dst_sel:DWORD dst_unused:UNUSED_PAD src0_sel:WORD_1
	v_pack_b32_f16 v134, v199, v135
	v_pk_mul_f32 v[136:137], v[136:137], v[200:201]
	v_cvt_f32_f16_sdwa v200, v203 dst_sel:DWORD dst_unused:UNUSED_PAD src0_sel:WORD_1
	v_cvt_pk_f16_f32 v199, v136, v137
	v_cvt_f32_f16_e32 v136, v203
	v_max_f32_e32 v126, 0xc1f00000, v126
	v_mul_f32_e32 v126, 0xbfb8aa3b, v126
	v_exp_f32_e32 v126, v126
	v_max_f32_e32 v136, 0xc1f00000, v136
	v_mul_f32_e32 v136, 0xbfb8aa3b, v136
	v_exp_f32_e32 v137, v136
	v_add_f32_e32 v126, 1.0, v126
	v_rcp_f32_e32 v136, v126
	v_alignbit_b32 v135, v199, v135, 16
	v_add_f32_e32 v126, 1.0, v137
	v_rcp_f32_e32 v137, v126
	v_mov_b32_e32 v126, v127
	v_mov_b32_e32 v127, v128
	v_cvt_f32_f16_e32 v128, v204
	v_pk_mul_f32 v[126:127], v[126:127], v[136:137]
	s_nop 0
	v_cvt_pk_f16_f32 v126, v126, v127
	v_max_f32_e32 v127, 0xc1f00000, v200
	v_mul_f32_e32 v127, 0xbfb8aa3b, v127
	v_exp_f32_e32 v127, v127
	v_alignbit_b32 v136, v126, v199, 16
	v_lshrrev_b32_e32 v137, 16, v126
	v_add_f32_e32 v126, 1.0, v127
	v_rcp_f32_e32 v126, v126
	v_max_f32_e32 v127, 0xc1f00000, v128
	v_mul_f32_e32 v127, 0xbfb8aa3b, v127
	v_exp_f32_e32 v127, v127
	v_fma_mixhi_f16 v137, v129, v126, 0
	v_cvt_f32_f16_sdwa v126, v204 dst_sel:DWORD dst_unused:UNUSED_PAD src0_sel:WORD_1
	v_cvt_f32_f16_e32 v128, v205
	v_add_f32_e32 v127, 1.0, v127
	v_rcp_f32_e32 v127, v127
	v_max_f32_e32 v126, 0xc1f00000, v126
	v_mul_f32_e32 v126, 0xbfb8aa3b, v126
	v_max_f32_e32 v128, 0xc1f00000, v128
	v_exp_f32_e32 v126, v126
	v_mul_f32_e32 v128, 0xbfb8aa3b, v128
	v_exp_f32_e32 v128, v128
	v_fma_mixlo_f16 v129, v118, v127, 0
	v_add_f32_e32 v118, 1.0, v126
	v_rcp_f32_e32 v126, v118
	v_add_f32_e32 v118, 1.0, v128
	v_rcp_f32_e32 v127, v118
	v_cvt_f32_f16_sdwa v128, v205 dst_sel:DWORD dst_unused:UNUSED_PAD src0_sel:WORD_1
	v_mov_b32_e32 v118, v119
	v_mov_b32_e32 v119, v120
	v_cvt_f32_f16_e32 v120, v206
	v_max_f32_e32 v128, 0xc1f00000, v128
	v_mul_f32_e32 v128, 0xbfb8aa3b, v128
	v_exp_f32_e32 v128, v128
	v_max_f32_e32 v120, 0xc1f00000, v120
	v_mul_f32_e32 v120, 0xbfb8aa3b, v120
	v_exp_f32_e32 v120, v120
	v_pk_mul_f32 v[118:119], v[118:119], v[126:127]
	v_add_f32_e32 v126, 1.0, v128
	v_rcp_f32_e32 v126, v126
	v_add_f32_e32 v120, 1.0, v120
	v_rcp_f32_e32 v127, v120
	v_pk_mov_b32 v[120:121], v[120:121], v[114:115] op_sel:[1,0]
	v_cvt_f32_f16_sdwa v114, v206 dst_sel:DWORD dst_unused:UNUSED_PAD src0_sel:WORD_1
	v_cvt_pk_f16_f32 v119, v118, v119
	v_pk_mul_f32 v[120:121], v[120:121], v[126:127]
	v_cvt_f32_f16_sdwa v127, v207 dst_sel:DWORD dst_unused:UNUSED_PAD src0_sel:WORD_1
	v_cvt_pk_f16_f32 v126, v120, v121
	v_cvt_f32_f16_e32 v120, v207
	v_max_f32_e32 v114, 0xc1f00000, v114
	v_mul_f32_e32 v114, 0xbfb8aa3b, v114
	v_exp_f32_e32 v114, v114
	v_max_f32_e32 v120, 0xc1f00000, v120
	v_mul_f32_e32 v120, 0xbfb8aa3b, v120
	v_exp_f32_e32 v121, v120
	v_add_f32_e32 v114, 1.0, v114
	v_rcp_f32_e32 v120, v114
	v_pack_b32_f16 v118, v129, v119
	v_add_f32_e32 v114, 1.0, v121
	v_rcp_f32_e32 v121, v114
	v_mov_b32_e32 v114, v115
	v_max_f32_e32 v115, 0xc1f00000, v127
	v_mul_f32_e32 v115, 0xbfb8aa3b, v115
	v_exp_f32_e32 v127, v115
	v_mov_b32_e32 v115, v116
	v_pk_mul_f32 v[114:115], v[114:115], v[120:121]
	v_cvt_f32_f16_e32 v116, v150
	v_cvt_pk_f16_f32 v114, v114, v115
	v_add_f32_e32 v115, 1.0, v127
	v_rcp_f32_e32 v115, v115
	v_alignbit_b32 v120, v114, v126, 16
	v_lshrrev_b32_e32 v121, 16, v114
	v_max_f32_e32 v114, 0xc1f00000, v116
	v_alignbit_b32 v119, v126, v119, 16
	v_fma_mixhi_f16 v121, v117, v115, 0
	v_mul_f32_e32 v114, 0xbfb8aa3b, v114
	v_cvt_f32_f16_sdwa v117, v150 dst_sel:DWORD dst_unused:UNUSED_PAD src0_sel:WORD_1
	v_exp_f32_e32 v116, v114
	global_store_dwordx4 v[208:209], v[118:121], off offset:256
	v_lshl_add_u64 v[114:115], v[192:193], 0, v[166:167]
	v_max_f32_e32 v117, 0xc1f00000, v117
	v_cvt_f32_f16_e32 v118, v151
	v_add_f32_e32 v116, 1.0, v116
	v_mul_f32_e32 v117, 0xbfb8aa3b, v117
	v_rcp_f32_e32 v116, v116
	v_max_f32_e32 v118, 0xc1f00000, v118
	v_exp_f32_e32 v117, v117
	v_mul_f32_e32 v118, 0xbfb8aa3b, v118
	v_exp_f32_e32 v118, v118
	v_fma_mixlo_f16 v119, v110, v116, 0
	v_add_f32_e32 v110, 1.0, v117
	v_rcp_f32_e32 v116, v110
	v_add_f32_e32 v110, 1.0, v118
	v_rcp_f32_e32 v117, v110
	v_cvt_f32_f16_sdwa v118, v151 dst_sel:DWORD dst_unused:UNUSED_PAD src0_sel:WORD_1
	v_mov_b32_e32 v110, v111
	v_mov_b32_e32 v111, v112
	v_cvt_f32_f16_e32 v112, v152
	v_pk_mul_f32 v[110:111], v[110:111], v[116:117]
	v_max_f32_e32 v116, 0xc1f00000, v118
	v_mul_f32_e32 v116, 0xbfb8aa3b, v116
	v_max_f32_e32 v112, 0xc1f00000, v112
	v_exp_f32_e32 v116, v116
	v_mul_f32_e32 v112, 0xbfb8aa3b, v112
	v_exp_f32_e32 v112, v112
	v_cvt_pk_f16_f32 v111, v110, v111
	v_add_f32_e32 v110, 1.0, v116
	v_rcp_f32_e32 v116, v110
	v_add_f32_e32 v110, 1.0, v112
	v_rcp_f32_e32 v117, v110
	v_pk_mov_b32 v[112:113], v[112:113], v[106:107] op_sel:[1,0]
	v_cvt_f32_f16_sdwa v106, v152 dst_sel:DWORD dst_unused:UNUSED_PAD src0_sel:WORD_1
	v_pack_b32_f16 v110, v119, v111
	v_pk_mul_f32 v[112:113], v[112:113], v[116:117]
	v_cvt_f32_f16_sdwa v117, v153 dst_sel:DWORD dst_unused:UNUSED_PAD src0_sel:WORD_1
	v_cvt_pk_f16_f32 v116, v112, v113
	v_cvt_f32_f16_e32 v112, v153
	v_max_f32_e32 v106, 0xc1f00000, v106
	v_mul_f32_e32 v106, 0xbfb8aa3b, v106
	v_exp_f32_e32 v106, v106
	v_max_f32_e32 v112, 0xc1f00000, v112
	v_mul_f32_e32 v112, 0xbfb8aa3b, v112
	v_exp_f32_e32 v113, v112
	v_add_f32_e32 v106, 1.0, v106
	v_rcp_f32_e32 v112, v106
	v_alignbit_b32 v111, v116, v111, 16
	v_add_f32_e32 v106, 1.0, v113
	v_rcp_f32_e32 v113, v106
	v_mov_b32_e32 v106, v107
	v_mov_b32_e32 v107, v108
	v_cvt_f32_f16_e32 v108, v146
	v_pk_mul_f32 v[106:107], v[106:107], v[112:113]
	global_store_dwordx4 v[208:209], v[134:137], off
	v_cvt_pk_f16_f32 v106, v106, v107
	v_max_f32_e32 v107, 0xc1f00000, v117
	v_mul_f32_e32 v107, 0xbfb8aa3b, v107
	v_exp_f32_e32 v107, v107
	v_alignbit_b32 v112, v106, v116, 16
	v_lshrrev_b32_e32 v113, 16, v106
	v_add_f32_e32 v106, 1.0, v107
	v_rcp_f32_e32 v106, v106
	v_max_f32_e32 v107, 0xc1f00000, v108
	v_mul_f32_e32 v107, 0xbfb8aa3b, v107
	v_exp_f32_e32 v107, v107
	v_fma_mixhi_f16 v113, v109, v106, 0
	v_cvt_f32_f16_sdwa v106, v146 dst_sel:DWORD dst_unused:UNUSED_PAD src0_sel:WORD_1
	v_cvt_f32_f16_e32 v108, v147
	v_add_f32_e32 v107, 1.0, v107
	v_rcp_f32_e32 v107, v107
	v_max_f32_e32 v106, 0xc1f00000, v106
	v_mul_f32_e32 v106, 0xbfb8aa3b, v106
	v_max_f32_e32 v108, 0xc1f00000, v108
	v_exp_f32_e32 v106, v106
	v_mul_f32_e32 v108, 0xbfb8aa3b, v108
	v_exp_f32_e32 v108, v108
	v_fma_mixlo_f16 v109, v102, v107, 0
	v_add_f32_e32 v102, 1.0, v106
	v_rcp_f32_e32 v106, v102
	v_add_f32_e32 v102, 1.0, v108
	v_rcp_f32_e32 v107, v102
	v_cvt_f32_f16_sdwa v108, v147 dst_sel:DWORD dst_unused:UNUSED_PAD src0_sel:WORD_1
	v_mov_b32_e32 v102, v103
	v_mov_b32_e32 v103, v104
	v_cvt_f32_f16_e32 v104, v148
	v_max_f32_e32 v108, 0xc1f00000, v108
	v_mul_f32_e32 v108, 0xbfb8aa3b, v108
	v_exp_f32_e32 v108, v108
	v_max_f32_e32 v104, 0xc1f00000, v104
	v_mul_f32_e32 v104, 0xbfb8aa3b, v104
	v_exp_f32_e32 v104, v104
	v_pk_mul_f32 v[102:103], v[102:103], v[106:107]
	v_add_f32_e32 v106, 1.0, v108
	v_rcp_f32_e32 v106, v106
	v_add_f32_e32 v104, 1.0, v104
	v_rcp_f32_e32 v107, v104
	v_pk_mov_b32 v[104:105], v[104:105], v[98:99] op_sel:[1,0]
	v_cvt_f32_f16_sdwa v98, v148 dst_sel:DWORD dst_unused:UNUSED_PAD src0_sel:WORD_1
	v_cvt_pk_f16_f32 v103, v102, v103
	v_pk_mul_f32 v[104:105], v[104:105], v[106:107]
	v_cvt_f32_f16_sdwa v107, v149 dst_sel:DWORD dst_unused:UNUSED_PAD src0_sel:WORD_1
	v_cvt_pk_f16_f32 v106, v104, v105
	v_cvt_f32_f16_e32 v104, v149
	v_max_f32_e32 v98, 0xc1f00000, v98
	v_mul_f32_e32 v98, 0xbfb8aa3b, v98
	v_exp_f32_e32 v98, v98
	v_max_f32_e32 v104, 0xc1f00000, v104
	v_mul_f32_e32 v104, 0xbfb8aa3b, v104
	v_exp_f32_e32 v105, v104
	v_add_f32_e32 v98, 1.0, v98
	v_rcp_f32_e32 v104, v98
	v_pack_b32_f16 v102, v109, v103
	v_add_f32_e32 v98, 1.0, v105
	v_rcp_f32_e32 v105, v98
	v_mov_b32_e32 v98, v99
	v_max_f32_e32 v99, 0xc1f00000, v107
	v_mul_f32_e32 v99, 0xbfb8aa3b, v99
	v_exp_f32_e32 v107, v99
	v_mov_b32_e32 v99, v100
	v_pk_mul_f32 v[98:99], v[98:99], v[104:105]
	v_cvt_f32_f16_e32 v100, v142
	v_cvt_pk_f16_f32 v98, v98, v99
	v_add_f32_e32 v99, 1.0, v107
	v_rcp_f32_e32 v99, v99
	v_alignbit_b32 v104, v98, v106, 16
	v_lshrrev_b32_e32 v105, 16, v98
	v_max_f32_e32 v98, 0xc1f00000, v100
	v_alignbit_b32 v103, v106, v103, 16
	v_fma_mixhi_f16 v105, v101, v99, 0
	v_mul_f32_e32 v98, 0xbfb8aa3b, v98
	v_cvt_f32_f16_sdwa v101, v142 dst_sel:DWORD dst_unused:UNUSED_PAD src0_sel:WORD_1
	v_exp_f32_e32 v100, v98
	global_store_dwordx4 v[114:115], v[102:105], off offset:256
	v_lshl_add_u64 v[98:99], v[192:193], 0, v[168:169]
	v_max_f32_e32 v101, 0xc1f00000, v101
	v_cvt_f32_f16_e32 v102, v143
	v_add_f32_e32 v100, 1.0, v100
	v_mul_f32_e32 v101, 0xbfb8aa3b, v101
	v_rcp_f32_e32 v100, v100
	v_max_f32_e32 v102, 0xc1f00000, v102
	v_exp_f32_e32 v101, v101
	v_mul_f32_e32 v102, 0xbfb8aa3b, v102
	v_exp_f32_e32 v102, v102
	v_fma_mixlo_f16 v103, v94, v100, 0
	v_add_f32_e32 v94, 1.0, v101
	v_rcp_f32_e32 v100, v94
	v_add_f32_e32 v94, 1.0, v102
	v_rcp_f32_e32 v101, v94
	v_cvt_f32_f16_sdwa v102, v143 dst_sel:DWORD dst_unused:UNUSED_PAD src0_sel:WORD_1
	v_mov_b32_e32 v94, v95
	v_mov_b32_e32 v95, v96
	v_cvt_f32_f16_e32 v96, v144
	v_pk_mul_f32 v[94:95], v[94:95], v[100:101]
	v_max_f32_e32 v100, 0xc1f00000, v102
	v_mul_f32_e32 v100, 0xbfb8aa3b, v100
	v_max_f32_e32 v96, 0xc1f00000, v96
	v_exp_f32_e32 v100, v100
	v_mul_f32_e32 v96, 0xbfb8aa3b, v96
	v_exp_f32_e32 v96, v96
	v_cvt_pk_f16_f32 v95, v94, v95
	v_add_f32_e32 v94, 1.0, v100
	v_rcp_f32_e32 v100, v94
	v_add_f32_e32 v94, 1.0, v96
	v_rcp_f32_e32 v101, v94
	v_pk_mov_b32 v[96:97], v[96:97], v[90:91] op_sel:[1,0]
	v_cvt_f32_f16_sdwa v90, v144 dst_sel:DWORD dst_unused:UNUSED_PAD src0_sel:WORD_1
	v_pack_b32_f16 v94, v103, v95
	v_pk_mul_f32 v[96:97], v[96:97], v[100:101]
	v_cvt_f32_f16_sdwa v101, v145 dst_sel:DWORD dst_unused:UNUSED_PAD src0_sel:WORD_1
	v_cvt_pk_f16_f32 v100, v96, v97
	v_cvt_f32_f16_e32 v96, v145
	v_max_f32_e32 v90, 0xc1f00000, v90
	v_mul_f32_e32 v90, 0xbfb8aa3b, v90
	v_exp_f32_e32 v90, v90
	v_max_f32_e32 v96, 0xc1f00000, v96
	v_mul_f32_e32 v96, 0xbfb8aa3b, v96
	v_exp_f32_e32 v97, v96
	v_add_f32_e32 v90, 1.0, v90
	v_rcp_f32_e32 v96, v90
	v_alignbit_b32 v95, v100, v95, 16
	v_add_f32_e32 v90, 1.0, v97
	v_rcp_f32_e32 v97, v90
	v_mov_b32_e32 v90, v91
	v_mov_b32_e32 v91, v92
	v_cvt_f32_f16_e32 v92, v138
	v_pk_mul_f32 v[90:91], v[90:91], v[96:97]
	global_store_dwordx4 v[114:115], v[110:113], off
	v_cvt_pk_f16_f32 v90, v90, v91
	v_max_f32_e32 v91, 0xc1f00000, v101
	v_mul_f32_e32 v91, 0xbfb8aa3b, v91
	v_exp_f32_e32 v91, v91
	v_alignbit_b32 v96, v90, v100, 16
	v_lshrrev_b32_e32 v97, 16, v90
	v_add_f32_e32 v90, 1.0, v91
	v_rcp_f32_e32 v90, v90
	v_max_f32_e32 v91, 0xc1f00000, v92
	v_mul_f32_e32 v91, 0xbfb8aa3b, v91
	v_exp_f32_e32 v91, v91
	v_fma_mixhi_f16 v97, v93, v90, 0
	v_cvt_f32_f16_sdwa v90, v138 dst_sel:DWORD dst_unused:UNUSED_PAD src0_sel:WORD_1
	v_cvt_f32_f16_e32 v92, v139
	v_add_f32_e32 v91, 1.0, v91
	v_rcp_f32_e32 v91, v91
	v_max_f32_e32 v90, 0xc1f00000, v90
	v_mul_f32_e32 v90, 0xbfb8aa3b, v90
	v_max_f32_e32 v92, 0xc1f00000, v92
	v_exp_f32_e32 v90, v90
	v_mul_f32_e32 v92, 0xbfb8aa3b, v92
	v_exp_f32_e32 v92, v92
	v_fma_mixlo_f16 v93, v86, v91, 0
	v_add_f32_e32 v86, 1.0, v90
	v_rcp_f32_e32 v90, v86
	v_add_f32_e32 v86, 1.0, v92
	v_rcp_f32_e32 v91, v86
	v_cvt_f32_f16_sdwa v92, v139 dst_sel:DWORD dst_unused:UNUSED_PAD src0_sel:WORD_1
	v_mov_b32_e32 v86, v87
	v_mov_b32_e32 v87, v88
	v_cvt_f32_f16_e32 v88, v140
	v_max_f32_e32 v92, 0xc1f00000, v92
	v_mul_f32_e32 v92, 0xbfb8aa3b, v92
	v_exp_f32_e32 v92, v92
	v_max_f32_e32 v88, 0xc1f00000, v88
	v_mul_f32_e32 v88, 0xbfb8aa3b, v88
	v_exp_f32_e32 v88, v88
	v_pk_mul_f32 v[86:87], v[86:87], v[90:91]
	v_add_f32_e32 v90, 1.0, v92
	v_rcp_f32_e32 v90, v90
	v_add_f32_e32 v88, 1.0, v88
	v_rcp_f32_e32 v91, v88
	v_pk_mov_b32 v[88:89], v[88:89], v[82:83] op_sel:[1,0]
	v_cvt_f32_f16_sdwa v82, v140 dst_sel:DWORD dst_unused:UNUSED_PAD src0_sel:WORD_1
	v_cvt_pk_f16_f32 v87, v86, v87
	v_pk_mul_f32 v[88:89], v[88:89], v[90:91]
	v_cvt_f32_f16_sdwa v91, v141 dst_sel:DWORD dst_unused:UNUSED_PAD src0_sel:WORD_1
	v_cvt_pk_f16_f32 v90, v88, v89
	v_cvt_f32_f16_e32 v88, v141
	v_max_f32_e32 v82, 0xc1f00000, v82
	v_mul_f32_e32 v82, 0xbfb8aa3b, v82
	v_exp_f32_e32 v82, v82
	v_max_f32_e32 v88, 0xc1f00000, v88
	v_mul_f32_e32 v88, 0xbfb8aa3b, v88
	v_exp_f32_e32 v89, v88
	v_add_f32_e32 v82, 1.0, v82
	v_rcp_f32_e32 v88, v82
	v_pack_b32_f16 v86, v93, v87
	v_add_f32_e32 v82, 1.0, v89
	v_rcp_f32_e32 v89, v82
	v_mov_b32_e32 v82, v83
	v_max_f32_e32 v83, 0xc1f00000, v91
	v_mul_f32_e32 v83, 0xbfb8aa3b, v83
	v_exp_f32_e32 v91, v83
	v_mov_b32_e32 v83, v84
	v_pk_mul_f32 v[82:83], v[82:83], v[88:89]
	v_cvt_f32_f16_e32 v84, v130
	v_cvt_pk_f16_f32 v82, v82, v83
	v_add_f32_e32 v83, 1.0, v91
	v_rcp_f32_e32 v83, v83
	v_alignbit_b32 v88, v82, v90, 16
	v_lshrrev_b32_e32 v89, 16, v82
	v_max_f32_e32 v82, 0xc1f00000, v84
	v_alignbit_b32 v87, v90, v87, 16
	v_fma_mixhi_f16 v89, v85, v83, 0
	v_mul_f32_e32 v82, 0xbfb8aa3b, v82
	v_cvt_f32_f16_sdwa v85, v130 dst_sel:DWORD dst_unused:UNUSED_PAD src0_sel:WORD_1
	v_exp_f32_e32 v84, v82
	global_store_dwordx4 v[98:99], v[86:89], off offset:256
	v_lshl_add_u64 v[82:83], v[192:193], 0, v[170:171]
	v_max_f32_e32 v85, 0xc1f00000, v85
	v_cvt_f32_f16_e32 v86, v131
	v_add_f32_e32 v84, 1.0, v84
	v_mul_f32_e32 v85, 0xbfb8aa3b, v85
	v_rcp_f32_e32 v84, v84
	v_max_f32_e32 v86, 0xc1f00000, v86
	v_exp_f32_e32 v85, v85
	v_mul_f32_e32 v86, 0xbfb8aa3b, v86
	v_exp_f32_e32 v86, v86
	v_fma_mixlo_f16 v87, v78, v84, 0
	v_add_f32_e32 v78, 1.0, v85
	v_rcp_f32_e32 v84, v78
	v_add_f32_e32 v78, 1.0, v86
	v_rcp_f32_e32 v85, v78
	v_cvt_f32_f16_sdwa v86, v131 dst_sel:DWORD dst_unused:UNUSED_PAD src0_sel:WORD_1
	v_mov_b32_e32 v78, v79
	v_mov_b32_e32 v79, v80
	v_cvt_f32_f16_e32 v80, v132
	v_pk_mul_f32 v[78:79], v[78:79], v[84:85]
	v_max_f32_e32 v84, 0xc1f00000, v86
	v_mul_f32_e32 v84, 0xbfb8aa3b, v84
	v_max_f32_e32 v80, 0xc1f00000, v80
	v_exp_f32_e32 v84, v84
	v_mul_f32_e32 v80, 0xbfb8aa3b, v80
	v_exp_f32_e32 v80, v80
	v_cvt_pk_f16_f32 v79, v78, v79
	v_add_f32_e32 v78, 1.0, v84
	v_rcp_f32_e32 v84, v78
	v_add_f32_e32 v78, 1.0, v80
	v_rcp_f32_e32 v85, v78
	v_pk_mov_b32 v[80:81], v[80:81], v[74:75] op_sel:[1,0]
	v_cvt_f32_f16_sdwa v74, v132 dst_sel:DWORD dst_unused:UNUSED_PAD src0_sel:WORD_1
	v_pack_b32_f16 v78, v87, v79
	v_pk_mul_f32 v[80:81], v[80:81], v[84:85]
	v_cvt_f32_f16_sdwa v85, v133 dst_sel:DWORD dst_unused:UNUSED_PAD src0_sel:WORD_1
	v_cvt_pk_f16_f32 v84, v80, v81
	v_cvt_f32_f16_e32 v80, v133
	v_max_f32_e32 v74, 0xc1f00000, v74
	v_mul_f32_e32 v74, 0xbfb8aa3b, v74
	v_exp_f32_e32 v74, v74
	v_max_f32_e32 v80, 0xc1f00000, v80
	v_mul_f32_e32 v80, 0xbfb8aa3b, v80
	v_exp_f32_e32 v81, v80
	v_add_f32_e32 v74, 1.0, v74
	v_rcp_f32_e32 v80, v74
	v_alignbit_b32 v79, v84, v79, 16
	v_add_f32_e32 v74, 1.0, v81
	v_rcp_f32_e32 v81, v74
	v_mov_b32_e32 v74, v75
	v_mov_b32_e32 v75, v76
	v_cvt_f32_f16_e32 v76, v122
	v_pk_mul_f32 v[74:75], v[74:75], v[80:81]
	global_store_dwordx4 v[98:99], v[94:97], off
	v_cvt_pk_f16_f32 v74, v74, v75
	v_max_f32_e32 v75, 0xc1f00000, v85
	v_mul_f32_e32 v75, 0xbfb8aa3b, v75
	v_exp_f32_e32 v75, v75
	v_alignbit_b32 v80, v74, v84, 16
	v_lshrrev_b32_e32 v81, 16, v74
	v_add_f32_e32 v74, 1.0, v75
	v_rcp_f32_e32 v74, v74
	v_max_f32_e32 v75, 0xc1f00000, v76
	v_mul_f32_e32 v75, 0xbfb8aa3b, v75
	v_exp_f32_e32 v75, v75
	v_fma_mixhi_f16 v81, v77, v74, 0
	v_cvt_f32_f16_sdwa v74, v122 dst_sel:DWORD dst_unused:UNUSED_PAD src0_sel:WORD_1
	v_cvt_f32_f16_e32 v76, v123
	v_add_f32_e32 v75, 1.0, v75
	v_rcp_f32_e32 v75, v75
	v_max_f32_e32 v74, 0xc1f00000, v74
	v_mul_f32_e32 v74, 0xbfb8aa3b, v74
	v_max_f32_e32 v76, 0xc1f00000, v76
	v_exp_f32_e32 v74, v74
	v_mul_f32_e32 v76, 0xbfb8aa3b, v76
	v_exp_f32_e32 v76, v76
	v_fma_mixlo_f16 v77, v70, v75, 0
	v_add_f32_e32 v70, 1.0, v74
	v_rcp_f32_e32 v74, v70
	v_add_f32_e32 v70, 1.0, v76
	v_rcp_f32_e32 v75, v70
	v_cvt_f32_f16_sdwa v76, v123 dst_sel:DWORD dst_unused:UNUSED_PAD src0_sel:WORD_1
	v_mov_b32_e32 v70, v71
	v_mov_b32_e32 v71, v72
	v_cvt_f32_f16_e32 v72, v124
	v_max_f32_e32 v76, 0xc1f00000, v76
	v_mul_f32_e32 v76, 0xbfb8aa3b, v76
	v_exp_f32_e32 v76, v76
	v_max_f32_e32 v72, 0xc1f00000, v72
	v_mul_f32_e32 v72, 0xbfb8aa3b, v72
	v_exp_f32_e32 v72, v72
	v_pk_mul_f32 v[70:71], v[70:71], v[74:75]
	v_add_f32_e32 v74, 1.0, v76
	v_rcp_f32_e32 v74, v74
	v_add_f32_e32 v72, 1.0, v72
	v_rcp_f32_e32 v75, v72
	v_pk_mov_b32 v[72:73], v[72:73], v[66:67] op_sel:[1,0]
	v_cvt_f32_f16_sdwa v66, v124 dst_sel:DWORD dst_unused:UNUSED_PAD src0_sel:WORD_1
	v_cvt_pk_f16_f32 v71, v70, v71
	v_pk_mul_f32 v[72:73], v[72:73], v[74:75]
	v_cvt_f32_f16_sdwa v75, v125 dst_sel:DWORD dst_unused:UNUSED_PAD src0_sel:WORD_1
	v_cvt_pk_f16_f32 v74, v72, v73
	v_cvt_f32_f16_e32 v72, v125
	v_max_f32_e32 v66, 0xc1f00000, v66
	v_mul_f32_e32 v66, 0xbfb8aa3b, v66
	v_exp_f32_e32 v66, v66
	v_max_f32_e32 v72, 0xc1f00000, v72
	v_mul_f32_e32 v72, 0xbfb8aa3b, v72
	v_exp_f32_e32 v73, v72
	v_add_f32_e32 v66, 1.0, v66
	v_rcp_f32_e32 v72, v66
	v_pack_b32_f16 v70, v77, v71
	v_add_f32_e32 v66, 1.0, v73
	v_rcp_f32_e32 v73, v66
	v_max_f32_e32 v66, 0xc1f00000, v75
	v_mul_f32_e32 v66, 0xbfb8aa3b, v66
	v_exp_f32_e32 v75, v66
	v_mov_b32_e32 v66, v67
	v_mov_b32_e32 v67, v68
	v_pk_mul_f32 v[66:67], v[66:67], v[72:73]
	v_add_f32_e32 v68, 1.0, v75
	v_rcp_f32_e32 v68, v68
	v_cvt_pk_f16_f32 v66, v66, v67
	v_lshrrev_b32_e32 v73, 16, v66
	v_alignbit_b32 v71, v74, v71, 16
	v_alignbit_b32 v72, v66, v74, 16
	v_fma_mixhi_f16 v73, v69, v68, 0
	global_store_dwordx4 v[82:83], v[78:81], off
	global_store_dwordx4 v[82:83], v[70:73], off offset:256
	v_lshl_add_u64 v[66:67], v[194:195], 0, v[172:173]
	v_lshl_add_u64 v[68:69], v[194:195], 0, v[174:175]
	v_lshl_add_u64 v[70:71], v[194:195], 0, v[176:177]
	v_lshl_add_u64 v[98:99], v[194:195], 0, v[178:179]
	global_load_dwordx4 v[90:93], v[66:67], off
	global_load_dwordx4 v[94:97], v[66:67], off offset:256
	global_load_dwordx4 v[86:89], v[68:69], off
	global_load_dwordx4 v[82:85], v[68:69], off offset:256
	global_load_dwordx4 v[78:81], v[70:71], off
	global_load_dwordx4 v[74:77], v[70:71], off offset:256
	s_nop 0
	global_load_dwordx4 v[70:73], v[98:99], off
	global_load_dwordx4 v[66:69], v[98:99], off offset:256
	s_waitcnt vmcnt(0)
	v_cvt_f32_f16_e32 v100, v90
	v_cvt_f32_f16_sdwa v90, v90 dst_sel:DWORD dst_unused:UNUSED_PAD src0_sel:WORD_1
	v_cvt_f32_f16_e32 v101, v91
	v_lshl_add_u64 v[98:99], v[192:193], 0, v[180:181]
	v_max_f32_e32 v100, 0xc1f00000, v100
	v_mul_f32_e32 v100, 0xbfb8aa3b, v100
	v_exp_f32_e32 v100, v100
	v_max_f32_e32 v90, 0xc1f00000, v90
	v_max_f32_e32 v101, 0xc1f00000, v101
	v_mul_f32_e32 v90, 0xbfb8aa3b, v90
	v_add_f32_e32 v100, 1.0, v100
	v_rcp_f32_e32 v100, v100
	v_exp_f32_e32 v90, v90
	v_mul_f32_e32 v101, 0xbfb8aa3b, v101
	v_exp_f32_e32 v101, v101
	v_fma_mixlo_f16 v102, v62, v100, 0
	v_add_f32_e32 v62, 1.0, v90
	v_rcp_f32_e32 v100, v62
	v_add_f32_e32 v62, 1.0, v101
	v_cvt_f32_f16_sdwa v90, v91 dst_sel:DWORD dst_unused:UNUSED_PAD src0_sel:WORD_1
	v_rcp_f32_e32 v101, v62
	v_mov_b32_e32 v62, v63
	v_mov_b32_e32 v63, v64
	v_cvt_f32_f16_e32 v64, v92
	v_max_f32_e32 v90, 0xc1f00000, v90
	v_mul_f32_e32 v90, 0xbfb8aa3b, v90
	v_exp_f32_e32 v90, v90
	v_max_f32_e32 v64, 0xc1f00000, v64
	v_mul_f32_e32 v64, 0xbfb8aa3b, v64
	v_exp_f32_e32 v64, v64
	v_pk_mul_f32 v[62:63], v[62:63], v[100:101]
	s_nop 0
	v_cvt_pk_f16_f32 v63, v62, v63
	v_add_f32_e32 v62, 1.0, v90
	v_rcp_f32_e32 v90, v62
	v_add_f32_e32 v62, 1.0, v64
	v_rcp_f32_e32 v91, v62
	v_pk_mov_b32 v[64:65], v[64:65], v[58:59] op_sel:[1,0]
	v_cvt_f32_f16_sdwa v58, v92 dst_sel:DWORD dst_unused:UNUSED_PAD src0_sel:WORD_1
	v_pack_b32_f16 v62, v102, v63
	v_pk_mul_f32 v[64:65], v[64:65], v[90:91]
	v_cvt_f32_f16_sdwa v91, v93 dst_sel:DWORD dst_unused:UNUSED_PAD src0_sel:WORD_1
	v_cvt_pk_f16_f32 v90, v64, v65
	v_cvt_f32_f16_e32 v64, v93
	v_max_f32_e32 v58, 0xc1f00000, v58
	v_mul_f32_e32 v58, 0xbfb8aa3b, v58
	v_exp_f32_e32 v58, v58
	v_max_f32_e32 v64, 0xc1f00000, v64
	v_mul_f32_e32 v64, 0xbfb8aa3b, v64
	v_exp_f32_e32 v65, v64
	v_add_f32_e32 v58, 1.0, v58
	v_rcp_f32_e32 v64, v58
	v_alignbit_b32 v63, v90, v63, 16
	v_add_f32_e32 v58, 1.0, v65
	v_rcp_f32_e32 v65, v58
	v_mov_b32_e32 v58, v59
	v_mov_b32_e32 v59, v60
	v_cvt_f32_f16_e32 v60, v94
	v_pk_mul_f32 v[58:59], v[58:59], v[64:65]
	s_nop 0
	v_cvt_pk_f16_f32 v58, v58, v59
	v_max_f32_e32 v59, 0xc1f00000, v91
	v_mul_f32_e32 v59, 0xbfb8aa3b, v59
	v_exp_f32_e32 v59, v59
	v_alignbit_b32 v64, v58, v90, 16
	v_lshrrev_b32_e32 v65, 16, v58
	v_add_f32_e32 v58, 1.0, v59
	v_rcp_f32_e32 v58, v58
	v_max_f32_e32 v59, 0xc1f00000, v60
	v_mul_f32_e32 v59, 0xbfb8aa3b, v59
	v_exp_f32_e32 v59, v59
	v_fma_mixhi_f16 v65, v61, v58, 0
	v_cvt_f32_f16_sdwa v58, v94 dst_sel:DWORD dst_unused:UNUSED_PAD src0_sel:WORD_1
	v_cvt_f32_f16_e32 v60, v95
	v_add_f32_e32 v59, 1.0, v59
	v_rcp_f32_e32 v59, v59
	v_max_f32_e32 v58, 0xc1f00000, v58
	v_mul_f32_e32 v58, 0xbfb8aa3b, v58
	v_max_f32_e32 v60, 0xc1f00000, v60
	v_exp_f32_e32 v58, v58
	v_mul_f32_e32 v60, 0xbfb8aa3b, v60
	v_exp_f32_e32 v60, v60
	v_fma_mixlo_f16 v61, v54, v59, 0
	v_add_f32_e32 v54, 1.0, v58
	v_rcp_f32_e32 v58, v54
	v_add_f32_e32 v54, 1.0, v60
	v_rcp_f32_e32 v59, v54
	v_cvt_f32_f16_sdwa v60, v95 dst_sel:DWORD dst_unused:UNUSED_PAD src0_sel:WORD_1
	v_mov_b32_e32 v54, v55
	v_mov_b32_e32 v55, v56
	v_cvt_f32_f16_e32 v56, v96
	v_max_f32_e32 v60, 0xc1f00000, v60
	v_mul_f32_e32 v60, 0xbfb8aa3b, v60
	v_exp_f32_e32 v60, v60
	v_max_f32_e32 v56, 0xc1f00000, v56
	v_mul_f32_e32 v56, 0xbfb8aa3b, v56
	v_exp_f32_e32 v56, v56
	v_pk_mul_f32 v[54:55], v[54:55], v[58:59]
	v_add_f32_e32 v58, 1.0, v60
	v_rcp_f32_e32 v58, v58
	v_add_f32_e32 v56, 1.0, v56
	v_rcp_f32_e32 v59, v56
	v_pk_mov_b32 v[56:57], v[56:57], v[50:51] op_sel:[1,0]
	v_cvt_f32_f16_sdwa v50, v96 dst_sel:DWORD dst_unused:UNUSED_PAD src0_sel:WORD_1
	v_cvt_pk_f16_f32 v55, v54, v55
	v_pk_mul_f32 v[56:57], v[56:57], v[58:59]
	v_cvt_f32_f16_sdwa v59, v97 dst_sel:DWORD dst_unused:UNUSED_PAD src0_sel:WORD_1
	v_cvt_pk_f16_f32 v58, v56, v57
	v_cvt_f32_f16_e32 v56, v97
	v_max_f32_e32 v50, 0xc1f00000, v50
	v_mul_f32_e32 v50, 0xbfb8aa3b, v50
	v_exp_f32_e32 v50, v50
	v_max_f32_e32 v56, 0xc1f00000, v56
	v_mul_f32_e32 v56, 0xbfb8aa3b, v56
	v_exp_f32_e32 v57, v56
	v_add_f32_e32 v50, 1.0, v50
	v_rcp_f32_e32 v56, v50
	v_pack_b32_f16 v54, v61, v55
	v_add_f32_e32 v50, 1.0, v57
	v_rcp_f32_e32 v57, v50
	v_mov_b32_e32 v50, v51
	v_max_f32_e32 v51, 0xc1f00000, v59
	v_mul_f32_e32 v51, 0xbfb8aa3b, v51
	v_exp_f32_e32 v59, v51
	v_mov_b32_e32 v51, v52
	v_pk_mul_f32 v[50:51], v[50:51], v[56:57]
	v_cvt_f32_f16_e32 v52, v86
	v_cvt_pk_f16_f32 v50, v50, v51
	v_add_f32_e32 v51, 1.0, v59
	v_rcp_f32_e32 v51, v51
	v_alignbit_b32 v56, v50, v58, 16
	v_lshrrev_b32_e32 v57, 16, v50
	v_max_f32_e32 v50, 0xc1f00000, v52
	v_alignbit_b32 v55, v58, v55, 16
	v_fma_mixhi_f16 v57, v53, v51, 0
	v_mul_f32_e32 v50, 0xbfb8aa3b, v50
	v_cvt_f32_f16_sdwa v53, v86 dst_sel:DWORD dst_unused:UNUSED_PAD src0_sel:WORD_1
	v_exp_f32_e32 v52, v50
	global_store_dwordx4 v[98:99], v[54:57], off offset:256
	v_lshl_add_u64 v[50:51], v[192:193], 0, v[182:183]
	v_max_f32_e32 v53, 0xc1f00000, v53
	v_cvt_f32_f16_e32 v54, v87
	v_add_f32_e32 v52, 1.0, v52
	v_mul_f32_e32 v53, 0xbfb8aa3b, v53
	v_rcp_f32_e32 v52, v52
	v_max_f32_e32 v54, 0xc1f00000, v54
	v_exp_f32_e32 v53, v53
	v_mul_f32_e32 v54, 0xbfb8aa3b, v54
	v_exp_f32_e32 v54, v54
	v_fma_mixlo_f16 v55, v46, v52, 0
	v_add_f32_e32 v46, 1.0, v53
	v_rcp_f32_e32 v52, v46
	v_add_f32_e32 v46, 1.0, v54
	v_rcp_f32_e32 v53, v46
	v_cvt_f32_f16_sdwa v54, v87 dst_sel:DWORD dst_unused:UNUSED_PAD src0_sel:WORD_1
	v_mov_b32_e32 v46, v47
	v_mov_b32_e32 v47, v48
	v_cvt_f32_f16_e32 v48, v88
	v_pk_mul_f32 v[46:47], v[46:47], v[52:53]
	v_max_f32_e32 v52, 0xc1f00000, v54
	v_mul_f32_e32 v52, 0xbfb8aa3b, v52
	v_max_f32_e32 v48, 0xc1f00000, v48
	v_exp_f32_e32 v52, v52
	v_mul_f32_e32 v48, 0xbfb8aa3b, v48
	v_exp_f32_e32 v48, v48
	v_cvt_pk_f16_f32 v47, v46, v47
	v_add_f32_e32 v46, 1.0, v52
	v_rcp_f32_e32 v52, v46
	v_add_f32_e32 v46, 1.0, v48
	v_rcp_f32_e32 v53, v46
	v_pk_mov_b32 v[48:49], v[48:49], v[42:43] op_sel:[1,0]
	v_cvt_f32_f16_sdwa v42, v88 dst_sel:DWORD dst_unused:UNUSED_PAD src0_sel:WORD_1
	v_pack_b32_f16 v46, v55, v47
	v_pk_mul_f32 v[48:49], v[48:49], v[52:53]
	v_cvt_f32_f16_sdwa v53, v89 dst_sel:DWORD dst_unused:UNUSED_PAD src0_sel:WORD_1
	v_cvt_pk_f16_f32 v52, v48, v49
	v_cvt_f32_f16_e32 v48, v89
	v_max_f32_e32 v42, 0xc1f00000, v42
	v_mul_f32_e32 v42, 0xbfb8aa3b, v42
	v_exp_f32_e32 v42, v42
	v_max_f32_e32 v48, 0xc1f00000, v48
	v_mul_f32_e32 v48, 0xbfb8aa3b, v48
	v_exp_f32_e32 v49, v48
	v_add_f32_e32 v42, 1.0, v42
	v_rcp_f32_e32 v48, v42
	v_alignbit_b32 v47, v52, v47, 16
	v_add_f32_e32 v42, 1.0, v49
	v_rcp_f32_e32 v49, v42
	v_mov_b32_e32 v42, v43
	v_mov_b32_e32 v43, v44
	v_cvt_f32_f16_e32 v44, v82
	v_pk_mul_f32 v[42:43], v[42:43], v[48:49]
	global_store_dwordx4 v[98:99], v[62:65], off
	v_cvt_pk_f16_f32 v42, v42, v43
	v_max_f32_e32 v43, 0xc1f00000, v53
	v_mul_f32_e32 v43, 0xbfb8aa3b, v43
	v_exp_f32_e32 v43, v43
	v_alignbit_b32 v48, v42, v52, 16
	v_lshrrev_b32_e32 v49, 16, v42
	v_add_f32_e32 v42, 1.0, v43
	v_rcp_f32_e32 v42, v42
	v_max_f32_e32 v43, 0xc1f00000, v44
	v_mul_f32_e32 v43, 0xbfb8aa3b, v43
	v_exp_f32_e32 v43, v43
	v_fma_mixhi_f16 v49, v45, v42, 0
	v_cvt_f32_f16_sdwa v42, v82 dst_sel:DWORD dst_unused:UNUSED_PAD src0_sel:WORD_1
	v_cvt_f32_f16_e32 v44, v83
	v_add_f32_e32 v43, 1.0, v43
	v_rcp_f32_e32 v43, v43
	v_max_f32_e32 v42, 0xc1f00000, v42
	v_mul_f32_e32 v42, 0xbfb8aa3b, v42
	v_max_f32_e32 v44, 0xc1f00000, v44
	v_exp_f32_e32 v42, v42
	v_mul_f32_e32 v44, 0xbfb8aa3b, v44
	v_exp_f32_e32 v44, v44
	v_fma_mixlo_f16 v45, v38, v43, 0
	v_add_f32_e32 v38, 1.0, v42
	v_rcp_f32_e32 v42, v38
	v_add_f32_e32 v38, 1.0, v44
	v_rcp_f32_e32 v43, v38
	v_cvt_f32_f16_sdwa v44, v83 dst_sel:DWORD dst_unused:UNUSED_PAD src0_sel:WORD_1
	v_mov_b32_e32 v38, v39
	v_mov_b32_e32 v39, v40
	v_cvt_f32_f16_e32 v40, v84
	v_max_f32_e32 v44, 0xc1f00000, v44
	v_mul_f32_e32 v44, 0xbfb8aa3b, v44
	v_exp_f32_e32 v44, v44
	v_max_f32_e32 v40, 0xc1f00000, v40
	v_mul_f32_e32 v40, 0xbfb8aa3b, v40
	v_exp_f32_e32 v40, v40
	v_pk_mul_f32 v[38:39], v[38:39], v[42:43]
	v_add_f32_e32 v42, 1.0, v44
	v_rcp_f32_e32 v42, v42
	v_add_f32_e32 v40, 1.0, v40
	v_rcp_f32_e32 v43, v40
	v_pk_mov_b32 v[40:41], v[40:41], v[34:35] op_sel:[1,0]
	v_cvt_f32_f16_sdwa v34, v84 dst_sel:DWORD dst_unused:UNUSED_PAD src0_sel:WORD_1
	v_cvt_pk_f16_f32 v39, v38, v39
	v_pk_mul_f32 v[40:41], v[40:41], v[42:43]
	v_cvt_f32_f16_sdwa v43, v85 dst_sel:DWORD dst_unused:UNUSED_PAD src0_sel:WORD_1
	v_cvt_pk_f16_f32 v42, v40, v41
	v_cvt_f32_f16_e32 v40, v85
	v_max_f32_e32 v34, 0xc1f00000, v34
	v_mul_f32_e32 v34, 0xbfb8aa3b, v34
	v_exp_f32_e32 v34, v34
	v_max_f32_e32 v40, 0xc1f00000, v40
	v_mul_f32_e32 v40, 0xbfb8aa3b, v40
	v_exp_f32_e32 v41, v40
	v_add_f32_e32 v34, 1.0, v34
	v_rcp_f32_e32 v40, v34
	v_pack_b32_f16 v38, v45, v39
	v_add_f32_e32 v34, 1.0, v41
	v_rcp_f32_e32 v41, v34
	v_mov_b32_e32 v34, v35
	v_max_f32_e32 v35, 0xc1f00000, v43
	v_mul_f32_e32 v35, 0xbfb8aa3b, v35
	v_exp_f32_e32 v43, v35
	v_mov_b32_e32 v35, v36
	v_pk_mul_f32 v[34:35], v[34:35], v[40:41]
	v_cvt_f32_f16_e32 v36, v78
	v_cvt_pk_f16_f32 v34, v34, v35
	v_add_f32_e32 v35, 1.0, v43
	v_rcp_f32_e32 v35, v35
	v_alignbit_b32 v40, v34, v42, 16
	v_lshrrev_b32_e32 v41, 16, v34
	v_max_f32_e32 v34, 0xc1f00000, v36
	v_alignbit_b32 v39, v42, v39, 16
	v_fma_mixhi_f16 v41, v37, v35, 0
	v_mul_f32_e32 v34, 0xbfb8aa3b, v34
	v_cvt_f32_f16_sdwa v37, v78 dst_sel:DWORD dst_unused:UNUSED_PAD src0_sel:WORD_1
	v_exp_f32_e32 v36, v34
	global_store_dwordx4 v[50:51], v[38:41], off offset:256
	v_lshl_add_u64 v[34:35], v[192:193], 0, v[184:185]
	v_max_f32_e32 v37, 0xc1f00000, v37
	v_cvt_f32_f16_e32 v38, v79
	v_add_f32_e32 v36, 1.0, v36
	v_mul_f32_e32 v37, 0xbfb8aa3b, v37
	v_rcp_f32_e32 v36, v36
	v_max_f32_e32 v38, 0xc1f00000, v38
	v_exp_f32_e32 v37, v37
	v_mul_f32_e32 v38, 0xbfb8aa3b, v38
	v_exp_f32_e32 v38, v38
	v_fma_mixlo_f16 v39, v28, v36, 0
	v_add_f32_e32 v28, 1.0, v37
	v_rcp_f32_e32 v36, v28
	v_add_f32_e32 v28, 1.0, v38
	v_rcp_f32_e32 v37, v28
	v_cvt_f32_f16_sdwa v38, v79 dst_sel:DWORD dst_unused:UNUSED_PAD src0_sel:WORD_1
	v_mov_b32_e32 v28, v29
	v_mov_b32_e32 v29, v30
	v_cvt_f32_f16_e32 v30, v80
	v_pk_mul_f32 v[28:29], v[28:29], v[36:37]
	v_max_f32_e32 v36, 0xc1f00000, v38
	v_mul_f32_e32 v36, 0xbfb8aa3b, v36
	v_max_f32_e32 v30, 0xc1f00000, v30
	v_exp_f32_e32 v36, v36
	v_mul_f32_e32 v30, 0xbfb8aa3b, v30
	v_exp_f32_e32 v30, v30
	v_cvt_pk_f16_f32 v29, v28, v29
	v_add_f32_e32 v28, 1.0, v36
	v_rcp_f32_e32 v36, v28
	v_add_f32_e32 v28, 1.0, v30
	v_rcp_f32_e32 v37, v28
	v_pk_mov_b32 v[30:31], v[30:31], v[24:25] op_sel:[1,0]
	v_cvt_f32_f16_sdwa v24, v80 dst_sel:DWORD dst_unused:UNUSED_PAD src0_sel:WORD_1
	v_pack_b32_f16 v28, v39, v29
	v_pk_mul_f32 v[30:31], v[30:31], v[36:37]
	v_cvt_f32_f16_sdwa v37, v81 dst_sel:DWORD dst_unused:UNUSED_PAD src0_sel:WORD_1
	v_cvt_pk_f16_f32 v36, v30, v31
	v_cvt_f32_f16_e32 v30, v81
	v_max_f32_e32 v24, 0xc1f00000, v24
	v_mul_f32_e32 v24, 0xbfb8aa3b, v24
	v_exp_f32_e32 v24, v24
	v_max_f32_e32 v30, 0xc1f00000, v30
	v_mul_f32_e32 v30, 0xbfb8aa3b, v30
	v_exp_f32_e32 v31, v30
	v_add_f32_e32 v24, 1.0, v24
	v_rcp_f32_e32 v30, v24
	v_alignbit_b32 v29, v36, v29, 16
	v_add_f32_e32 v24, 1.0, v31
	v_rcp_f32_e32 v31, v24
	v_mov_b32_e32 v24, v25
	v_mov_b32_e32 v25, v26
	v_cvt_f32_f16_e32 v26, v74
	v_pk_mul_f32 v[24:25], v[24:25], v[30:31]
	global_store_dwordx4 v[50:51], v[46:49], off
	v_cvt_pk_f16_f32 v24, v24, v25
	v_max_f32_e32 v25, 0xc1f00000, v37
	v_mul_f32_e32 v25, 0xbfb8aa3b, v25
	v_exp_f32_e32 v25, v25
	v_alignbit_b32 v30, v24, v36, 16
	v_lshrrev_b32_e32 v31, 16, v24
	v_add_f32_e32 v24, 1.0, v25
	v_rcp_f32_e32 v24, v24
	v_max_f32_e32 v25, 0xc1f00000, v26
	v_mul_f32_e32 v25, 0xbfb8aa3b, v25
	v_exp_f32_e32 v25, v25
	v_fma_mixhi_f16 v31, v27, v24, 0
	v_cvt_f32_f16_sdwa v24, v74 dst_sel:DWORD dst_unused:UNUSED_PAD src0_sel:WORD_1
	v_cvt_f32_f16_e32 v26, v75
	v_add_f32_e32 v25, 1.0, v25
	v_rcp_f32_e32 v25, v25
	v_max_f32_e32 v24, 0xc1f00000, v24
	v_mul_f32_e32 v24, 0xbfb8aa3b, v24
	v_max_f32_e32 v26, 0xc1f00000, v26
	v_exp_f32_e32 v24, v24
	v_mul_f32_e32 v26, 0xbfb8aa3b, v26
	v_exp_f32_e32 v26, v26
	v_fma_mixlo_f16 v27, v20, v25, 0
	v_add_f32_e32 v20, 1.0, v24
	v_rcp_f32_e32 v24, v20
	v_add_f32_e32 v20, 1.0, v26
	v_rcp_f32_e32 v25, v20
	v_cvt_f32_f16_sdwa v26, v75 dst_sel:DWORD dst_unused:UNUSED_PAD src0_sel:WORD_1
	v_mov_b32_e32 v20, v21
	v_mov_b32_e32 v21, v22
	v_cvt_f32_f16_e32 v22, v76
	v_max_f32_e32 v26, 0xc1f00000, v26
	v_mul_f32_e32 v26, 0xbfb8aa3b, v26
	v_exp_f32_e32 v26, v26
	v_max_f32_e32 v22, 0xc1f00000, v22
	v_mul_f32_e32 v22, 0xbfb8aa3b, v22
	v_exp_f32_e32 v22, v22
	v_pk_mul_f32 v[20:21], v[20:21], v[24:25]
	v_add_f32_e32 v24, 1.0, v26
	v_rcp_f32_e32 v24, v24
	v_add_f32_e32 v22, 1.0, v22
	v_rcp_f32_e32 v25, v22
	v_pk_mov_b32 v[22:23], v[22:23], v[16:17] op_sel:[1,0]
	v_cvt_f32_f16_sdwa v16, v76 dst_sel:DWORD dst_unused:UNUSED_PAD src0_sel:WORD_1
	v_cvt_pk_f16_f32 v21, v20, v21
	v_pk_mul_f32 v[22:23], v[22:23], v[24:25]
	v_cvt_f32_f16_sdwa v25, v77 dst_sel:DWORD dst_unused:UNUSED_PAD src0_sel:WORD_1
	v_cvt_pk_f16_f32 v24, v22, v23
	v_cvt_f32_f16_e32 v22, v77
	v_max_f32_e32 v16, 0xc1f00000, v16
	v_mul_f32_e32 v16, 0xbfb8aa3b, v16
	v_exp_f32_e32 v16, v16
	v_max_f32_e32 v22, 0xc1f00000, v22
	v_mul_f32_e32 v22, 0xbfb8aa3b, v22
	v_exp_f32_e32 v23, v22
	v_add_f32_e32 v16, 1.0, v16
	v_rcp_f32_e32 v22, v16
	v_pack_b32_f16 v20, v27, v21
	v_add_f32_e32 v16, 1.0, v23
	v_rcp_f32_e32 v23, v16
	v_mov_b32_e32 v16, v17
	v_max_f32_e32 v17, 0xc1f00000, v25
	v_mul_f32_e32 v17, 0xbfb8aa3b, v17
	v_exp_f32_e32 v25, v17
	v_mov_b32_e32 v17, v18
	v_pk_mul_f32 v[16:17], v[16:17], v[22:23]
	v_cvt_f32_f16_e32 v18, v70
	v_cvt_pk_f16_f32 v16, v16, v17
	v_add_f32_e32 v17, 1.0, v25
	v_rcp_f32_e32 v17, v17
	v_alignbit_b32 v22, v16, v24, 16
	v_lshrrev_b32_e32 v23, 16, v16
	v_max_f32_e32 v16, 0xc1f00000, v18
	v_alignbit_b32 v21, v24, v21, 16
	v_fma_mixhi_f16 v23, v19, v17, 0
	v_mul_f32_e32 v16, 0xbfb8aa3b, v16
	v_cvt_f32_f16_sdwa v19, v70 dst_sel:DWORD dst_unused:UNUSED_PAD src0_sel:WORD_1
	v_exp_f32_e32 v18, v16
	global_store_dwordx4 v[34:35], v[20:23], off offset:256
	v_lshl_add_u64 v[16:17], v[192:193], 0, v[186:187]
	v_max_f32_e32 v19, 0xc1f00000, v19
	v_cvt_f32_f16_e32 v20, v71
	v_add_f32_e32 v18, 1.0, v18
	v_mul_f32_e32 v19, 0xbfb8aa3b, v19
	v_rcp_f32_e32 v18, v18
	v_max_f32_e32 v20, 0xc1f00000, v20
	v_exp_f32_e32 v19, v19
	v_mul_f32_e32 v20, 0xbfb8aa3b, v20
	v_exp_f32_e32 v20, v20
	v_fma_mixlo_f16 v21, v12, v18, 0
	v_add_f32_e32 v12, 1.0, v19
	v_rcp_f32_e32 v18, v12
	v_add_f32_e32 v12, 1.0, v20
	v_rcp_f32_e32 v19, v12
	v_cvt_f32_f16_sdwa v20, v71 dst_sel:DWORD dst_unused:UNUSED_PAD src0_sel:WORD_1
	v_mov_b32_e32 v12, v13
	v_mov_b32_e32 v13, v14
	v_cvt_f32_f16_e32 v14, v72
	v_pk_mul_f32 v[12:13], v[12:13], v[18:19]
	v_max_f32_e32 v18, 0xc1f00000, v20
	v_mul_f32_e32 v18, 0xbfb8aa3b, v18
	v_max_f32_e32 v14, 0xc1f00000, v14
	v_exp_f32_e32 v18, v18
	v_mul_f32_e32 v14, 0xbfb8aa3b, v14
	v_exp_f32_e32 v14, v14
	v_cvt_pk_f16_f32 v13, v12, v13
	v_add_f32_e32 v12, 1.0, v18
	v_rcp_f32_e32 v18, v12
	v_add_f32_e32 v12, 1.0, v14
	v_rcp_f32_e32 v19, v12
	v_pk_mov_b32 v[14:15], v[14:15], v[8:9] op_sel:[1,0]
	v_cvt_f32_f16_sdwa v8, v72 dst_sel:DWORD dst_unused:UNUSED_PAD src0_sel:WORD_1
	v_pack_b32_f16 v12, v21, v13
	v_pk_mul_f32 v[14:15], v[14:15], v[18:19]
	v_cvt_f32_f16_sdwa v19, v73 dst_sel:DWORD dst_unused:UNUSED_PAD src0_sel:WORD_1
	v_cvt_pk_f16_f32 v18, v14, v15
	v_cvt_f32_f16_e32 v14, v73
	v_max_f32_e32 v8, 0xc1f00000, v8
	v_mul_f32_e32 v8, 0xbfb8aa3b, v8
	v_exp_f32_e32 v8, v8
	v_max_f32_e32 v14, 0xc1f00000, v14
	v_mul_f32_e32 v14, 0xbfb8aa3b, v14
	v_exp_f32_e32 v15, v14
	v_add_f32_e32 v8, 1.0, v8
	v_rcp_f32_e32 v14, v8
	v_alignbit_b32 v13, v18, v13, 16
	v_add_f32_e32 v8, 1.0, v15
	v_rcp_f32_e32 v15, v8
	v_mov_b32_e32 v8, v9
	v_mov_b32_e32 v9, v10
	v_cvt_f32_f16_e32 v10, v66
	v_pk_mul_f32 v[8:9], v[8:9], v[14:15]
	global_store_dwordx4 v[34:35], v[28:31], off
	v_cvt_pk_f16_f32 v8, v8, v9
	v_max_f32_e32 v9, 0xc1f00000, v19
	v_mul_f32_e32 v9, 0xbfb8aa3b, v9
	v_exp_f32_e32 v9, v9
	v_alignbit_b32 v14, v8, v18, 16
	v_lshrrev_b32_e32 v15, 16, v8
	v_add_f32_e32 v8, 1.0, v9
	v_rcp_f32_e32 v8, v8
	v_max_f32_e32 v9, 0xc1f00000, v10
	v_mul_f32_e32 v9, 0xbfb8aa3b, v9
	v_exp_f32_e32 v9, v9
	v_fma_mixhi_f16 v15, v11, v8, 0
	v_cvt_f32_f16_sdwa v8, v66 dst_sel:DWORD dst_unused:UNUSED_PAD src0_sel:WORD_1
	v_cvt_f32_f16_e32 v10, v67
	v_add_f32_e32 v9, 1.0, v9
	v_rcp_f32_e32 v9, v9
	v_max_f32_e32 v8, 0xc1f00000, v8
	v_mul_f32_e32 v8, 0xbfb8aa3b, v8
	v_max_f32_e32 v10, 0xc1f00000, v10
	v_exp_f32_e32 v8, v8
	v_mul_f32_e32 v10, 0xbfb8aa3b, v10
	v_exp_f32_e32 v10, v10
	v_fma_mixlo_f16 v11, v4, v9, 0
	v_add_f32_e32 v4, 1.0, v8
	v_rcp_f32_e32 v8, v4
	v_add_f32_e32 v4, 1.0, v10
	v_rcp_f32_e32 v9, v4
	v_cvt_f32_f16_sdwa v10, v67 dst_sel:DWORD dst_unused:UNUSED_PAD src0_sel:WORD_1
	v_mov_b32_e32 v4, v5
	v_mov_b32_e32 v5, v6
	v_cvt_f32_f16_e32 v6, v68
	v_max_f32_e32 v10, 0xc1f00000, v10
	v_mul_f32_e32 v10, 0xbfb8aa3b, v10
	v_exp_f32_e32 v10, v10
	v_max_f32_e32 v6, 0xc1f00000, v6
	v_mul_f32_e32 v6, 0xbfb8aa3b, v6
	v_exp_f32_e32 v6, v6
	v_pk_mul_f32 v[4:5], v[4:5], v[8:9]
	v_add_f32_e32 v8, 1.0, v10
	v_rcp_f32_e32 v8, v8
	v_add_f32_e32 v6, 1.0, v6
	v_rcp_f32_e32 v9, v6
	v_pk_mov_b32 v[6:7], v[6:7], v[0:1] op_sel:[1,0]
	v_cvt_f32_f16_sdwa v0, v68 dst_sel:DWORD dst_unused:UNUSED_PAD src0_sel:WORD_1
	v_cvt_pk_f16_f32 v5, v4, v5
	v_pk_mul_f32 v[6:7], v[6:7], v[8:9]
	v_cvt_f32_f16_sdwa v9, v69 dst_sel:DWORD dst_unused:UNUSED_PAD src0_sel:WORD_1
	v_cvt_pk_f16_f32 v8, v6, v7
	v_cvt_f32_f16_e32 v6, v69
	v_max_f32_e32 v0, 0xc1f00000, v0
	v_mul_f32_e32 v0, 0xbfb8aa3b, v0
	v_exp_f32_e32 v0, v0
	v_max_f32_e32 v6, 0xc1f00000, v6
	v_mul_f32_e32 v6, 0xbfb8aa3b, v6
	v_exp_f32_e32 v7, v6
	v_add_f32_e32 v0, 1.0, v0
	v_rcp_f32_e32 v6, v0
	v_pack_b32_f16 v4, v11, v5
	v_add_f32_e32 v0, 1.0, v7
	v_rcp_f32_e32 v7, v0
	v_max_f32_e32 v0, 0xc1f00000, v9
	v_mul_f32_e32 v0, 0xbfb8aa3b, v0
	v_exp_f32_e32 v9, v0
	v_mov_b32_e32 v0, v1
	v_mov_b32_e32 v1, v2
	v_pk_mul_f32 v[0:1], v[0:1], v[6:7]
	v_add_f32_e32 v2, 1.0, v9
	v_rcp_f32_e32 v2, v2
	v_cvt_pk_f16_f32 v0, v0, v1
	v_lshrrev_b32_e32 v7, 16, v0
	v_alignbit_b32 v5, v8, v5, 16
	v_alignbit_b32 v6, v0, v8, 16
	v_fma_mixhi_f16 v7, v3, v2, 0
	global_store_dwordx4 v[16:17], v[12:15], off
	global_store_dwordx4 v[16:17], v[4:7], off offset:256
	s_and_b64 vcc, exec, s[4:5]
	s_mov_b32 s31, s30
	s_mov_b32 s34, s29
	s_mov_b64 s[12:13], s[0:1]
	s_mov_b64 s[10:11], s[2:3]
	s_cbranch_vccz .LBB0_955
	s_waitcnt vmcnt(0)
	s_cmpk_gt_u32 s19, 0xff
	s_cbranch_scc1 .LBB0_962
	s_barrier

.LBB0_1117:
	s_add_i32 s41, s22, 2
	s_add_u32 s20, s14, 0x100
	s_addc_u32 s21, s15, 0
	s_add_i32 s42, 0, 0x10000
	s_waitcnt vmcnt(0)
	v_add_u32_e32 v102, s42, v230
	ds_read_b128 v[78:81], v102
	ds_read_b128 v[94:97], v102 offset:2048
	ds_read_b128 v[86:89], v102 offset:1024
	ds_read_b128 v[102:105], v102 offset:3072
	s_cmp_eq_u32 s38, s22
	s_cselect_b32 s22, s18, s39
	s_cselect_b32 s25, s17, s21
	s_cselect_b32 s24, s16, s20
	s_cselect_b32 s23, s19, s40
	v_lshl_add_u64 v[178:179], s[14:15], 0, v[200:201]
	s_add_i32 m0, s28, 0xc000
	ds_read_b128 v[122:125], v232
	ds_read_b128 v[130:133], v232 offset:2048
	ds_read_b128 v[154:157], v232 offset:4096
	ds_read_b128 v[170:173], v232 offset:6144
	ds_read_b128 v[126:129], v232 offset:1024
	ds_read_b128 v[134:137], v232 offset:3072
	ds_read_b128 v[158:161], v232 offset:5120
	ds_read_b128 v[174:177], v232 offset:7168
	global_load_lds_dwordx4 v[178:179], off
	v_lshl_add_u64 v[178:179], s[14:15], 0, v[202:203]
	s_add_i32 m0, s28, 0xe000
	s_nop 0
	global_load_lds_dwordx4 v[178:179], off
	s_waitcnt lgkmcnt(8)
	s_setprio 1
	s_barrier
	s_waitcnt lgkmcnt(7)
	v_mfma_f32_16x16x32_f16 v[166:169], v[78:81], v[122:125], v[166:169]
	v_mfma_f32_16x16x32_f16 v[162:165], v[94:97], v[122:125], v[162:165]
	s_waitcnt lgkmcnt(6)
	v_mfma_f32_16x16x32_f16 v[150:153], v[78:81], v[130:133], v[150:153]
	v_mfma_f32_16x16x32_f16 v[142:145], v[94:97], v[130:133], v[142:145]
	s_waitcnt lgkmcnt(5)
	v_mfma_f32_16x16x32_f16 v[110:113], v[78:81], v[154:157], v[110:113]
	v_mfma_f32_16x16x32_f16 v[106:109], v[94:97], v[154:157], v[106:109]
	s_waitcnt lgkmcnt(4)
	v_mfma_f32_16x16x32_f16 v[82:85], v[78:81], v[170:173], v[82:85]
	v_mfma_f32_16x16x32_f16 v[74:77], v[94:97], v[170:173], v[74:77]
	s_waitcnt lgkmcnt(3)
	v_mfma_f32_16x16x32_f16 v[166:169], v[86:89], v[126:129], v[166:169]
	v_mfma_f32_16x16x32_f16 v[162:165], v[102:105], v[126:129], v[162:165]
	s_waitcnt lgkmcnt(2)
	v_mfma_f32_16x16x32_f16 v[150:153], v[86:89], v[134:137], v[150:153]
	v_mfma_f32_16x16x32_f16 v[142:145], v[102:105], v[134:137], v[142:145]
	s_waitcnt lgkmcnt(1)
	v_mfma_f32_16x16x32_f16 v[110:113], v[86:89], v[158:161], v[110:113]
	v_mfma_f32_16x16x32_f16 v[106:109], v[102:105], v[158:161], v[106:109]
	s_waitcnt lgkmcnt(0)
	v_mfma_f32_16x16x32_f16 v[82:85], v[86:89], v[174:177], v[82:85]
	v_mfma_f32_16x16x32_f16 v[74:77], v[102:105], v[174:177], v[74:77]
	s_setprio 0
	s_barrier
	s_add_i32 s43, 0, 0x14000
	s_add_i32 s14, s42, s13
	v_add_u32_e32 v190, s43, v230
	v_lshl_add_u64 v[204:205], s[22:23], 0, v[32:33]
	s_mov_b32 m0, s14
	ds_read_b128 v[178:181], v190
	ds_read_b128 v[186:189], v190 offset:2048
	ds_read_b128 v[182:185], v190 offset:1024
	ds_read_b128 v[190:193], v190 offset:3072
	global_load_lds_dwordx4 v[204:205], off
	v_lshl_add_u64 v[206:207], s[22:23], 0, v[198:199]
	s_add_i32 m0, s14, 0x2000
	s_nop 0
	global_load_lds_dwordx4 v[206:207], off
	s_setprio 1
	s_barrier
	s_waitcnt lgkmcnt(3)
	v_mfma_f32_16x16x32_f16 v[146:149], v[178:181], v[122:125], v[146:149]
	v_mfma_f32_16x16x32_f16 v[118:121], v[178:181], v[130:133], v[118:121]
	s_waitcnt lgkmcnt(2)
	v_mfma_f32_16x16x32_f16 v[114:117], v[186:189], v[130:133], v[114:117]
	v_mfma_f32_16x16x32_f16 v[98:101], v[178:181], v[154:157], v[98:101]
	v_mfma_f32_16x16x32_f16 v[90:93], v[186:189], v[154:157], v[90:93]
	v_mfma_f32_16x16x32_f16 v[70:73], v[178:181], v[170:173], v[70:73]
	s_waitcnt lgkmcnt(1)
	v_mfma_f32_16x16x32_f16 v[66:69], v[186:189], v[170:173], v[66:69]
	v_mfma_f32_16x16x32_f16 v[146:149], v[182:185], v[126:129], v[146:149]
	v_mfma_f32_16x16x32_f16 v[122:125], v[186:189], v[122:125], v[138:141]
	v_mfma_f32_16x16x32_f16 v[118:121], v[182:185], v[134:137], v[118:121]
	s_waitcnt lgkmcnt(0)
	v_mfma_f32_16x16x32_f16 v[114:117], v[190:193], v[134:137], v[114:117]
	v_mfma_f32_16x16x32_f16 v[98:101], v[182:185], v[158:161], v[98:101]
	v_mfma_f32_16x16x32_f16 v[90:93], v[190:193], v[158:161], v[90:93]
	v_mfma_f32_16x16x32_f16 v[70:73], v[182:185], v[174:177], v[70:73]
	v_mfma_f32_16x16x32_f16 v[66:69], v[190:193], v[174:177], v[66:69]
	v_mfma_f32_16x16x32_f16 v[122:125], v[190:193], v[126:129], v[122:125]
	s_setprio 0
	s_mov_b32 m0, s28
	v_lshl_add_u64 v[208:209], s[24:25], 0, v[32:33]
	s_barrier
	ds_read_b128 v[126:129], v232 offset:16384
	ds_read_b128 v[134:137], v232 offset:18432
	ds_read_b128 v[154:157], v232 offset:20480
	ds_read_b128 v[170:173], v232 offset:22528
	ds_read_b128 v[130:133], v232 offset:17408
	ds_read_b128 v[138:141], v232 offset:19456
	ds_read_b128 v[158:161], v232 offset:21504
	ds_read_b128 v[174:177], v232 offset:23552
	global_load_lds_dwordx4 v[208:209], off
	v_lshl_add_u64 v[210:211], s[24:25], 0, v[198:199]
	s_mov_b32 m0, s29
	s_nop 0
	global_load_lds_dwordx4 v[210:211], off
	s_setprio 1
	s_barrier
	s_waitcnt lgkmcnt(7)
	v_mfma_f32_16x16x32_f16 v[62:65], v[78:81], v[126:129], v[62:65]
	v_mfma_f32_16x16x32_f16 v[58:61], v[94:97], v[126:129], v[58:61]
	s_waitcnt lgkmcnt(6)
	v_mfma_f32_16x16x32_f16 v[46:49], v[78:81], v[134:137], v[46:49]
	v_mfma_f32_16x16x32_f16 v[42:45], v[94:97], v[134:137], v[42:45]
	s_waitcnt lgkmcnt(5)
	v_mfma_f32_16x16x32_f16 v[28:31], v[78:81], v[154:157], v[28:31]
	v_mfma_f32_16x16x32_f16 v[24:27], v[94:97], v[154:157], v[24:27]
	s_waitcnt lgkmcnt(4)
	v_mfma_f32_16x16x32_f16 v[12:15], v[78:81], v[170:173], v[12:15]
	v_mfma_f32_16x16x32_f16 v[8:11], v[94:97], v[170:173], v[8:11]
	s_waitcnt lgkmcnt(3)
	v_mfma_f32_16x16x32_f16 v[62:65], v[86:89], v[130:133], v[62:65]
	v_mfma_f32_16x16x32_f16 v[58:61], v[102:105], v[130:133], v[58:61]
	s_waitcnt lgkmcnt(2)
	v_mfma_f32_16x16x32_f16 v[46:49], v[86:89], v[138:141], v[46:49]
	v_mfma_f32_16x16x32_f16 v[42:45], v[102:105], v[138:141], v[42:45]
	s_waitcnt lgkmcnt(1)
	v_mfma_f32_16x16x32_f16 v[28:31], v[86:89], v[158:161], v[28:31]
	v_mfma_f32_16x16x32_f16 v[24:27], v[102:105], v[158:161], v[24:27]
	s_waitcnt lgkmcnt(0)
	v_mfma_f32_16x16x32_f16 v[12:15], v[86:89], v[174:177], v[12:15]
	v_mfma_f32_16x16x32_f16 v[8:11], v[102:105], v[174:177], v[8:11]
	s_setprio 0
	s_barrier
	s_add_u32 s14, s22, 0x40000
	s_addc_u32 s15, s23, 0
	s_add_i32 s42, s43, s13
	v_lshl_add_u64 v[78:79], s[14:15], 0, v[32:33]
	s_mov_b32 m0, s42
	s_nop 0
	global_load_lds_dwordx4 v[78:79], off
	v_lshl_add_u64 v[78:79], s[14:15], 0, v[198:199]
	s_add_i32 m0, s42, 0x2000
	s_nop 0
	global_load_lds_dwordx4 v[78:79], off
	s_waitcnt vmcnt(6)
	s_setprio 1
	s_barrier
	v_mfma_f32_16x16x32_f16 v[54:57], v[178:181], v[126:129], v[54:57]
	v_mfma_f32_16x16x32_f16 v[50:53], v[186:189], v[126:129], v[50:53]
	v_mfma_f32_16x16x32_f16 v[38:41], v[178:181], v[134:137], v[38:41]
	v_mfma_f32_16x16x32_f16 v[34:37], v[186:189], v[134:137], v[34:37]
	v_mfma_f32_16x16x32_f16 v[20:23], v[178:181], v[154:157], v[20:23]
	v_mfma_f32_16x16x32_f16 v[16:19], v[186:189], v[154:157], v[16:19]
	v_mfma_f32_16x16x32_f16 v[4:7], v[178:181], v[170:173], v[4:7]
	v_mfma_f32_16x16x32_f16 v[0:3], v[186:189], v[170:173], v[0:3]
	v_mfma_f32_16x16x32_f16 v[54:57], v[182:185], v[130:133], v[54:57]
	v_mfma_f32_16x16x32_f16 v[50:53], v[190:193], v[130:133], v[50:53]
	v_mfma_f32_16x16x32_f16 v[38:41], v[182:185], v[138:141], v[38:41]
	v_mfma_f32_16x16x32_f16 v[34:37], v[190:193], v[138:141], v[34:37]
	v_mfma_f32_16x16x32_f16 v[20:23], v[182:185], v[158:161], v[20:23]
	v_mfma_f32_16x16x32_f16 v[16:19], v[190:193], v[158:161], v[16:19]
	v_mfma_f32_16x16x32_f16 v[4:7], v[182:185], v[174:177], v[4:7]
	v_mfma_f32_16x16x32_f16 v[0:3], v[190:193], v[174:177], v[0:3]
	s_setprio 0
	s_add_i32 s42, 0, 0x18000
	v_add_u32_e32 v102, s42, v230
	s_barrier
	ds_read_b128 v[78:81], v102
	ds_read_b128 v[86:89], v102 offset:1024
	ds_read_b128 v[94:97], v102 offset:2048
	ds_read_b128 v[102:105], v102 offset:3072
	s_add_u32 s14, s24, 0x40000
	s_addc_u32 s15, s25, 0
	s_mov_b32 m0, s30
	v_lshl_add_u64 v[138:139], s[14:15], 0, v[32:33]
	ds_read_b128 v[126:129], v232 offset:32768
	ds_read_b128 v[130:133], v232 offset:33792
	ds_read_b128 v[134:137], v232 offset:34816
	ds_read_b128 v[154:157], v232 offset:35840
	ds_read_b128 v[158:161], v232 offset:36864
	ds_read_b128 v[174:177], v232 offset:38912
	ds_read_b128 v[170:173], v232 offset:37888
	ds_read_b128 v[178:181], v232 offset:39936
	global_load_lds_dwordx4 v[138:139], off
	v_lshl_add_u64 v[138:139], s[14:15], 0, v[198:199]
	s_mov_b32 m0, s31
	s_nop 0
	global_load_lds_dwordx4 v[138:139], off
	s_waitcnt lgkmcnt(8)
	s_setprio 1
	s_barrier
	s_waitcnt lgkmcnt(6)
	v_mfma_f32_16x16x32_f16 v[138:141], v[78:81], v[126:129], v[166:169]
	v_mfma_f32_16x16x32_f16 v[166:169], v[86:89], v[130:133], v[138:141]
	v_mfma_f32_16x16x32_f16 v[138:141], v[94:97], v[126:129], v[162:165]
	v_mfma_f32_16x16x32_f16 v[162:165], v[102:105], v[130:133], v[138:141]
	s_waitcnt lgkmcnt(4)
	v_mfma_f32_16x16x32_f16 v[138:141], v[78:81], v[134:137], v[150:153]
	v_mfma_f32_16x16x32_f16 v[150:153], v[86:89], v[154:157], v[138:141]
	s_waitcnt lgkmcnt(3)
	v_mfma_f32_16x16x32_f16 v[138:141], v[94:97], v[134:137], v[142:145]
	v_mfma_f32_16x16x32_f16 v[110:113], v[78:81], v[158:161], v[110:113]
	s_waitcnt lgkmcnt(2)
	v_mfma_f32_16x16x32_f16 v[106:109], v[94:97], v[158:161], v[106:109]
	v_mfma_f32_16x16x32_f16 v[82:85], v[78:81], v[174:177], v[82:85]
	v_mfma_f32_16x16x32_f16 v[74:77], v[94:97], v[174:177], v[74:77]
	v_mfma_f32_16x16x32_f16 v[142:145], v[102:105], v[154:157], v[138:141]
	s_waitcnt lgkmcnt(1)
	v_mfma_f32_16x16x32_f16 v[110:113], v[86:89], v[170:173], v[110:113]
	v_mfma_f32_16x16x32_f16 v[106:109], v[102:105], v[170:173], v[106:109]
	s_waitcnt lgkmcnt(0)
	v_mfma_f32_16x16x32_f16 v[82:85], v[86:89], v[178:181], v[82:85]
	v_mfma_f32_16x16x32_f16 v[74:77], v[102:105], v[178:181], v[74:77]
	s_setprio 0
	s_barrier
	s_add_i32 s24, 0, 0x1c000
	v_add_u32_e32 v138, s24, v230
	s_add_i32 s14, s42, s13
	ds_read_b128 v[182:185], v138
	ds_read_b128 v[190:193], v138 offset:2048
	ds_read_b128 v[186:189], v138 offset:1024
	ds_read_b128 v[194:197], v138 offset:3072
	v_lshl_add_u64 v[138:139], v[204:205], 0, s[84:85]
	s_mov_b32 m0, s14
	s_nop 0
	global_load_lds_dwordx4 v[138:139], off
	v_lshl_add_u64 v[138:139], v[206:207], 0, s[84:85]
	s_add_i32 m0, s14, 0x2000
	s_nop 0
	global_load_lds_dwordx4 v[138:139], off
	s_setprio 1
	s_barrier
	s_waitcnt lgkmcnt(2)
	v_mfma_f32_16x16x32_f16 v[138:141], v[182:185], v[126:129], v[146:149]
	v_mfma_f32_16x16x32_f16 v[122:125], v[190:193], v[126:129], v[122:125]
	v_mfma_f32_16x16x32_f16 v[118:121], v[182:185], v[134:137], v[118:121]
	v_mfma_f32_16x16x32_f16 v[114:117], v[190:193], v[134:137], v[114:117]
	v_mfma_f32_16x16x32_f16 v[98:101], v[182:185], v[158:161], v[98:101]
	v_mfma_f32_16x16x32_f16 v[90:93], v[190:193], v[158:161], v[90:93]
	v_mfma_f32_16x16x32_f16 v[70:73], v[182:185], v[174:177], v[70:73]
	v_mfma_f32_16x16x32_f16 v[66:69], v[190:193], v[174:177], v[66:69]
	s_waitcnt lgkmcnt(0)
	v_mfma_f32_16x16x32_f16 v[146:149], v[186:189], v[130:133], v[138:141]
	v_mfma_f32_16x16x32_f16 v[138:141], v[194:197], v[130:133], v[122:125]
	v_mfma_f32_16x16x32_f16 v[118:121], v[186:189], v[154:157], v[118:121]
	v_mfma_f32_16x16x32_f16 v[114:117], v[194:197], v[154:157], v[114:117]
	v_mfma_f32_16x16x32_f16 v[98:101], v[186:189], v[170:173], v[98:101]
	v_mfma_f32_16x16x32_f16 v[90:93], v[194:197], v[170:173], v[90:93]
	v_mfma_f32_16x16x32_f16 v[70:73], v[186:189], v[178:181], v[70:73]
	v_mfma_f32_16x16x32_f16 v[66:69], v[194:197], v[178:181], v[66:69]
	s_setprio 0
	s_mov_b32 m0, s34
	v_lshl_add_u64 v[178:179], v[208:209], 0, s[84:85]
	s_barrier
	ds_read_b128 v[122:125], v232 offset:49152
	ds_read_b128 v[130:133], v232 offset:51200
	ds_read_b128 v[154:157], v232 offset:53248
	ds_read_b128 v[170:173], v232 offset:55296
	ds_read_b128 v[126:129], v232 offset:50176
	ds_read_b128 v[134:137], v232 offset:52224
	ds_read_b128 v[158:161], v232 offset:54272
	ds_read_b128 v[174:177], v232 offset:56320
	global_load_lds_dwordx4 v[178:179], off
	v_lshl_add_u64 v[178:179], v[210:211], 0, s[84:85]
	s_mov_b32 m0, s35
	s_nop 0
	global_load_lds_dwordx4 v[178:179], off
	s_setprio 1
	s_barrier
	s_waitcnt lgkmcnt(7)
	v_mfma_f32_16x16x32_f16 v[62:65], v[78:81], v[122:125], v[62:65]
	v_mfma_f32_16x16x32_f16 v[58:61], v[94:97], v[122:125], v[58:61]
	s_waitcnt lgkmcnt(6)
	v_mfma_f32_16x16x32_f16 v[46:49], v[78:81], v[130:133], v[46:49]
	v_mfma_f32_16x16x32_f16 v[42:45], v[94:97], v[130:133], v[42:45]
	s_waitcnt lgkmcnt(5)
	v_mfma_f32_16x16x32_f16 v[28:31], v[78:81], v[154:157], v[28:31]
	v_mfma_f32_16x16x32_f16 v[24:27], v[94:97], v[154:157], v[24:27]
	s_waitcnt lgkmcnt(4)
	v_mfma_f32_16x16x32_f16 v[12:15], v[78:81], v[170:173], v[12:15]
	v_mfma_f32_16x16x32_f16 v[8:11], v[94:97], v[170:173], v[8:11]
	s_waitcnt lgkmcnt(3)
	v_mfma_f32_16x16x32_f16 v[62:65], v[86:89], v[126:129], v[62:65]
	v_mfma_f32_16x16x32_f16 v[58:61], v[102:105], v[126:129], v[58:61]
	s_waitcnt lgkmcnt(2)
	v_mfma_f32_16x16x32_f16 v[46:49], v[86:89], v[134:137], v[46:49]
	v_mfma_f32_16x16x32_f16 v[42:45], v[102:105], v[134:137], v[42:45]
	s_waitcnt lgkmcnt(1)
	v_mfma_f32_16x16x32_f16 v[28:31], v[86:89], v[158:161], v[28:31]
	v_mfma_f32_16x16x32_f16 v[24:27], v[102:105], v[158:161], v[24:27]
	s_waitcnt lgkmcnt(0)
	v_mfma_f32_16x16x32_f16 v[12:15], v[86:89], v[174:177], v[12:15]
	v_mfma_f32_16x16x32_f16 v[8:11], v[102:105], v[174:177], v[8:11]
	s_setprio 0
	s_barrier
	s_add_u32 s14, s22, 0x40080
	s_addc_u32 s15, s23, 0
	s_add_i32 s22, s24, s13
	v_lshl_add_u64 v[78:79], s[14:15], 0, v[32:33]
	s_mov_b32 m0, s22
	s_nop 0
	global_load_lds_dwordx4 v[78:79], off
	v_lshl_add_u64 v[78:79], s[14:15], 0, v[198:199]
	s_add_i32 m0, s22, 0x2000
	s_nop 0
	global_load_lds_dwordx4 v[78:79], off
	s_waitcnt vmcnt(6)
	s_setprio 1
	s_barrier
	v_mfma_f32_16x16x32_f16 v[54:57], v[182:185], v[122:125], v[54:57]
	v_mfma_f32_16x16x32_f16 v[50:53], v[190:193], v[122:125], v[50:53]
	v_mfma_f32_16x16x32_f16 v[38:41], v[182:185], v[130:133], v[38:41]
	v_mfma_f32_16x16x32_f16 v[34:37], v[190:193], v[130:133], v[34:37]
	v_mfma_f32_16x16x32_f16 v[20:23], v[182:185], v[154:157], v[20:23]
	v_mfma_f32_16x16x32_f16 v[16:19], v[190:193], v[154:157], v[16:19]
	v_mfma_f32_16x16x32_f16 v[4:7], v[182:185], v[170:173], v[4:7]
	v_mfma_f32_16x16x32_f16 v[0:3], v[190:193], v[170:173], v[0:3]
	v_mfma_f32_16x16x32_f16 v[54:57], v[186:189], v[126:129], v[54:57]
	v_mfma_f32_16x16x32_f16 v[50:53], v[194:197], v[126:129], v[50:53]
	v_mfma_f32_16x16x32_f16 v[38:41], v[186:189], v[134:137], v[38:41]
	v_mfma_f32_16x16x32_f16 v[34:37], v[194:197], v[134:137], v[34:37]
	v_mfma_f32_16x16x32_f16 v[20:23], v[186:189], v[158:161], v[20:23]
	v_mfma_f32_16x16x32_f16 v[16:19], v[194:197], v[158:161], v[16:19]
	v_mfma_f32_16x16x32_f16 v[4:7], v[186:189], v[174:177], v[4:7]
	v_mfma_f32_16x16x32_f16 v[0:3], v[194:197], v[174:177], v[0:3]
	s_setprio 0
	s_add_u32 s39, s39, 0x100
	s_addc_u32 s40, s40, 0
	s_cmp_ge_u32 s41, s37
	s_mov_b64 s[14:15], s[20:21]
	s_mov_b32 s22, s41
	s_barrier
	s_cbranch_scc0 .LBB0_1117
	v_lshl_or_b32 v124, s12, 8, v231
	s_cmp_eq_u32 s10, 0
	s_movk_i32 s12, 0x5000
	s_cselect_b32 s12, 0xe000, s12
	v_readlane_b32 s14, v252, 51
	s_add_u32 s14, s14, s12
	v_readlane_b32 s12, v252, 52
	s_addc_u32 s15, s12, 0
	v_ashrrev_i32_e32 v125, 31, v124
	v_lshl_add_u64 v[86:87], v[124:125], 2, s[14:15]
	global_load_dwordx4 v[94:97], v[86:87], off offset:16
	global_load_dwordx4 v[102:105], v[86:87], off
	global_load_dwordx4 v[78:81], v[86:87], off offset:528
	s_nop 0
	global_load_dwordx4 v[86:89], v[86:87], off offset:512
	v_lshl_add_u32 v130, s10, 8, v229
	v_or_b32_e32 v128, 16, v130
	v_or_b32_e32 v126, 32, v130
	v_or_b32_e32 v122, 48, v130
	s_cmp_eq_u32 s11, 0
	v_ashrrev_i32_e32 v131, 31, v130
	v_ashrrev_i32_e32 v129, 31, v128
	v_ashrrev_i32_e32 v127, 31, v126
	v_ashrrev_i32_e32 v123, 31, v122
	s_cbranch_scc1 .LBB0_1120
	s_add_i32 s96, s11, -1
	s_lshl_b64 s[10:11], s[96:97], 20
	v_readlane_b32 s14, v252, 11
	v_readlane_b32 s15, v252, 12
	s_add_u32 s10, s14, s10
	s_addc_u32 s11, s15, s11
	v_lshlrev_b64 v[132:133], 2, v[124:125]
	v_lshrrev_b32_e32 v134, 5, v220
	v_mul_u32_u24_e32 v134, 48, v134
	s_nop 0
	v_sub_co_u32_e32 v132, vcc, v132, v134
	s_nop 1
	v_subbrev_co_u32_e32 v133, vcc, 0, v133, vcc
	v_lshl_add_u64 v[132:133], s[10:11], 0, v[132:133]
	s_mov_b64 s[10:11], 0x80000
	v_lshlrev_b64 v[204:205], 12, v[130:131]
	v_lshl_add_u64 v[204:205], v[204:205], 0, v[132:133]
	v_lshl_add_u64 v[212:213], v[204:205], 0, s[10:11]
	v_lshlrev_b64 v[206:207], 12, v[128:129]
	v_lshl_add_u64 v[206:207], v[206:207], 0, v[132:133]
	v_lshl_add_u64 v[214:215], v[206:207], 0, s[10:11]
	v_lshlrev_b64 v[208:209], 12, v[126:127]
	v_lshl_add_u64 v[208:209], v[208:209], 0, v[132:133]
	v_lshl_add_u64 v[216:217], v[208:209], 0, s[10:11]
	v_lshlrev_b64 v[210:211], 12, v[122:123]
	v_lshl_add_u64 v[210:211], v[210:211], 0, v[132:133]
	v_lshl_add_u64 v[218:219], v[210:211], 0, s[10:11]
	s_waitcnt vmcnt(0)
	v_pk_mul_f32 v[172:173], v[166:167], v[102:103]
	v_pk_mul_f32 v[174:175], v[168:169], v[104:105]
	v_pk_mul_f32 v[176:177], v[162:163], v[94:95]
	v_pk_mul_f32 v[178:179], v[164:165], v[96:97]
	s_nop 1
	v_permlane32_swap_b32_e32 v172, v176
	v_permlane32_swap_b32_e32 v173, v177
	v_permlane32_swap_b32_e32 v174, v178
	v_permlane32_swap_b32_e32 v175, v179
	s_nop 0
	global_store_dwordx4 v[204:205], v[172:175], off
	global_store_dwordx4 v[204:205], v[176:179], off offset:64
	v_pk_mul_f32 v[180:181], v[146:147], v[86:87]
	v_pk_mul_f32 v[182:183], v[148:149], v[88:89]
	v_pk_mul_f32 v[184:185], v[138:139], v[78:79]
	v_pk_mul_f32 v[186:187], v[140:141], v[80:81]
	s_nop 1
	v_permlane32_swap_b32_e32 v180, v184
	v_permlane32_swap_b32_e32 v181, v185
	v_permlane32_swap_b32_e32 v182, v186
	v_permlane32_swap_b32_e32 v183, v187
	s_nop 0
	global_store_dwordx4 v[204:205], v[180:183], off offset:512
	global_store_dwordx4 v[204:205], v[184:187], off offset:576
	v_pk_mul_f32 v[188:189], v[150:151], v[102:103]
	v_pk_mul_f32 v[190:191], v[152:153], v[104:105]
	v_pk_mul_f32 v[192:193], v[142:143], v[94:95]
	v_pk_mul_f32 v[194:195], v[144:145], v[96:97]
	s_nop 1
	v_permlane32_swap_b32_e32 v188, v192
	v_permlane32_swap_b32_e32 v189, v193
	v_permlane32_swap_b32_e32 v190, v194
	v_permlane32_swap_b32_e32 v191, v195
	s_nop 0
	global_store_dwordx4 v[206:207], v[188:191], off
	global_store_dwordx4 v[206:207], v[192:195], off offset:64
	v_pk_mul_f32 v[154:155], v[118:119], v[86:87]
	v_pk_mul_f32 v[156:157], v[120:121], v[88:89]
	v_pk_mul_f32 v[158:159], v[114:115], v[78:79]
	v_pk_mul_f32 v[160:161], v[116:117], v[80:81]
	s_nop 1
	v_permlane32_swap_b32_e32 v154, v158
	v_permlane32_swap_b32_e32 v155, v159
	v_permlane32_swap_b32_e32 v156, v160
	v_permlane32_swap_b32_e32 v157, v161
	s_nop 0
	global_store_dwordx4 v[206:207], v[154:157], off offset:512
	global_store_dwordx4 v[206:207], v[158:161], off offset:576
	v_pk_mul_f32 v[172:173], v[110:111], v[102:103]
	v_pk_mul_f32 v[174:175], v[112:113], v[104:105]
	v_pk_mul_f32 v[176:177], v[106:107], v[94:95]
	v_pk_mul_f32 v[178:179], v[108:109], v[96:97]
	s_nop 1
	v_permlane32_swap_b32_e32 v172, v176
	v_permlane32_swap_b32_e32 v173, v177
	v_permlane32_swap_b32_e32 v174, v178
	v_permlane32_swap_b32_e32 v175, v179
	s_nop 0
	global_store_dwordx4 v[208:209], v[172:175], off
	global_store_dwordx4 v[208:209], v[176:179], off offset:64
	v_pk_mul_f32 v[180:181], v[98:99], v[86:87]
	v_pk_mul_f32 v[182:183], v[100:101], v[88:89]
	v_pk_mul_f32 v[184:185], v[90:91], v[78:79]
	v_pk_mul_f32 v[186:187], v[92:93], v[80:81]
	s_nop 1
	v_permlane32_swap_b32_e32 v180, v184
	v_permlane32_swap_b32_e32 v181, v185
	v_permlane32_swap_b32_e32 v182, v186
	v_permlane32_swap_b32_e32 v183, v187
	s_nop 0
	global_store_dwordx4 v[208:209], v[180:183], off offset:512
	global_store_dwordx4 v[208:209], v[184:187], off offset:576
	v_pk_mul_f32 v[188:189], v[82:83], v[102:103]
	v_pk_mul_f32 v[190:191], v[84:85], v[104:105]
	v_pk_mul_f32 v[192:193], v[74:75], v[94:95]
	v_pk_mul_f32 v[194:195], v[76:77], v[96:97]
	s_nop 1
	v_permlane32_swap_b32_e32 v188, v192
	v_permlane32_swap_b32_e32 v189, v193
	v_permlane32_swap_b32_e32 v190, v194
	v_permlane32_swap_b32_e32 v191, v195
	s_nop 0
	global_store_dwordx4 v[210:211], v[188:191], off
	global_store_dwordx4 v[210:211], v[192:195], off offset:64
	v_pk_mul_f32 v[154:155], v[70:71], v[86:87]
	v_pk_mul_f32 v[156:157], v[72:73], v[88:89]
	v_pk_mul_f32 v[158:159], v[66:67], v[78:79]
	v_pk_mul_f32 v[160:161], v[68:69], v[80:81]
	s_nop 1
	v_permlane32_swap_b32_e32 v154, v158
	v_permlane32_swap_b32_e32 v155, v159
	v_permlane32_swap_b32_e32 v156, v160
	v_permlane32_swap_b32_e32 v157, v161
	s_nop 0
	global_store_dwordx4 v[210:211], v[154:157], off offset:512
	global_store_dwordx4 v[210:211], v[158:161], off offset:576
	v_pk_mul_f32 v[172:173], v[62:63], v[102:103]
	v_pk_mul_f32 v[174:175], v[64:65], v[104:105]
	v_pk_mul_f32 v[176:177], v[58:59], v[94:95]
	v_pk_mul_f32 v[178:179], v[60:61], v[96:97]
	s_nop 1
	v_permlane32_swap_b32_e32 v172, v176
	v_permlane32_swap_b32_e32 v173, v177
	v_permlane32_swap_b32_e32 v174, v178
	v_permlane32_swap_b32_e32 v175, v179
	s_nop 0
	global_store_dwordx4 v[212:213], v[172:175], off
	global_store_dwordx4 v[212:213], v[176:179], off offset:64
	v_pk_mul_f32 v[180:181], v[54:55], v[86:87]
	v_pk_mul_f32 v[182:183], v[56:57], v[88:89]
	v_pk_mul_f32 v[184:185], v[50:51], v[78:79]
	v_pk_mul_f32 v[186:187], v[52:53], v[80:81]
	s_nop 1
	v_permlane32_swap_b32_e32 v180, v184
	v_permlane32_swap_b32_e32 v181, v185
	v_permlane32_swap_b32_e32 v182, v186
	v_permlane32_swap_b32_e32 v183, v187
	s_nop 0
	global_store_dwordx4 v[212:213], v[180:183], off offset:512
	global_store_dwordx4 v[212:213], v[184:187], off offset:576
	v_pk_mul_f32 v[188:189], v[46:47], v[102:103]
	v_pk_mul_f32 v[190:191], v[48:49], v[104:105]
	v_pk_mul_f32 v[192:193], v[42:43], v[94:95]
	v_pk_mul_f32 v[194:195], v[44:45], v[96:97]
	s_nop 1
	v_permlane32_swap_b32_e32 v188, v192
	v_permlane32_swap_b32_e32 v189, v193
	v_permlane32_swap_b32_e32 v190, v194
	v_permlane32_swap_b32_e32 v191, v195
	s_nop 0
	global_store_dwordx4 v[214:215], v[188:191], off
	global_store_dwordx4 v[214:215], v[192:195], off offset:64
	v_pk_mul_f32 v[154:155], v[38:39], v[86:87]
	v_pk_mul_f32 v[156:157], v[40:41], v[88:89]
	v_pk_mul_f32 v[158:159], v[34:35], v[78:79]
	v_pk_mul_f32 v[160:161], v[36:37], v[80:81]
	s_nop 1
	v_permlane32_swap_b32_e32 v154, v158
	v_permlane32_swap_b32_e32 v155, v159
	v_permlane32_swap_b32_e32 v156, v160
	v_permlane32_swap_b32_e32 v157, v161
	s_nop 0
	global_store_dwordx4 v[214:215], v[154:157], off offset:512
	global_store_dwordx4 v[214:215], v[158:161], off offset:576
	v_pk_mul_f32 v[172:173], v[28:29], v[102:103]
	v_pk_mul_f32 v[174:175], v[30:31], v[104:105]
	v_pk_mul_f32 v[176:177], v[24:25], v[94:95]
	v_pk_mul_f32 v[178:179], v[26:27], v[96:97]
	s_nop 1
	v_permlane32_swap_b32_e32 v172, v176
	v_permlane32_swap_b32_e32 v173, v177
	v_permlane32_swap_b32_e32 v174, v178
	v_permlane32_swap_b32_e32 v175, v179
	s_nop 0
	global_store_dwordx4 v[216:217], v[172:175], off
	global_store_dwordx4 v[216:217], v[176:179], off offset:64
	v_pk_mul_f32 v[180:181], v[20:21], v[86:87]
	v_pk_mul_f32 v[182:183], v[22:23], v[88:89]
	v_pk_mul_f32 v[184:185], v[16:17], v[78:79]
	v_pk_mul_f32 v[186:187], v[18:19], v[80:81]
	s_nop 1
	v_permlane32_swap_b32_e32 v180, v184
	v_permlane32_swap_b32_e32 v181, v185
	v_permlane32_swap_b32_e32 v182, v186
	v_permlane32_swap_b32_e32 v183, v187
	s_nop 0
	global_store_dwordx4 v[216:217], v[180:183], off offset:512
	global_store_dwordx4 v[216:217], v[184:187], off offset:576
	v_pk_mul_f32 v[188:189], v[12:13], v[102:103]
	v_pk_mul_f32 v[190:191], v[14:15], v[104:105]
	v_pk_mul_f32 v[192:193], v[8:9], v[94:95]
	v_pk_mul_f32 v[194:195], v[10:11], v[96:97]
	s_nop 1
	v_permlane32_swap_b32_e32 v188, v192
	v_permlane32_swap_b32_e32 v189, v193
	v_permlane32_swap_b32_e32 v190, v194
	v_permlane32_swap_b32_e32 v191, v195
	s_nop 0
	global_store_dwordx4 v[218:219], v[188:191], off
	global_store_dwordx4 v[218:219], v[192:195], off offset:64
	v_pk_mul_f32 v[154:155], v[4:5], v[86:87]
	v_pk_mul_f32 v[156:157], v[6:7], v[88:89]
	v_pk_mul_f32 v[158:159], v[0:1], v[78:79]
	v_pk_mul_f32 v[160:161], v[2:3], v[80:81]
	s_nop 1
	v_permlane32_swap_b32_e32 v154, v158
	v_permlane32_swap_b32_e32 v155, v159
	v_permlane32_swap_b32_e32 v156, v160
	v_permlane32_swap_b32_e32 v157, v161
	s_nop 0
	global_store_dwordx4 v[218:219], v[154:157], off offset:512
	global_store_dwordx4 v[218:219], v[158:161], off offset:576
	s_cbranch_execnz .LBB0_1104
	s_branch .LBB0_1103

.LBB0_1276:
	s_add_u32 s16, s14, 0x100
	s_addc_u32 s17, s15, 0
	s_add_i32 s39, 0, 0x10000
	v_add_u32_e32 v152, s39, v137
	ds_read_b128 v[140:143], v152
	ds_read_b128 v[148:151], v152 offset:2048
	ds_read_b128 v[144:147], v152 offset:1024
	ds_read_b128 v[152:155], v152 offset:3072
	s_cmp_eq_u32 s38, 12
	s_cselect_b32 s21, s11, s17
	s_cselect_b32 s20, s10, s16
	s_cselect_b32 s19, s13, s37
	s_cselect_b32 s18, s12, s3
	v_lshl_add_u64 v[188:189], s[14:15], 0, v[132:133]
	s_add_i32 m0, s9, 0xc000
	ds_read_b128 v[156:159], v139
	ds_read_b128 v[164:167], v139 offset:2048
	ds_read_b128 v[172:175], v139 offset:4096
	ds_read_b128 v[180:183], v139 offset:6144
	ds_read_b128 v[160:163], v139 offset:1024
	ds_read_b128 v[168:171], v139 offset:3072
	ds_read_b128 v[176:179], v139 offset:5120
	ds_read_b128 v[184:187], v139 offset:7168
	global_load_lds_dwordx4 v[188:189], off
	v_lshl_add_u64 v[188:189], s[14:15], 0, v[134:135]
	s_add_i32 m0, s9, 0xe000
	s_nop 0
	global_load_lds_dwordx4 v[188:189], off
	s_waitcnt lgkmcnt(8)
	s_setprio 1
	s_barrier
	s_waitcnt lgkmcnt(7)
	v_mfma_f32_16x16x32_f16 v[126:129], v[140:143], v[156:159], v[126:129]
	v_mfma_f32_16x16x32_f16 v[122:125], v[148:151], v[156:159], v[122:125]
	s_waitcnt lgkmcnt(6)
	v_mfma_f32_16x16x32_f16 v[110:113], v[140:143], v[164:167], v[110:113]
	v_mfma_f32_16x16x32_f16 v[106:109], v[148:151], v[164:167], v[106:109]
	s_waitcnt lgkmcnt(5)
	v_mfma_f32_16x16x32_f16 v[94:97], v[140:143], v[172:175], v[94:97]
	v_mfma_f32_16x16x32_f16 v[90:93], v[148:151], v[172:175], v[90:93]
	s_waitcnt lgkmcnt(4)
	v_mfma_f32_16x16x32_f16 v[78:81], v[140:143], v[180:183], v[78:81]
	v_mfma_f32_16x16x32_f16 v[74:77], v[148:151], v[180:183], v[74:77]
	s_waitcnt lgkmcnt(3)
	v_mfma_f32_16x16x32_f16 v[126:129], v[144:147], v[160:163], v[126:129]
	v_mfma_f32_16x16x32_f16 v[122:125], v[152:155], v[160:163], v[122:125]
	s_waitcnt lgkmcnt(2)
	v_mfma_f32_16x16x32_f16 v[110:113], v[144:147], v[168:171], v[110:113]
	v_mfma_f32_16x16x32_f16 v[106:109], v[152:155], v[168:171], v[106:109]
	s_waitcnt lgkmcnt(1)
	v_mfma_f32_16x16x32_f16 v[94:97], v[144:147], v[176:179], v[94:97]
	v_mfma_f32_16x16x32_f16 v[90:93], v[152:155], v[176:179], v[90:93]
	s_waitcnt lgkmcnt(0)
	v_mfma_f32_16x16x32_f16 v[78:81], v[144:147], v[184:187], v[78:81]
	v_mfma_f32_16x16x32_f16 v[74:77], v[152:155], v[184:187], v[74:77]
	s_setprio 0
	s_barrier
	s_add_i32 s40, 0, 0x14000
	s_add_i32 s14, s39, s26
	v_add_u32_e32 v200, s40, v137
	v_lshl_add_u64 v[204:205], s[18:19], 0, v[32:33]
	s_mov_b32 m0, s14
	ds_read_b128 v[188:191], v200
	ds_read_b128 v[196:199], v200 offset:2048
	ds_read_b128 v[192:195], v200 offset:1024
	ds_read_b128 v[200:203], v200 offset:3072
	global_load_lds_dwordx4 v[204:205], off
	v_lshl_add_u64 v[206:207], s[18:19], 0, v[130:131]
	s_add_i32 m0, s14, 0x2000
	s_nop 0
	global_load_lds_dwordx4 v[206:207], off
	s_setprio 1
	s_barrier
	s_waitcnt lgkmcnt(2)
	v_mfma_f32_16x16x32_f16 v[118:121], v[188:191], v[156:159], v[118:121]
	v_mfma_f32_16x16x32_f16 v[114:117], v[196:199], v[156:159], v[114:117]
	v_mfma_f32_16x16x32_f16 v[102:105], v[188:191], v[164:167], v[102:105]
	v_mfma_f32_16x16x32_f16 v[98:101], v[196:199], v[164:167], v[98:101]
	v_mfma_f32_16x16x32_f16 v[86:89], v[188:191], v[172:175], v[86:89]
	v_mfma_f32_16x16x32_f16 v[82:85], v[196:199], v[172:175], v[82:85]
	v_mfma_f32_16x16x32_f16 v[70:73], v[188:191], v[180:183], v[70:73]
	v_mfma_f32_16x16x32_f16 v[66:69], v[196:199], v[180:183], v[66:69]
	s_waitcnt lgkmcnt(0)
	v_mfma_f32_16x16x32_f16 v[118:121], v[192:195], v[160:163], v[118:121]
	v_mfma_f32_16x16x32_f16 v[114:117], v[200:203], v[160:163], v[114:117]
	v_mfma_f32_16x16x32_f16 v[102:105], v[192:195], v[168:171], v[102:105]
	v_mfma_f32_16x16x32_f16 v[98:101], v[200:203], v[168:171], v[98:101]
	v_mfma_f32_16x16x32_f16 v[86:89], v[192:195], v[176:179], v[86:89]
	v_mfma_f32_16x16x32_f16 v[82:85], v[200:203], v[176:179], v[82:85]
	v_mfma_f32_16x16x32_f16 v[70:73], v[192:195], v[184:187], v[70:73]
	v_mfma_f32_16x16x32_f16 v[66:69], v[200:203], v[184:187], v[66:69]
	s_setprio 0
	s_mov_b32 m0, s9
	v_lshl_add_u64 v[208:209], s[20:21], 0, v[32:33]
	s_barrier
	ds_read_b128 v[156:159], v139 offset:16384
	ds_read_b128 v[164:167], v139 offset:18432
	ds_read_b128 v[172:175], v139 offset:20480
	ds_read_b128 v[180:183], v139 offset:22528
	ds_read_b128 v[160:163], v139 offset:17408
	ds_read_b128 v[168:171], v139 offset:19456
	ds_read_b128 v[176:179], v139 offset:21504
	ds_read_b128 v[184:187], v139 offset:23552
	global_load_lds_dwordx4 v[208:209], off
	v_lshl_add_u64 v[210:211], s[20:21], 0, v[130:131]
	s_mov_b32 m0, s27
	s_nop 0
	global_load_lds_dwordx4 v[210:211], off
	s_setprio 1
	s_barrier
	s_waitcnt lgkmcnt(7)
	v_mfma_f32_16x16x32_f16 v[62:65], v[140:143], v[156:159], v[62:65]
	v_mfma_f32_16x16x32_f16 v[58:61], v[148:151], v[156:159], v[58:61]
	s_waitcnt lgkmcnt(6)
	v_mfma_f32_16x16x32_f16 v[46:49], v[140:143], v[164:167], v[46:49]
	v_mfma_f32_16x16x32_f16 v[42:45], v[148:151], v[164:167], v[42:45]
	s_waitcnt lgkmcnt(5)
	v_mfma_f32_16x16x32_f16 v[28:31], v[140:143], v[172:175], v[28:31]
	v_mfma_f32_16x16x32_f16 v[24:27], v[148:151], v[172:175], v[24:27]
	s_waitcnt lgkmcnt(4)
	v_mfma_f32_16x16x32_f16 v[12:15], v[140:143], v[180:183], v[12:15]
	v_mfma_f32_16x16x32_f16 v[8:11], v[148:151], v[180:183], v[8:11]
	s_waitcnt lgkmcnt(3)
	v_mfma_f32_16x16x32_f16 v[62:65], v[144:147], v[160:163], v[62:65]
	v_mfma_f32_16x16x32_f16 v[58:61], v[152:155], v[160:163], v[58:61]
	s_waitcnt lgkmcnt(2)
	v_mfma_f32_16x16x32_f16 v[46:49], v[144:147], v[168:171], v[46:49]
	v_mfma_f32_16x16x32_f16 v[42:45], v[152:155], v[168:171], v[42:45]
	s_waitcnt lgkmcnt(1)
	v_mfma_f32_16x16x32_f16 v[28:31], v[144:147], v[176:179], v[28:31]
	v_mfma_f32_16x16x32_f16 v[24:27], v[152:155], v[176:179], v[24:27]
	s_waitcnt lgkmcnt(0)
	v_mfma_f32_16x16x32_f16 v[12:15], v[144:147], v[184:187], v[12:15]
	v_mfma_f32_16x16x32_f16 v[8:11], v[152:155], v[184:187], v[8:11]
	s_setprio 0
	s_barrier
	s_add_u32 s14, s18, 0x40000
	s_addc_u32 s15, s19, 0
	s_add_i32 s39, s40, s26
	v_lshl_add_u64 v[140:141], s[14:15], 0, v[32:33]
	s_mov_b32 m0, s39
	s_nop 0
	global_load_lds_dwordx4 v[140:141], off
	v_lshl_add_u64 v[140:141], s[14:15], 0, v[130:131]
	s_add_i32 m0, s39, 0x2000
	s_nop 0
	global_load_lds_dwordx4 v[140:141], off
	s_waitcnt vmcnt(6)
	s_setprio 1
	s_barrier
	v_mfma_f32_16x16x32_f16 v[54:57], v[188:191], v[156:159], v[54:57]
	v_mfma_f32_16x16x32_f16 v[50:53], v[196:199], v[156:159], v[50:53]
	v_mfma_f32_16x16x32_f16 v[38:41], v[188:191], v[164:167], v[38:41]
	v_mfma_f32_16x16x32_f16 v[34:37], v[196:199], v[164:167], v[34:37]
	v_mfma_f32_16x16x32_f16 v[20:23], v[188:191], v[172:175], v[20:23]
	v_mfma_f32_16x16x32_f16 v[16:19], v[196:199], v[172:175], v[16:19]
	v_mfma_f32_16x16x32_f16 v[4:7], v[188:191], v[180:183], v[4:7]
	v_mfma_f32_16x16x32_f16 v[0:3], v[196:199], v[180:183], v[0:3]
	v_mfma_f32_16x16x32_f16 v[54:57], v[192:195], v[160:163], v[54:57]
	v_mfma_f32_16x16x32_f16 v[50:53], v[200:203], v[160:163], v[50:53]
	v_mfma_f32_16x16x32_f16 v[38:41], v[192:195], v[168:171], v[38:41]
	v_mfma_f32_16x16x32_f16 v[34:37], v[200:203], v[168:171], v[34:37]
	v_mfma_f32_16x16x32_f16 v[20:23], v[192:195], v[176:179], v[20:23]
	v_mfma_f32_16x16x32_f16 v[16:19], v[200:203], v[176:179], v[16:19]
	v_mfma_f32_16x16x32_f16 v[4:7], v[192:195], v[184:187], v[4:7]
	v_mfma_f32_16x16x32_f16 v[0:3], v[200:203], v[184:187], v[0:3]
	s_setprio 0
	s_add_i32 s39, 0, 0x18000
	v_add_u32_e32 v152, s39, v137
	s_barrier
	ds_read_b128 v[140:143], v152
	ds_read_b128 v[148:151], v152 offset:2048
	ds_read_b128 v[144:147], v152 offset:1024
	ds_read_b128 v[152:155], v152 offset:3072
	s_add_u32 s14, s20, 0x40000
	s_addc_u32 s15, s21, 0
	s_mov_b32 m0, s28
	v_lshl_add_u64 v[188:189], s[14:15], 0, v[32:33]
	ds_read_b128 v[156:159], v139 offset:32768
	ds_read_b128 v[164:167], v139 offset:34816
	ds_read_b128 v[172:175], v139 offset:36864
	ds_read_b128 v[180:183], v139 offset:38912
	ds_read_b128 v[160:163], v139 offset:33792
	ds_read_b128 v[168:171], v139 offset:35840
	ds_read_b128 v[176:179], v139 offset:37888
	ds_read_b128 v[184:187], v139 offset:39936
	global_load_lds_dwordx4 v[188:189], off
	v_lshl_add_u64 v[188:189], s[14:15], 0, v[130:131]
	s_mov_b32 m0, s29
	s_nop 0
	global_load_lds_dwordx4 v[188:189], off
	s_waitcnt lgkmcnt(8)
	s_setprio 1
	s_barrier
	s_waitcnt lgkmcnt(7)
	v_mfma_f32_16x16x32_f16 v[126:129], v[140:143], v[156:159], v[126:129]
	v_mfma_f32_16x16x32_f16 v[122:125], v[148:151], v[156:159], v[122:125]
	s_waitcnt lgkmcnt(6)
	v_mfma_f32_16x16x32_f16 v[110:113], v[140:143], v[164:167], v[110:113]
	v_mfma_f32_16x16x32_f16 v[106:109], v[148:151], v[164:167], v[106:109]
	s_waitcnt lgkmcnt(5)
	v_mfma_f32_16x16x32_f16 v[94:97], v[140:143], v[172:175], v[94:97]
	v_mfma_f32_16x16x32_f16 v[90:93], v[148:151], v[172:175], v[90:93]
	s_waitcnt lgkmcnt(4)
	v_mfma_f32_16x16x32_f16 v[78:81], v[140:143], v[180:183], v[78:81]
	v_mfma_f32_16x16x32_f16 v[74:77], v[148:151], v[180:183], v[74:77]
	s_waitcnt lgkmcnt(3)
	v_mfma_f32_16x16x32_f16 v[126:129], v[144:147], v[160:163], v[126:129]
	v_mfma_f32_16x16x32_f16 v[122:125], v[152:155], v[160:163], v[122:125]
	s_waitcnt lgkmcnt(2)
	v_mfma_f32_16x16x32_f16 v[110:113], v[144:147], v[168:171], v[110:113]
	v_mfma_f32_16x16x32_f16 v[106:109], v[152:155], v[168:171], v[106:109]
	s_waitcnt lgkmcnt(1)
	v_mfma_f32_16x16x32_f16 v[94:97], v[144:147], v[176:179], v[94:97]
	v_mfma_f32_16x16x32_f16 v[90:93], v[152:155], v[176:179], v[90:93]
	s_waitcnt lgkmcnt(0)
	v_mfma_f32_16x16x32_f16 v[78:81], v[144:147], v[184:187], v[78:81]
	v_mfma_f32_16x16x32_f16 v[74:77], v[152:155], v[184:187], v[74:77]
	s_setprio 0
	s_barrier
	s_add_i32 s20, 0, 0x1c000
	s_add_i32 s14, s39, s26
	v_add_u32_e32 v200, s20, v137
	v_lshl_add_u64 v[204:205], v[204:205], 0, s[84:85]
	s_mov_b32 m0, s14
	ds_read_b128 v[188:191], v200
	ds_read_b128 v[196:199], v200 offset:2048
	ds_read_b128 v[192:195], v200 offset:1024
	ds_read_b128 v[200:203], v200 offset:3072
	global_load_lds_dwordx4 v[204:205], off
	v_lshl_add_u64 v[204:205], v[206:207], 0, s[84:85]
	s_add_i32 m0, s14, 0x2000
	s_nop 0
	global_load_lds_dwordx4 v[204:205], off
	s_setprio 1
	s_barrier
	s_waitcnt lgkmcnt(2)
	v_mfma_f32_16x16x32_f16 v[118:121], v[188:191], v[156:159], v[118:121]
	v_mfma_f32_16x16x32_f16 v[114:117], v[196:199], v[156:159], v[114:117]
	v_mfma_f32_16x16x32_f16 v[102:105], v[188:191], v[164:167], v[102:105]
	v_mfma_f32_16x16x32_f16 v[98:101], v[196:199], v[164:167], v[98:101]
	v_mfma_f32_16x16x32_f16 v[86:89], v[188:191], v[172:175], v[86:89]
	v_mfma_f32_16x16x32_f16 v[82:85], v[196:199], v[172:175], v[82:85]
	v_mfma_f32_16x16x32_f16 v[70:73], v[188:191], v[180:183], v[70:73]
	v_mfma_f32_16x16x32_f16 v[66:69], v[196:199], v[180:183], v[66:69]
	s_waitcnt lgkmcnt(0)
	v_mfma_f32_16x16x32_f16 v[118:121], v[192:195], v[160:163], v[118:121]
	v_mfma_f32_16x16x32_f16 v[114:117], v[200:203], v[160:163], v[114:117]
	v_mfma_f32_16x16x32_f16 v[102:105], v[192:195], v[168:171], v[102:105]
	v_mfma_f32_16x16x32_f16 v[98:101], v[200:203], v[168:171], v[98:101]
	v_mfma_f32_16x16x32_f16 v[86:89], v[192:195], v[176:179], v[86:89]
	v_mfma_f32_16x16x32_f16 v[82:85], v[200:203], v[176:179], v[82:85]
	v_mfma_f32_16x16x32_f16 v[70:73], v[192:195], v[184:187], v[70:73]
	v_mfma_f32_16x16x32_f16 v[66:69], v[200:203], v[184:187], v[66:69]
	s_setprio 0
	s_mov_b32 m0, s30
	v_lshl_add_u64 v[204:205], v[208:209], 0, s[84:85]
	s_barrier
	ds_read_b128 v[156:159], v139 offset:49152
	ds_read_b128 v[164:167], v139 offset:51200
	ds_read_b128 v[172:175], v139 offset:53248
	ds_read_b128 v[180:183], v139 offset:55296
	ds_read_b128 v[160:163], v139 offset:50176
	ds_read_b128 v[168:171], v139 offset:52224
	ds_read_b128 v[176:179], v139 offset:54272
	ds_read_b128 v[184:187], v139 offset:56320
	global_load_lds_dwordx4 v[204:205], off
	v_lshl_add_u64 v[204:205], v[210:211], 0, s[84:85]
	s_mov_b32 m0, s31
	s_nop 0
	global_load_lds_dwordx4 v[204:205], off
	s_setprio 1
	s_barrier
	s_waitcnt lgkmcnt(7)
	v_mfma_f32_16x16x32_f16 v[62:65], v[140:143], v[156:159], v[62:65]
	v_mfma_f32_16x16x32_f16 v[58:61], v[148:151], v[156:159], v[58:61]
	s_waitcnt lgkmcnt(6)
	v_mfma_f32_16x16x32_f16 v[46:49], v[140:143], v[164:167], v[46:49]
	v_mfma_f32_16x16x32_f16 v[42:45], v[148:151], v[164:167], v[42:45]
	s_waitcnt lgkmcnt(5)
	v_mfma_f32_16x16x32_f16 v[28:31], v[140:143], v[172:175], v[28:31]
	v_mfma_f32_16x16x32_f16 v[24:27], v[148:151], v[172:175], v[24:27]
	s_waitcnt lgkmcnt(4)
	v_mfma_f32_16x16x32_f16 v[12:15], v[140:143], v[180:183], v[12:15]
	v_mfma_f32_16x16x32_f16 v[8:11], v[148:151], v[180:183], v[8:11]
	s_waitcnt lgkmcnt(3)
	v_mfma_f32_16x16x32_f16 v[62:65], v[144:147], v[160:163], v[62:65]
	v_mfma_f32_16x16x32_f16 v[58:61], v[152:155], v[160:163], v[58:61]
	s_waitcnt lgkmcnt(2)
	v_mfma_f32_16x16x32_f16 v[46:49], v[144:147], v[168:171], v[46:49]
	v_mfma_f32_16x16x32_f16 v[42:45], v[152:155], v[168:171], v[42:45]
	s_waitcnt lgkmcnt(1)
	v_mfma_f32_16x16x32_f16 v[28:31], v[144:147], v[176:179], v[28:31]
	v_mfma_f32_16x16x32_f16 v[24:27], v[152:155], v[176:179], v[24:27]
	s_waitcnt lgkmcnt(0)
	v_mfma_f32_16x16x32_f16 v[12:15], v[144:147], v[184:187], v[12:15]
	v_mfma_f32_16x16x32_f16 v[8:11], v[152:155], v[184:187], v[8:11]
	s_setprio 0
	s_barrier
	s_add_u32 s14, s18, 0x40080
	s_addc_u32 s15, s19, 0
	s_add_i32 s18, s20, s26
	v_lshl_add_u64 v[140:141], s[14:15], 0, v[32:33]
	s_mov_b32 m0, s18
	s_nop 0
	global_load_lds_dwordx4 v[140:141], off
	v_lshl_add_u64 v[140:141], s[14:15], 0, v[130:131]
	s_add_i32 m0, s18, 0x2000
	s_nop 0
	global_load_lds_dwordx4 v[140:141], off
	s_waitcnt vmcnt(6)
	s_setprio 1
	s_barrier
	v_mfma_f32_16x16x32_f16 v[54:57], v[188:191], v[156:159], v[54:57]
	v_mfma_f32_16x16x32_f16 v[50:53], v[196:199], v[156:159], v[50:53]
	v_mfma_f32_16x16x32_f16 v[38:41], v[188:191], v[164:167], v[38:41]
	v_mfma_f32_16x16x32_f16 v[34:37], v[196:199], v[164:167], v[34:37]
	v_mfma_f32_16x16x32_f16 v[20:23], v[188:191], v[172:175], v[20:23]
	v_mfma_f32_16x16x32_f16 v[16:19], v[196:199], v[172:175], v[16:19]
	v_mfma_f32_16x16x32_f16 v[4:7], v[188:191], v[180:183], v[4:7]
	v_mfma_f32_16x16x32_f16 v[0:3], v[196:199], v[180:183], v[0:3]
	v_mfma_f32_16x16x32_f16 v[54:57], v[192:195], v[160:163], v[54:57]
	v_mfma_f32_16x16x32_f16 v[50:53], v[200:203], v[160:163], v[50:53]
	v_mfma_f32_16x16x32_f16 v[38:41], v[192:195], v[168:171], v[38:41]
	v_mfma_f32_16x16x32_f16 v[34:37], v[200:203], v[168:171], v[34:37]
	v_mfma_f32_16x16x32_f16 v[20:23], v[192:195], v[176:179], v[20:23]
	v_mfma_f32_16x16x32_f16 v[16:19], v[200:203], v[176:179], v[16:19]
	v_mfma_f32_16x16x32_f16 v[4:7], v[192:195], v[184:187], v[4:7]
	v_mfma_f32_16x16x32_f16 v[0:3], v[200:203], v[184:187], v[0:3]
	s_setprio 0
	s_add_i32 s38, s38, 2
	s_add_u32 s3, s3, 0x100
	s_addc_u32 s37, s37, 0
	s_cmp_gt_u32 s38, 13
	s_mov_b64 s[14:15], s[16:17]
	s_barrier
	s_cbranch_scc0 .LBB0_1276
	v_mul_f32_e32 v144, 0xbfb8aa3b, v127
	v_mul_f32_e32 v141, 0xbfb8aa3b, v126
	v_exp_f32_e32 v145, v144
	v_mul_f32_e32 v144, 0xbfb8aa3b, v128
	v_exp_f32_e32 v141, v141
	v_exp_f32_e32 v146, v144
	v_mul_f32_e32 v144, 0xbfb8aa3b, v129
	v_exp_f32_e32 v147, v144
	v_mul_f32_e32 v144, 0xbfb8aa3b, v122
	v_exp_f32_e32 v148, v144
	v_mul_f32_e32 v144, 0xbfb8aa3b, v123
	v_exp_f32_e32 v149, v144
	v_mul_f32_e32 v144, 0xbfb8aa3b, v124
	v_exp_f32_e32 v150, v144
	v_mul_f32_e32 v144, 0xbfb8aa3b, v125
	v_add_f32_e32 v141, 1.0, v141
	v_exp_f32_e32 v151, v144
	v_rcp_f32_e32 v144, v141
	v_add_f32_e32 v141, 1.0, v145
	v_rcp_f32_e32 v145, v141
	v_add_f32_e32 v141, 1.0, v146
	v_rcp_f32_e32 v146, v141
	v_add_f32_e32 v141, 1.0, v147
	v_rcp_f32_e32 v147, v141
	v_add_f32_e32 v141, 1.0, v148
	v_rcp_f32_e32 v148, v141
	v_add_f32_e32 v141, 1.0, v149
	v_rcp_f32_e32 v149, v141
	v_add_f32_e32 v141, 1.0, v150
	v_rcp_f32_e32 v150, v141
	v_add_f32_e32 v141, 1.0, v151
	v_pk_mul_f32 v[126:127], v[126:127], v[144:145]
	v_rcp_f32_e32 v151, v141
	v_pk_mul_f32 v[118:119], v[126:127], v[118:119]
	v_pk_mul_f32 v[126:127], v[128:129], v[146:147]
	v_cvt_pk_f16_f32 v118, v118, v119
	v_pk_mul_f32 v[120:121], v[126:127], v[120:121]
	v_lshl_or_b32 v142, s36, 7, v138
	v_cvt_pk_f16_f32 v119, v120, v121
	v_pk_mul_f32 v[120:121], v[122:123], v[148:149]
	v_lshl_add_u32 v140, s8, 8, v136
	v_pk_mul_f32 v[114:115], v[120:121], v[114:115]
	v_ashrrev_i32_e32 v143, 31, v142
	v_cvt_pk_f16_f32 v120, v114, v115
	v_pk_mul_f32 v[114:115], v[124:125], v[150:151]
	s_movk_i32 s3, 0x1600
	v_pk_mul_f32 v[114:115], v[114:115], v[116:117]
	v_lshlrev_b64 v[116:117], 1, v[142:143]
	v_cvt_pk_f16_f32 v121, v114, v115
	v_mov_b64_e32 v[114:115], s[92:93]
	v_mad_i64_i32 v[122:123], s[10:11], v140, s3, v[114:115]
	v_lshl_add_u64 v[122:123], v[122:123], 0, v[116:117]
	global_store_dwordx4 v[122:123], v[118:121], off
	v_mul_f32_e32 v122, 0xbfb8aa3b, v106
	v_mul_f32_e32 v123, 0xbfb8aa3b, v107
	v_mul_f32_e32 v118, 0xbfb8aa3b, v110
	v_mul_f32_e32 v119, 0xbfb8aa3b, v111
	v_exp_f32_e32 v118, v118
	v_exp_f32_e32 v119, v119
	v_mul_f32_e32 v120, 0xbfb8aa3b, v112
	v_mul_f32_e32 v121, 0xbfb8aa3b, v113
	v_exp_f32_e32 v120, v120
	v_exp_f32_e32 v121, v121
	v_exp_f32_e32 v122, v122
	v_exp_f32_e32 v123, v123
	v_mul_f32_e32 v124, 0xbfb8aa3b, v108
	v_mul_f32_e32 v125, 0xbfb8aa3b, v109
	v_add_f32_e32 v118, 1.0, v118
	v_add_f32_e32 v119, 1.0, v119
	v_exp_f32_e32 v124, v124
	v_exp_f32_e32 v125, v125
	v_rcp_f32_e32 v118, v118
	v_rcp_f32_e32 v119, v119
	v_add_f32_e32 v120, 1.0, v120
	v_add_f32_e32 v121, 1.0, v121
	v_rcp_f32_e32 v120, v120
	v_rcp_f32_e32 v121, v121
	v_add_f32_e32 v122, 1.0, v122
	v_add_f32_e32 v123, 1.0, v123
	v_rcp_f32_e32 v122, v122
	v_rcp_f32_e32 v123, v123
	v_add_f32_e32 v124, 1.0, v124
	v_add_f32_e32 v125, 1.0, v125
	v_pk_mul_f32 v[110:111], v[110:111], v[118:119]
	v_rcp_f32_e32 v124, v124
	v_rcp_f32_e32 v125, v125
	v_pk_mul_f32 v[102:103], v[110:111], v[102:103]
	v_pk_mul_f32 v[110:111], v[112:113], v[120:121]
	v_cvt_pk_f16_f32 v102, v102, v103
	v_pk_mul_f32 v[104:105], v[110:111], v[104:105]
	s_and_b64 vcc, exec, s[0:1]
	v_cvt_pk_f16_f32 v103, v104, v105
	v_pk_mul_f32 v[104:105], v[106:107], v[122:123]
	s_mov_b32 s36, s35
	v_pk_mul_f32 v[98:99], v[104:105], v[98:99]
	s_mov_b32 s8, s2
	v_cvt_pk_f16_f32 v104, v98, v99
	v_pk_mul_f32 v[98:99], v[108:109], v[124:125]
	s_mov_b64 s[16:17], s[6:7]
	v_pk_mul_f32 v[98:99], v[98:99], v[100:101]
	v_mul_f32_e32 v100, 0xbfb8aa3b, v96
	v_cvt_pk_f16_f32 v105, v98, v99
	v_or_b32_e32 v98, 16, v140
	v_mad_i64_i32 v[98:99], s[10:11], v98, s3, v[114:115]
	v_lshl_add_u64 v[98:99], v[98:99], 0, v[116:117]
	global_store_dwordx4 v[98:99], v[102:105], off
	v_mul_f32_e32 v98, 0xbfb8aa3b, v94
	v_mul_f32_e32 v99, 0xbfb8aa3b, v95
	v_exp_f32_e32 v98, v98
	v_exp_f32_e32 v99, v99
	v_mul_f32_e32 v101, 0xbfb8aa3b, v97
	v_exp_f32_e32 v100, v100
	v_exp_f32_e32 v101, v101
	v_mul_f32_e32 v102, 0xbfb8aa3b, v90
	v_mul_f32_e32 v103, 0xbfb8aa3b, v91
	v_exp_f32_e32 v102, v102
	v_exp_f32_e32 v103, v103
	v_mul_f32_e32 v104, 0xbfb8aa3b, v92
	v_mul_f32_e32 v105, 0xbfb8aa3b, v93
	v_add_f32_e32 v98, 1.0, v98
	v_add_f32_e32 v99, 1.0, v99
	v_exp_f32_e32 v104, v104
	v_exp_f32_e32 v105, v105
	v_rcp_f32_e32 v98, v98
	v_rcp_f32_e32 v99, v99
	v_add_f32_e32 v100, 1.0, v100
	v_add_f32_e32 v101, 1.0, v101
	v_rcp_f32_e32 v100, v100
	v_rcp_f32_e32 v101, v101
	v_add_f32_e32 v102, 1.0, v102
	v_add_f32_e32 v103, 1.0, v103
	v_rcp_f32_e32 v102, v102
	v_rcp_f32_e32 v103, v103
	v_add_f32_e32 v104, 1.0, v104
	v_add_f32_e32 v105, 1.0, v105
	v_pk_mul_f32 v[94:95], v[94:95], v[98:99]
	v_rcp_f32_e32 v104, v104
	v_rcp_f32_e32 v105, v105
	v_pk_mul_f32 v[86:87], v[94:95], v[86:87]
	v_pk_mul_f32 v[94:95], v[96:97], v[100:101]
	v_cvt_pk_f16_f32 v86, v86, v87
	v_pk_mul_f32 v[88:89], v[94:95], v[88:89]
	s_mov_b64 s[14:15], s[4:5]
	v_cvt_pk_f16_f32 v87, v88, v89
	v_pk_mul_f32 v[88:89], v[90:91], v[102:103]
	s_nop 0
	v_pk_mul_f32 v[82:83], v[88:89], v[82:83]
	s_nop 0
	v_cvt_pk_f16_f32 v88, v82, v83
	v_pk_mul_f32 v[82:83], v[92:93], v[104:105]
	s_nop 0
	v_pk_mul_f32 v[82:83], v[82:83], v[84:85]
	v_mul_f32_e32 v84, 0xbfb8aa3b, v80
	v_cvt_pk_f16_f32 v89, v82, v83
	v_or_b32_e32 v82, 32, v140
	v_mad_i64_i32 v[82:83], s[10:11], v82, s3, v[114:115]
	v_lshl_add_u64 v[82:83], v[82:83], 0, v[116:117]
	global_store_dwordx4 v[82:83], v[86:89], off
	v_mul_f32_e32 v82, 0xbfb8aa3b, v78
	v_mul_f32_e32 v83, 0xbfb8aa3b, v79
	v_exp_f32_e32 v82, v82
	v_exp_f32_e32 v83, v83
	v_mul_f32_e32 v85, 0xbfb8aa3b, v81
	v_exp_f32_e32 v84, v84
	v_exp_f32_e32 v85, v85
	v_mul_f32_e32 v86, 0xbfb8aa3b, v74
	v_mul_f32_e32 v87, 0xbfb8aa3b, v75
	v_exp_f32_e32 v86, v86
	v_exp_f32_e32 v87, v87
	v_mul_f32_e32 v88, 0xbfb8aa3b, v76
	v_mul_f32_e32 v89, 0xbfb8aa3b, v77
	v_add_f32_e32 v82, 1.0, v82
	v_add_f32_e32 v83, 1.0, v83
	v_exp_f32_e32 v88, v88
	v_exp_f32_e32 v89, v89
	v_rcp_f32_e32 v82, v82
	v_rcp_f32_e32 v83, v83
	v_add_f32_e32 v84, 1.0, v84
	v_add_f32_e32 v85, 1.0, v85
	v_rcp_f32_e32 v84, v84
	v_rcp_f32_e32 v85, v85
	v_add_f32_e32 v86, 1.0, v86
	v_add_f32_e32 v87, 1.0, v87
	v_rcp_f32_e32 v86, v86
	v_rcp_f32_e32 v87, v87
	v_add_f32_e32 v88, 1.0, v88
	v_add_f32_e32 v89, 1.0, v89
	v_pk_mul_f32 v[78:79], v[78:79], v[82:83]
	v_rcp_f32_e32 v88, v88
	v_rcp_f32_e32 v89, v89
	v_pk_mul_f32 v[70:71], v[78:79], v[70:71]
	v_pk_mul_f32 v[78:79], v[80:81], v[84:85]
	v_cvt_pk_f16_f32 v70, v70, v71
	v_pk_mul_f32 v[72:73], v[78:79], v[72:73]
	s_nop 0
	v_cvt_pk_f16_f32 v71, v72, v73
	v_pk_mul_f32 v[72:73], v[74:75], v[86:87]
	v_add_u32_e32 v74, 0x80, v140
	v_pk_mul_f32 v[66:67], v[72:73], v[66:67]
	s_nop 0
	v_cvt_pk_f16_f32 v72, v66, v67
	v_pk_mul_f32 v[66:67], v[76:77], v[88:89]
	s_nop 0
	v_pk_mul_f32 v[66:67], v[66:67], v[68:69]
	v_mul_f32_e32 v68, 0xbfb8aa3b, v64
	v_cvt_pk_f16_f32 v73, v66, v67
	v_or_b32_e32 v66, 48, v140
	v_mad_i64_i32 v[66:67], s[10:11], v66, s3, v[114:115]
	v_lshl_add_u64 v[66:67], v[66:67], 0, v[116:117]
	global_store_dwordx4 v[66:67], v[70:73], off
	v_mul_f32_e32 v66, 0xbfb8aa3b, v62
	v_mul_f32_e32 v67, 0xbfb8aa3b, v63
	v_exp_f32_e32 v66, v66
	v_exp_f32_e32 v67, v67
	v_mul_f32_e32 v69, 0xbfb8aa3b, v65
	v_exp_f32_e32 v68, v68
	v_exp_f32_e32 v69, v69
	v_mul_f32_e32 v70, 0xbfb8aa3b, v58
	v_mul_f32_e32 v71, 0xbfb8aa3b, v59
	v_exp_f32_e32 v70, v70
	v_exp_f32_e32 v71, v71
	v_mul_f32_e32 v72, 0xbfb8aa3b, v60
	v_mul_f32_e32 v73, 0xbfb8aa3b, v61
	v_add_f32_e32 v66, 1.0, v66
	v_add_f32_e32 v67, 1.0, v67
	v_exp_f32_e32 v72, v72
	v_exp_f32_e32 v73, v73
	v_rcp_f32_e32 v66, v66
	v_rcp_f32_e32 v67, v67
	v_add_f32_e32 v68, 1.0, v68
	v_add_f32_e32 v69, 1.0, v69
	v_rcp_f32_e32 v68, v68
	v_rcp_f32_e32 v69, v69
	v_add_f32_e32 v70, 1.0, v70
	v_add_f32_e32 v71, 1.0, v71
	v_rcp_f32_e32 v70, v70
	v_rcp_f32_e32 v71, v71
	v_add_f32_e32 v72, 1.0, v72
	v_add_f32_e32 v73, 1.0, v73
	v_pk_mul_f32 v[62:63], v[62:63], v[66:67]
	v_rcp_f32_e32 v72, v72
	v_rcp_f32_e32 v73, v73
	v_pk_mul_f32 v[54:55], v[62:63], v[54:55]
	v_pk_mul_f32 v[62:63], v[64:65], v[68:69]
	v_cvt_pk_f16_f32 v54, v54, v55
	v_pk_mul_f32 v[56:57], v[62:63], v[56:57]
	s_nop 0
	v_cvt_pk_f16_f32 v55, v56, v57
	v_pk_mul_f32 v[56:57], v[58:59], v[70:71]
	s_nop 0
	v_pk_mul_f32 v[50:51], v[56:57], v[50:51]
	s_nop 0
	v_cvt_pk_f16_f32 v56, v50, v51
	v_pk_mul_f32 v[50:51], v[60:61], v[72:73]
	s_nop 0
	v_pk_mul_f32 v[50:51], v[50:51], v[52:53]
	v_mul_f32_e32 v52, 0xbfb8aa3b, v48
	v_cvt_pk_f16_f32 v57, v50, v51
	v_mad_i64_i32 v[50:51], s[10:11], v74, s3, v[114:115]
	v_lshl_add_u64 v[50:51], v[50:51], 0, v[116:117]
	global_store_dwordx4 v[50:51], v[54:57], off
	v_mul_f32_e32 v50, 0xbfb8aa3b, v46
	v_mul_f32_e32 v51, 0xbfb8aa3b, v47
	v_exp_f32_e32 v50, v50
	v_exp_f32_e32 v51, v51
	v_mul_f32_e32 v53, 0xbfb8aa3b, v49
	v_exp_f32_e32 v52, v52
	v_exp_f32_e32 v53, v53
	v_mul_f32_e32 v54, 0xbfb8aa3b, v42
	v_mul_f32_e32 v55, 0xbfb8aa3b, v43
	v_exp_f32_e32 v54, v54
	v_exp_f32_e32 v55, v55
	v_mul_f32_e32 v56, 0xbfb8aa3b, v44
	v_mul_f32_e32 v57, 0xbfb8aa3b, v45
	v_add_f32_e32 v50, 1.0, v50
	v_add_f32_e32 v51, 1.0, v51
	v_exp_f32_e32 v56, v56
	v_exp_f32_e32 v57, v57
	v_rcp_f32_e32 v50, v50
	v_rcp_f32_e32 v51, v51
	v_add_f32_e32 v52, 1.0, v52
	v_add_f32_e32 v53, 1.0, v53
	v_rcp_f32_e32 v52, v52
	v_rcp_f32_e32 v53, v53
	v_add_f32_e32 v54, 1.0, v54
	v_add_f32_e32 v55, 1.0, v55
	v_rcp_f32_e32 v54, v54
	v_rcp_f32_e32 v55, v55
	v_add_f32_e32 v56, 1.0, v56
	v_add_f32_e32 v57, 1.0, v57
	v_pk_mul_f32 v[46:47], v[46:47], v[50:51]
	v_rcp_f32_e32 v56, v56
	v_rcp_f32_e32 v57, v57
	v_pk_mul_f32 v[38:39], v[46:47], v[38:39]
	v_pk_mul_f32 v[46:47], v[48:49], v[52:53]
	v_cvt_pk_f16_f32 v38, v38, v39
	v_pk_mul_f32 v[40:41], v[46:47], v[40:41]
	s_nop 0
	v_cvt_pk_f16_f32 v39, v40, v41
	v_pk_mul_f32 v[40:41], v[42:43], v[54:55]
	s_nop 0
	v_pk_mul_f32 v[34:35], v[40:41], v[34:35]
	s_nop 0
	v_cvt_pk_f16_f32 v40, v34, v35
	v_pk_mul_f32 v[34:35], v[44:45], v[56:57]
	s_nop 0
	v_pk_mul_f32 v[34:35], v[34:35], v[36:37]
	v_mul_f32_e32 v36, 0xbfb8aa3b, v30
	v_cvt_pk_f16_f32 v41, v34, v35
	v_add_u32_e32 v34, 0x90, v140
	v_mad_i64_i32 v[34:35], s[10:11], v34, s3, v[114:115]
	v_lshl_add_u64 v[34:35], v[34:35], 0, v[116:117]
	global_store_dwordx4 v[34:35], v[38:41], off
	v_mul_f32_e32 v34, 0xbfb8aa3b, v28
	v_mul_f32_e32 v35, 0xbfb8aa3b, v29
	v_exp_f32_e32 v34, v34
	v_exp_f32_e32 v35, v35
	v_mul_f32_e32 v37, 0xbfb8aa3b, v31
	v_exp_f32_e32 v36, v36
	v_exp_f32_e32 v37, v37
	v_mul_f32_e32 v38, 0xbfb8aa3b, v24
	v_mul_f32_e32 v39, 0xbfb8aa3b, v25
	v_exp_f32_e32 v38, v38
	v_exp_f32_e32 v39, v39
	v_mul_f32_e32 v40, 0xbfb8aa3b, v26
	v_mul_f32_e32 v41, 0xbfb8aa3b, v27
	v_add_f32_e32 v34, 1.0, v34
	v_add_f32_e32 v35, 1.0, v35
	v_exp_f32_e32 v40, v40
	v_exp_f32_e32 v41, v41
	v_rcp_f32_e32 v34, v34
	v_rcp_f32_e32 v35, v35
	v_add_f32_e32 v36, 1.0, v36
	v_add_f32_e32 v37, 1.0, v37
	v_rcp_f32_e32 v36, v36
	v_rcp_f32_e32 v37, v37
	v_add_f32_e32 v38, 1.0, v38
	v_add_f32_e32 v39, 1.0, v39
	v_rcp_f32_e32 v38, v38
	v_rcp_f32_e32 v39, v39
	v_add_f32_e32 v40, 1.0, v40
	v_add_f32_e32 v41, 1.0, v41
	v_pk_mul_f32 v[28:29], v[28:29], v[34:35]
	v_rcp_f32_e32 v40, v40
	v_rcp_f32_e32 v41, v41
	v_pk_mul_f32 v[20:21], v[28:29], v[20:21]
	v_pk_mul_f32 v[28:29], v[30:31], v[36:37]
	v_cvt_pk_f16_f32 v20, v20, v21
	v_pk_mul_f32 v[22:23], v[28:29], v[22:23]
	s_nop 0
	v_cvt_pk_f16_f32 v21, v22, v23
	v_pk_mul_f32 v[22:23], v[24:25], v[38:39]
	s_nop 0
	v_pk_mul_f32 v[16:17], v[22:23], v[16:17]
	s_nop 0
	v_cvt_pk_f16_f32 v22, v16, v17
	v_pk_mul_f32 v[16:17], v[26:27], v[40:41]
	s_nop 0
	v_pk_mul_f32 v[16:17], v[16:17], v[18:19]
	v_mul_f32_e32 v18, 0xbfb8aa3b, v14
	v_cvt_pk_f16_f32 v23, v16, v17
	v_add_u32_e32 v16, 0xa0, v140
	v_mad_i64_i32 v[16:17], s[10:11], v16, s3, v[114:115]
	v_lshl_add_u64 v[16:17], v[16:17], 0, v[116:117]
	global_store_dwordx4 v[16:17], v[20:23], off
	v_mul_f32_e32 v16, 0xbfb8aa3b, v12
	v_mul_f32_e32 v17, 0xbfb8aa3b, v13
	v_exp_f32_e32 v16, v16
	v_exp_f32_e32 v17, v17
	v_mul_f32_e32 v19, 0xbfb8aa3b, v15
	v_exp_f32_e32 v18, v18
	v_exp_f32_e32 v19, v19
	v_mul_f32_e32 v20, 0xbfb8aa3b, v8
	v_mul_f32_e32 v21, 0xbfb8aa3b, v9
	v_exp_f32_e32 v20, v20
	v_exp_f32_e32 v21, v21
	v_mul_f32_e32 v22, 0xbfb8aa3b, v10
	v_mul_f32_e32 v23, 0xbfb8aa3b, v11
	v_add_f32_e32 v16, 1.0, v16
	v_add_f32_e32 v17, 1.0, v17
	v_exp_f32_e32 v22, v22
	v_exp_f32_e32 v23, v23
	v_rcp_f32_e32 v16, v16
	v_rcp_f32_e32 v17, v17
	v_add_f32_e32 v18, 1.0, v18
	v_add_f32_e32 v19, 1.0, v19
	v_rcp_f32_e32 v18, v18
	v_rcp_f32_e32 v19, v19
	v_add_f32_e32 v20, 1.0, v20
	v_add_f32_e32 v21, 1.0, v21
	v_rcp_f32_e32 v20, v20
	v_rcp_f32_e32 v21, v21
	v_add_f32_e32 v22, 1.0, v22
	v_add_f32_e32 v23, 1.0, v23
	v_pk_mul_f32 v[12:13], v[12:13], v[16:17]
	v_rcp_f32_e32 v22, v22
	v_rcp_f32_e32 v23, v23
	v_pk_mul_f32 v[4:5], v[12:13], v[4:5]
	v_pk_mul_f32 v[12:13], v[14:15], v[18:19]
	v_cvt_pk_f16_f32 v4, v4, v5
	v_pk_mul_f32 v[6:7], v[12:13], v[6:7]
	s_nop 0
	v_cvt_pk_f16_f32 v5, v6, v7
	v_pk_mul_f32 v[6:7], v[8:9], v[20:21]
	s_nop 0
	v_pk_mul_f32 v[0:1], v[6:7], v[0:1]
	s_nop 0
	v_cvt_pk_f16_f32 v6, v0, v1
	v_pk_mul_f32 v[0:1], v[10:11], v[22:23]
	s_nop 0
	v_pk_mul_f32 v[0:1], v[0:1], v[2:3]
	s_nop 0
	v_cvt_pk_f16_f32 v7, v0, v1
	v_add_u32_e32 v0, 0xb0, v140
	v_mad_i64_i32 v[0:1], s[10:11], v0, s3, v[114:115]
	v_lshl_add_u64 v[0:1], v[0:1], 0, v[116:117]
	global_store_dwordx4 v[0:1], v[4:7], off
	s_cmp_lg_u32 s34, 1
	s_cbranch_scc1 .Lups_skip
	s_and_b32 s0, s91, 63
	s_cmp_gt_u32 s0, 5
	s_cbranch_scc1 .Lups_skip
	s_cmp_gt_u32 s91, 196
	s_cbranch_scc1 .Lups_skip
	s_waitcnt vmcnt(0)
	s_barrier
	v_readlane_b32 s0, v251, 36
	s_cmp_lg_u32 s0, 0
	s_cbranch_scc1 .Lups_skip
	buffer_wbl2 sc1
	s_waitcnt vmcnt(0)
	v_readlane_b32 s2, v255, 45
	v_readlane_b32 s3, v254, 25
	s_lshl_b32 s2, s2, 1
	s_cmp_eq_u32 s3, 0
	s_cselect_b32 s3, 1, 0
	s_add_i32 s2, s2, s3
	s_lshl_b32 s2, s2, 2
	s_add_i32 s2, s2, 14016
	v_readlane_b32 s0, v251, 32
	v_readlane_b32 s1, v251, 33
	s_add_u32 s0, s0, s2
	s_addc_u32 s1, s1, 0
	s_mov_b64 s[2:3], exec
	s_mov_b64 exec, 1
	global_atomic_add v33, v248, s[0:1]
	s_mov_b64 exec, s[2:3]

.LBB0_1365:
	s_add_i32 s46, s14, 2
	s_add_u32 s12, s10, 0x100
	s_addc_u32 s13, s11, 0
	s_add_i32 s47, 0, 0x10000
	v_add_u32_e32 v134, s47, v230
	ds_read_b128 v[106:109], v134
	ds_read_b128 v[114:117], v134 offset:2048
	ds_read_b128 v[110:113], v134 offset:1024
	ds_read_b128 v[134:137], v134 offset:3072
	s_cmp_eq_u32 s43, s14
	s_cselect_b32 s14, s8, s44
	s_cselect_b32 s17, s7, s13
	s_cselect_b32 s16, s6, s12
	s_cselect_b32 s15, s9, s45
	v_lshl_add_u64 v[178:179], s[10:11], 0, v[184:185]
	s_add_i32 m0, s24, 0xc000
	ds_read_b128 v[138:141], v232
	ds_read_b128 v[154:157], v232 offset:2048
	ds_read_b128 v[162:165], v232 offset:4096
	ds_read_b128 v[170:173], v232 offset:6144
	ds_read_b128 v[150:153], v232 offset:1024
	ds_read_b128 v[158:161], v232 offset:3072
	ds_read_b128 v[166:169], v232 offset:5120
	ds_read_b128 v[174:177], v232 offset:7168
	global_load_lds_dwordx4 v[178:179], off
	v_lshl_add_u64 v[178:179], s[10:11], 0, v[186:187]
	s_add_i32 m0, s24, 0xe000
	s_nop 0
	global_load_lds_dwordx4 v[178:179], off
	s_waitcnt lgkmcnt(8)
	s_setprio 1
	s_barrier
	s_waitcnt lgkmcnt(7)
	v_mfma_f32_16x16x32_f16 v[146:149], v[106:109], v[138:141], v[146:149]
	v_mfma_f32_16x16x32_f16 v[142:145], v[114:117], v[138:141], v[142:145]
	s_waitcnt lgkmcnt(6)
	v_mfma_f32_16x16x32_f16 v[130:133], v[106:109], v[154:157], v[130:133]
	v_mfma_f32_16x16x32_f16 v[122:125], v[114:117], v[154:157], v[122:125]
	s_waitcnt lgkmcnt(5)
	v_mfma_f32_16x16x32_f16 v[94:97], v[106:109], v[162:165], v[94:97]
	v_mfma_f32_16x16x32_f16 v[90:93], v[114:117], v[162:165], v[90:93]
	s_waitcnt lgkmcnt(4)
	v_mfma_f32_16x16x32_f16 v[78:81], v[106:109], v[170:173], v[78:81]
	v_mfma_f32_16x16x32_f16 v[74:77], v[114:117], v[170:173], v[74:77]
	s_waitcnt lgkmcnt(3)
	v_mfma_f32_16x16x32_f16 v[146:149], v[110:113], v[150:153], v[146:149]
	v_mfma_f32_16x16x32_f16 v[142:145], v[134:137], v[150:153], v[142:145]
	s_waitcnt lgkmcnt(2)
	v_mfma_f32_16x16x32_f16 v[130:133], v[110:113], v[158:161], v[130:133]
	v_mfma_f32_16x16x32_f16 v[122:125], v[134:137], v[158:161], v[122:125]
	s_waitcnt lgkmcnt(1)
	v_mfma_f32_16x16x32_f16 v[94:97], v[110:113], v[166:169], v[94:97]
	v_mfma_f32_16x16x32_f16 v[90:93], v[134:137], v[166:169], v[90:93]
	s_waitcnt lgkmcnt(0)
	v_mfma_f32_16x16x32_f16 v[78:81], v[110:113], v[174:177], v[78:81]
	v_mfma_f32_16x16x32_f16 v[74:77], v[134:137], v[174:177], v[74:77]
	s_setprio 0
	s_barrier
	s_add_i32 s48, 0, 0x14000
	s_add_i32 s10, s47, s23
	v_add_u32_e32 v196, s48, v230
	v_lshl_add_u64 v[200:201], s[14:15], 0, v[32:33]
	s_mov_b32 m0, s10
	ds_read_b128 v[178:181], v196
	ds_read_b128 v[192:195], v196 offset:2048
	ds_read_b128 v[188:191], v196 offset:1024
	ds_read_b128 v[196:199], v196 offset:3072
	global_load_lds_dwordx4 v[200:201], off
	v_lshl_add_u64 v[202:203], s[14:15], 0, v[182:183]
	s_add_i32 m0, s10, 0x2000
	s_nop 0
	global_load_lds_dwordx4 v[202:203], off
	s_setprio 1
	s_barrier
	s_waitcnt lgkmcnt(2)
	v_mfma_f32_16x16x32_f16 v[126:129], v[178:181], v[138:141], v[126:129]
	v_mfma_f32_16x16x32_f16 v[118:121], v[192:195], v[138:141], v[118:121]
	v_mfma_f32_16x16x32_f16 v[102:105], v[178:181], v[154:157], v[102:105]
	v_mfma_f32_16x16x32_f16 v[98:101], v[192:195], v[154:157], v[98:101]
	v_mfma_f32_16x16x32_f16 v[86:89], v[178:181], v[162:165], v[86:89]
	v_mfma_f32_16x16x32_f16 v[82:85], v[192:195], v[162:165], v[82:85]
	v_mfma_f32_16x16x32_f16 v[70:73], v[178:181], v[170:173], v[70:73]
	v_mfma_f32_16x16x32_f16 v[66:69], v[192:195], v[170:173], v[66:69]
	s_waitcnt lgkmcnt(0)
	v_mfma_f32_16x16x32_f16 v[126:129], v[188:191], v[150:153], v[126:129]
	v_mfma_f32_16x16x32_f16 v[118:121], v[196:199], v[150:153], v[118:121]
	v_mfma_f32_16x16x32_f16 v[102:105], v[188:191], v[158:161], v[102:105]
	v_mfma_f32_16x16x32_f16 v[98:101], v[196:199], v[158:161], v[98:101]
	v_mfma_f32_16x16x32_f16 v[86:89], v[188:191], v[166:169], v[86:89]
	v_mfma_f32_16x16x32_f16 v[82:85], v[196:199], v[166:169], v[82:85]
	v_mfma_f32_16x16x32_f16 v[70:73], v[188:191], v[174:177], v[70:73]
	v_mfma_f32_16x16x32_f16 v[66:69], v[196:199], v[174:177], v[66:69]
	s_setprio 0
	s_mov_b32 m0, s24
	v_lshl_add_u64 v[204:205], s[16:17], 0, v[32:33]
	s_barrier
	ds_read_b128 v[138:141], v232 offset:16384
	ds_read_b128 v[154:157], v232 offset:18432
	ds_read_b128 v[162:165], v232 offset:20480
	ds_read_b128 v[170:173], v232 offset:22528
	ds_read_b128 v[150:153], v232 offset:17408
	ds_read_b128 v[158:161], v232 offset:19456
	ds_read_b128 v[166:169], v232 offset:21504
	ds_read_b128 v[174:177], v232 offset:23552
	global_load_lds_dwordx4 v[204:205], off
	v_lshl_add_u64 v[206:207], s[16:17], 0, v[182:183]
	s_mov_b32 m0, s25
	s_nop 0
	global_load_lds_dwordx4 v[206:207], off
	s_setprio 1
	s_barrier
	s_waitcnt lgkmcnt(7)
	v_mfma_f32_16x16x32_f16 v[62:65], v[106:109], v[138:141], v[62:65]
	v_mfma_f32_16x16x32_f16 v[58:61], v[114:117], v[138:141], v[58:61]
	s_waitcnt lgkmcnt(6)
	v_mfma_f32_16x16x32_f16 v[46:49], v[106:109], v[154:157], v[46:49]
	v_mfma_f32_16x16x32_f16 v[42:45], v[114:117], v[154:157], v[42:45]
	s_waitcnt lgkmcnt(5)
	v_mfma_f32_16x16x32_f16 v[28:31], v[106:109], v[162:165], v[28:31]
	v_mfma_f32_16x16x32_f16 v[24:27], v[114:117], v[162:165], v[24:27]
	s_waitcnt lgkmcnt(4)
	v_mfma_f32_16x16x32_f16 v[12:15], v[106:109], v[170:173], v[12:15]
	v_mfma_f32_16x16x32_f16 v[8:11], v[114:117], v[170:173], v[8:11]
	s_waitcnt lgkmcnt(3)
	v_mfma_f32_16x16x32_f16 v[62:65], v[110:113], v[150:153], v[62:65]
	v_mfma_f32_16x16x32_f16 v[58:61], v[134:137], v[150:153], v[58:61]
	s_waitcnt lgkmcnt(2)
	v_mfma_f32_16x16x32_f16 v[46:49], v[110:113], v[158:161], v[46:49]
	v_mfma_f32_16x16x32_f16 v[42:45], v[134:137], v[158:161], v[42:45]
	s_waitcnt lgkmcnt(1)
	v_mfma_f32_16x16x32_f16 v[28:31], v[110:113], v[166:169], v[28:31]
	v_mfma_f32_16x16x32_f16 v[24:27], v[134:137], v[166:169], v[24:27]
	s_waitcnt lgkmcnt(0)
	v_mfma_f32_16x16x32_f16 v[12:15], v[110:113], v[174:177], v[12:15]
	v_mfma_f32_16x16x32_f16 v[8:11], v[134:137], v[174:177], v[8:11]
	s_setprio 0
	s_barrier
	s_add_u32 s10, s14, 0xb0000
	s_addc_u32 s11, s15, 0
	s_add_i32 s47, s48, s23
	v_lshl_add_u64 v[106:107], s[10:11], 0, v[32:33]
	s_mov_b32 m0, s47
	s_nop 0
	global_load_lds_dwordx4 v[106:107], off
	v_lshl_add_u64 v[106:107], s[10:11], 0, v[182:183]
	s_add_i32 m0, s47, 0x2000
	s_nop 0
	global_load_lds_dwordx4 v[106:107], off
	s_waitcnt vmcnt(6)
	s_setprio 1
	s_barrier
	v_mfma_f32_16x16x32_f16 v[54:57], v[178:181], v[138:141], v[54:57]
	v_mfma_f32_16x16x32_f16 v[50:53], v[192:195], v[138:141], v[50:53]
	v_mfma_f32_16x16x32_f16 v[38:41], v[178:181], v[154:157], v[38:41]
	v_mfma_f32_16x16x32_f16 v[34:37], v[192:195], v[154:157], v[34:37]
	v_mfma_f32_16x16x32_f16 v[20:23], v[178:181], v[162:165], v[20:23]
	v_mfma_f32_16x16x32_f16 v[16:19], v[192:195], v[162:165], v[16:19]
	v_mfma_f32_16x16x32_f16 v[4:7], v[178:181], v[170:173], v[4:7]
	v_mfma_f32_16x16x32_f16 v[0:3], v[192:195], v[170:173], v[0:3]
	v_mfma_f32_16x16x32_f16 v[54:57], v[188:191], v[150:153], v[54:57]
	v_mfma_f32_16x16x32_f16 v[50:53], v[196:199], v[150:153], v[50:53]
	v_mfma_f32_16x16x32_f16 v[38:41], v[188:191], v[158:161], v[38:41]
	v_mfma_f32_16x16x32_f16 v[34:37], v[196:199], v[158:161], v[34:37]
	v_mfma_f32_16x16x32_f16 v[20:23], v[188:191], v[166:169], v[20:23]
	v_mfma_f32_16x16x32_f16 v[16:19], v[196:199], v[166:169], v[16:19]
	v_mfma_f32_16x16x32_f16 v[4:7], v[188:191], v[174:177], v[4:7]
	v_mfma_f32_16x16x32_f16 v[0:3], v[196:199], v[174:177], v[0:3]
	s_setprio 0
	s_add_i32 s47, 0, 0x18000
	v_add_u32_e32 v134, s47, v230
	s_barrier
	ds_read_b128 v[106:109], v134
	ds_read_b128 v[114:117], v134 offset:2048
	ds_read_b128 v[110:113], v134 offset:1024
	ds_read_b128 v[134:137], v134 offset:3072
	s_add_u32 s10, s16, 0xb0000
	s_addc_u32 s11, s17, 0
	s_mov_b32 m0, s26
	v_lshl_add_u64 v[178:179], s[10:11], 0, v[32:33]
	ds_read_b128 v[138:141], v232 offset:32768
	ds_read_b128 v[154:157], v232 offset:34816
	ds_read_b128 v[162:165], v232 offset:36864
	ds_read_b128 v[170:173], v232 offset:38912
	ds_read_b128 v[150:153], v232 offset:33792
	ds_read_b128 v[158:161], v232 offset:35840
	ds_read_b128 v[166:169], v232 offset:37888
	ds_read_b128 v[174:177], v232 offset:39936
	global_load_lds_dwordx4 v[178:179], off
	v_lshl_add_u64 v[178:179], s[10:11], 0, v[182:183]
	s_mov_b32 m0, s27
	s_nop 0
	global_load_lds_dwordx4 v[178:179], off
	s_waitcnt lgkmcnt(8)
	s_setprio 1
	s_barrier
	s_waitcnt lgkmcnt(7)
	v_mfma_f32_16x16x32_f16 v[146:149], v[106:109], v[138:141], v[146:149]
	v_mfma_f32_16x16x32_f16 v[142:145], v[114:117], v[138:141], v[142:145]
	s_waitcnt lgkmcnt(6)
	v_mfma_f32_16x16x32_f16 v[130:133], v[106:109], v[154:157], v[130:133]
	v_mfma_f32_16x16x32_f16 v[122:125], v[114:117], v[154:157], v[122:125]
	s_waitcnt lgkmcnt(5)
	v_mfma_f32_16x16x32_f16 v[94:97], v[106:109], v[162:165], v[94:97]
	v_mfma_f32_16x16x32_f16 v[90:93], v[114:117], v[162:165], v[90:93]
	s_waitcnt lgkmcnt(4)
	v_mfma_f32_16x16x32_f16 v[78:81], v[106:109], v[170:173], v[78:81]
	v_mfma_f32_16x16x32_f16 v[74:77], v[114:117], v[170:173], v[74:77]
	s_waitcnt lgkmcnt(3)
	v_mfma_f32_16x16x32_f16 v[146:149], v[110:113], v[150:153], v[146:149]
	v_mfma_f32_16x16x32_f16 v[142:145], v[134:137], v[150:153], v[142:145]
	s_waitcnt lgkmcnt(2)
	v_mfma_f32_16x16x32_f16 v[130:133], v[110:113], v[158:161], v[130:133]
	v_mfma_f32_16x16x32_f16 v[122:125], v[134:137], v[158:161], v[122:125]
	s_waitcnt lgkmcnt(1)
	v_mfma_f32_16x16x32_f16 v[94:97], v[110:113], v[166:169], v[94:97]
	v_mfma_f32_16x16x32_f16 v[90:93], v[134:137], v[166:169], v[90:93]
	s_waitcnt lgkmcnt(0)
	v_mfma_f32_16x16x32_f16 v[78:81], v[110:113], v[174:177], v[78:81]
	v_mfma_f32_16x16x32_f16 v[74:77], v[134:137], v[174:177], v[74:77]
	s_setprio 0
	s_barrier
	s_add_i32 s16, 0, 0x1c000
	s_add_i32 s10, s47, s23
	v_add_u32_e32 v196, s16, v230
	v_lshl_add_u64 v[200:201], v[200:201], 0, s[84:85]
	s_mov_b32 m0, s10
	ds_read_b128 v[178:181], v196
	ds_read_b128 v[192:195], v196 offset:2048
	ds_read_b128 v[188:191], v196 offset:1024
	ds_read_b128 v[196:199], v196 offset:3072
	global_load_lds_dwordx4 v[200:201], off
	v_lshl_add_u64 v[200:201], v[202:203], 0, s[84:85]
	s_add_i32 m0, s10, 0x2000
	s_nop 0
	global_load_lds_dwordx4 v[200:201], off
	s_setprio 1
	s_barrier
	s_waitcnt lgkmcnt(2)
	v_mfma_f32_16x16x32_f16 v[126:129], v[178:181], v[138:141], v[126:129]
	v_mfma_f32_16x16x32_f16 v[118:121], v[192:195], v[138:141], v[118:121]
	v_mfma_f32_16x16x32_f16 v[102:105], v[178:181], v[154:157], v[102:105]
	v_mfma_f32_16x16x32_f16 v[98:101], v[192:195], v[154:157], v[98:101]
	v_mfma_f32_16x16x32_f16 v[86:89], v[178:181], v[162:165], v[86:89]
	v_mfma_f32_16x16x32_f16 v[82:85], v[192:195], v[162:165], v[82:85]
	v_mfma_f32_16x16x32_f16 v[70:73], v[178:181], v[170:173], v[70:73]
	v_mfma_f32_16x16x32_f16 v[66:69], v[192:195], v[170:173], v[66:69]
	s_waitcnt lgkmcnt(0)
	v_mfma_f32_16x16x32_f16 v[126:129], v[188:191], v[150:153], v[126:129]
	v_mfma_f32_16x16x32_f16 v[118:121], v[196:199], v[150:153], v[118:121]
	v_mfma_f32_16x16x32_f16 v[102:105], v[188:191], v[158:161], v[102:105]
	v_mfma_f32_16x16x32_f16 v[98:101], v[196:199], v[158:161], v[98:101]
	v_mfma_f32_16x16x32_f16 v[86:89], v[188:191], v[166:169], v[86:89]
	v_mfma_f32_16x16x32_f16 v[82:85], v[196:199], v[166:169], v[82:85]
	v_mfma_f32_16x16x32_f16 v[70:73], v[188:191], v[174:177], v[70:73]
	v_mfma_f32_16x16x32_f16 v[66:69], v[196:199], v[174:177], v[66:69]
	s_setprio 0
	s_mov_b32 m0, s29
	v_lshl_add_u64 v[200:201], v[204:205], 0, s[84:85]
	s_barrier
	ds_read_b128 v[138:141], v232 offset:49152
	ds_read_b128 v[154:157], v232 offset:51200
	ds_read_b128 v[162:165], v232 offset:53248
	ds_read_b128 v[170:173], v232 offset:55296
	ds_read_b128 v[150:153], v232 offset:50176
	ds_read_b128 v[158:161], v232 offset:52224
	ds_read_b128 v[166:169], v232 offset:54272
	ds_read_b128 v[174:177], v232 offset:56320
	global_load_lds_dwordx4 v[200:201], off
	v_lshl_add_u64 v[200:201], v[206:207], 0, s[84:85]
	s_mov_b32 m0, s30
	s_nop 0
	global_load_lds_dwordx4 v[200:201], off
	s_setprio 1
	s_barrier
	s_waitcnt lgkmcnt(7)
	v_mfma_f32_16x16x32_f16 v[62:65], v[106:109], v[138:141], v[62:65]
	v_mfma_f32_16x16x32_f16 v[58:61], v[114:117], v[138:141], v[58:61]
	s_waitcnt lgkmcnt(6)
	v_mfma_f32_16x16x32_f16 v[46:49], v[106:109], v[154:157], v[46:49]
	v_mfma_f32_16x16x32_f16 v[42:45], v[114:117], v[154:157], v[42:45]
	s_waitcnt lgkmcnt(5)
	v_mfma_f32_16x16x32_f16 v[28:31], v[106:109], v[162:165], v[28:31]
	v_mfma_f32_16x16x32_f16 v[24:27], v[114:117], v[162:165], v[24:27]
	s_waitcnt lgkmcnt(4)
	v_mfma_f32_16x16x32_f16 v[12:15], v[106:109], v[170:173], v[12:15]
	v_mfma_f32_16x16x32_f16 v[8:11], v[114:117], v[170:173], v[8:11]
	s_waitcnt lgkmcnt(3)
	v_mfma_f32_16x16x32_f16 v[62:65], v[110:113], v[150:153], v[62:65]
	v_mfma_f32_16x16x32_f16 v[58:61], v[134:137], v[150:153], v[58:61]
	s_waitcnt lgkmcnt(2)
	v_mfma_f32_16x16x32_f16 v[46:49], v[110:113], v[158:161], v[46:49]
	v_mfma_f32_16x16x32_f16 v[42:45], v[134:137], v[158:161], v[42:45]
	s_waitcnt lgkmcnt(1)
	v_mfma_f32_16x16x32_f16 v[28:31], v[110:113], v[166:169], v[28:31]
	v_mfma_f32_16x16x32_f16 v[24:27], v[134:137], v[166:169], v[24:27]
	s_waitcnt lgkmcnt(0)
	v_mfma_f32_16x16x32_f16 v[12:15], v[110:113], v[174:177], v[12:15]
	v_mfma_f32_16x16x32_f16 v[8:11], v[134:137], v[174:177], v[8:11]
	s_setprio 0
	s_barrier
	s_add_u32 s10, s14, 0xb0080
	s_addc_u32 s11, s15, 0
	s_add_i32 s14, s16, s23
	v_lshl_add_u64 v[106:107], s[10:11], 0, v[32:33]
	s_mov_b32 m0, s14
	s_nop 0
	global_load_lds_dwordx4 v[106:107], off
	v_lshl_add_u64 v[106:107], s[10:11], 0, v[182:183]
	s_add_i32 m0, s14, 0x2000
	s_nop 0
	global_load_lds_dwordx4 v[106:107], off
	s_waitcnt vmcnt(6)
	s_setprio 1
	s_barrier
	v_mfma_f32_16x16x32_f16 v[54:57], v[178:181], v[138:141], v[54:57]
	v_mfma_f32_16x16x32_f16 v[50:53], v[192:195], v[138:141], v[50:53]
	v_mfma_f32_16x16x32_f16 v[38:41], v[178:181], v[154:157], v[38:41]
	v_mfma_f32_16x16x32_f16 v[34:37], v[192:195], v[154:157], v[34:37]
	v_mfma_f32_16x16x32_f16 v[20:23], v[178:181], v[162:165], v[20:23]
	v_mfma_f32_16x16x32_f16 v[16:19], v[192:195], v[162:165], v[16:19]
	v_mfma_f32_16x16x32_f16 v[4:7], v[178:181], v[170:173], v[4:7]
	v_mfma_f32_16x16x32_f16 v[0:3], v[192:195], v[170:173], v[0:3]
	v_mfma_f32_16x16x32_f16 v[54:57], v[188:191], v[150:153], v[54:57]
	v_mfma_f32_16x16x32_f16 v[50:53], v[196:199], v[150:153], v[50:53]
	v_mfma_f32_16x16x32_f16 v[38:41], v[188:191], v[158:161], v[38:41]
	v_mfma_f32_16x16x32_f16 v[34:37], v[196:199], v[158:161], v[34:37]
	v_mfma_f32_16x16x32_f16 v[20:23], v[188:191], v[166:169], v[20:23]
	v_mfma_f32_16x16x32_f16 v[16:19], v[196:199], v[166:169], v[16:19]
	v_mfma_f32_16x16x32_f16 v[4:7], v[188:191], v[174:177], v[4:7]
	v_mfma_f32_16x16x32_f16 v[0:3], v[196:199], v[174:177], v[0:3]
	s_setprio 0
	s_add_u32 s44, s44, 0x100
	s_addc_u32 s45, s45, 0
	s_cmp_ge_u32 s46, s42
	s_mov_b64 s[10:11], s[12:13]
	s_mov_b32 s14, s46
	s_barrier
	s_cbranch_scc0 .LBB0_1365
	s_cmp_eq_u32 s40, 0
	s_cselect_b32 s6, 0x9000, 0
	v_lshl_or_b32 v106, s41, 8, v231
	s_add_u32 s6, s31, s6
	s_addc_u32 s7, s34, 0
	v_ashrrev_i32_e32 v107, 31, v106
	v_lshl_add_u64 v[116:117], v[106:107], 2, s[6:7]
	global_load_dwordx4 v[108:111], v[116:117], off offset:16
	global_load_dwordx4 v[112:115], v[116:117], off
	s_cmp_eq_u32 s39, 0
	s_waitcnt vmcnt(0)
	v_pk_mul_f32 v[194:195], v[110:111], 0.5 op_sel_hi:[1,0]
	v_pk_mul_f32 v[198:199], v[114:115], 0.5 op_sel_hi:[1,0]
	v_pk_mul_f32 v[202:203], v[112:113], 0.5 op_sel_hi:[1,0]
	v_pk_mul_f32 v[200:201], v[108:109], 0.5 op_sel_hi:[1,0]
	global_load_dwordx4 v[108:111], v[116:117], off offset:528
	global_load_dwordx4 v[112:115], v[116:117], off offset:512
	s_waitcnt vmcnt(0)
	v_pk_mul_f32 v[188:189], v[110:111], 0.5 op_sel_hi:[1,0]
	v_pk_mul_f32 v[196:197], v[112:113], 0.5 op_sel_hi:[1,0]
	v_lshl_add_u32 v112, s40, 8, v229
	v_pk_mul_f32 v[190:191], v[114:115], 0.5 op_sel_hi:[1,0]
	v_pk_mul_f32 v[192:193], v[108:109], 0.5 op_sel_hi:[1,0]
	v_or_b32_e32 v114, 16, v112
	v_or_b32_e32 v110, 32, v112
	v_or_b32_e32 v108, 48, v112
	v_ashrrev_i32_e32 v113, 31, v112
	v_ashrrev_i32_e32 v115, 31, v114
	v_ashrrev_i32_e32 v111, 31, v110
	v_ashrrev_i32_e32 v109, 31, v108
	s_cbranch_scc1 .LBB0_1368
	s_add_i32 s96, s39, -1
	s_lshl_b64 s[6:7], s[96:97], 20
	v_readlane_b32 s8, v252, 11
	v_readlane_b32 s9, v252, 12
	s_add_u32 s6, s8, s6
	s_addc_u32 s7, s9, s7
	v_lshlrev_b64 v[138:139], 2, v[106:107]
	v_lshrrev_b32_e32 v150, 5, v220
	v_mul_u32_u24_e32 v150, 48, v150
	s_nop 0
	v_sub_co_u32_e32 v138, vcc, v138, v150
	s_nop 1
	v_subbrev_co_u32_e32 v139, vcc, 0, v139, vcc
	v_lshl_add_u64 v[138:139], s[6:7], 0, v[138:139]
	s_mov_b64 s[6:7], 0x80000
	v_lshlrev_b64 v[204:205], 12, v[112:113]
	v_lshl_add_u64 v[204:205], v[204:205], 0, v[138:139]
	v_lshl_add_u64 v[212:213], v[204:205], 0, s[6:7]
	v_lshlrev_b64 v[206:207], 12, v[114:115]
	v_lshl_add_u64 v[206:207], v[206:207], 0, v[138:139]
	v_lshl_add_u64 v[214:215], v[206:207], 0, s[6:7]
	v_lshlrev_b64 v[208:209], 12, v[110:111]
	v_lshl_add_u64 v[208:209], v[208:209], 0, v[138:139]
	v_lshl_add_u64 v[216:217], v[208:209], 0, s[6:7]
	v_lshlrev_b64 v[210:211], 12, v[108:109]
	v_lshl_add_u64 v[210:211], v[210:211], 0, v[138:139]
	v_lshl_add_u64 v[218:219], v[210:211], 0, s[6:7]
	s_waitcnt vmcnt(0)
	v_pk_mul_f32 v[152:153], v[146:147], v[202:203]
	v_pk_mul_f32 v[154:155], v[148:149], v[198:199]
	v_pk_mul_f32 v[156:157], v[142:143], v[200:201]
	v_pk_mul_f32 v[158:159], v[144:145], v[194:195]
	s_nop 1
	v_permlane32_swap_b32_e32 v152, v156
	v_permlane32_swap_b32_e32 v153, v157
	v_permlane32_swap_b32_e32 v154, v158
	v_permlane32_swap_b32_e32 v155, v159
	s_nop 0
	global_store_dwordx4 v[204:205], v[152:155], off
	global_store_dwordx4 v[204:205], v[156:159], off offset:64
	v_pk_mul_f32 v[160:161], v[126:127], v[196:197]
	v_pk_mul_f32 v[162:163], v[128:129], v[190:191]
	v_pk_mul_f32 v[164:165], v[118:119], v[192:193]
	v_pk_mul_f32 v[166:167], v[120:121], v[188:189]
	s_nop 1
	v_permlane32_swap_b32_e32 v160, v164
	v_permlane32_swap_b32_e32 v161, v165
	v_permlane32_swap_b32_e32 v162, v166
	v_permlane32_swap_b32_e32 v163, v167
	s_nop 0
	global_store_dwordx4 v[204:205], v[160:163], off offset:512
	global_store_dwordx4 v[204:205], v[164:167], off offset:576
	v_pk_mul_f32 v[168:169], v[130:131], v[202:203]
	v_pk_mul_f32 v[170:171], v[132:133], v[198:199]
	v_pk_mul_f32 v[172:173], v[122:123], v[200:201]
	v_pk_mul_f32 v[174:175], v[124:125], v[194:195]
	s_nop 1
	v_permlane32_swap_b32_e32 v168, v172
	v_permlane32_swap_b32_e32 v169, v173
	v_permlane32_swap_b32_e32 v170, v174
	v_permlane32_swap_b32_e32 v171, v175
	s_nop 0
	global_store_dwordx4 v[206:207], v[168:171], off
	global_store_dwordx4 v[206:207], v[172:175], off offset:64
	v_pk_mul_f32 v[176:177], v[102:103], v[196:197]
	v_pk_mul_f32 v[178:179], v[104:105], v[190:191]
	v_pk_mul_f32 v[180:181], v[98:99], v[192:193]
	v_pk_mul_f32 v[182:183], v[100:101], v[188:189]
	s_nop 1
	v_permlane32_swap_b32_e32 v176, v180
	v_permlane32_swap_b32_e32 v177, v181
	v_permlane32_swap_b32_e32 v178, v182
	v_permlane32_swap_b32_e32 v179, v183
	s_nop 0
	global_store_dwordx4 v[206:207], v[176:179], off offset:512
	global_store_dwordx4 v[206:207], v[180:183], off offset:576
	v_pk_mul_f32 v[152:153], v[94:95], v[202:203]
	v_pk_mul_f32 v[154:155], v[96:97], v[198:199]
	v_pk_mul_f32 v[156:157], v[90:91], v[200:201]
	v_pk_mul_f32 v[158:159], v[92:93], v[194:195]
	s_nop 1
	v_permlane32_swap_b32_e32 v152, v156
	v_permlane32_swap_b32_e32 v153, v157
	v_permlane32_swap_b32_e32 v154, v158
	v_permlane32_swap_b32_e32 v155, v159
	s_nop 0
	global_store_dwordx4 v[208:209], v[152:155], off
	global_store_dwordx4 v[208:209], v[156:159], off offset:64
	v_pk_mul_f32 v[160:161], v[86:87], v[196:197]
	v_pk_mul_f32 v[162:163], v[88:89], v[190:191]
	v_pk_mul_f32 v[164:165], v[82:83], v[192:193]
	v_pk_mul_f32 v[166:167], v[84:85], v[188:189]
	s_nop 1
	v_permlane32_swap_b32_e32 v160, v164
	v_permlane32_swap_b32_e32 v161, v165
	v_permlane32_swap_b32_e32 v162, v166
	v_permlane32_swap_b32_e32 v163, v167
	s_nop 0
	global_store_dwordx4 v[208:209], v[160:163], off offset:512
	global_store_dwordx4 v[208:209], v[164:167], off offset:576
	v_pk_mul_f32 v[168:169], v[78:79], v[202:203]
	v_pk_mul_f32 v[170:171], v[80:81], v[198:199]
	v_pk_mul_f32 v[172:173], v[74:75], v[200:201]
	v_pk_mul_f32 v[174:175], v[76:77], v[194:195]
	s_nop 1
	v_permlane32_swap_b32_e32 v168, v172
	v_permlane32_swap_b32_e32 v169, v173
	v_permlane32_swap_b32_e32 v170, v174
	v_permlane32_swap_b32_e32 v171, v175
	s_nop 0
	global_store_dwordx4 v[210:211], v[168:171], off
	global_store_dwordx4 v[210:211], v[172:175], off offset:64
	v_pk_mul_f32 v[176:177], v[70:71], v[196:197]
	v_pk_mul_f32 v[178:179], v[72:73], v[190:191]
	v_pk_mul_f32 v[180:181], v[66:67], v[192:193]
	v_pk_mul_f32 v[182:183], v[68:69], v[188:189]
	s_nop 1
	v_permlane32_swap_b32_e32 v176, v180
	v_permlane32_swap_b32_e32 v177, v181
	v_permlane32_swap_b32_e32 v178, v182
	v_permlane32_swap_b32_e32 v179, v183
	s_nop 0
	global_store_dwordx4 v[210:211], v[176:179], off offset:512
	global_store_dwordx4 v[210:211], v[180:183], off offset:576
	v_pk_mul_f32 v[152:153], v[62:63], v[202:203]
	v_pk_mul_f32 v[154:155], v[64:65], v[198:199]
	v_pk_mul_f32 v[156:157], v[58:59], v[200:201]
	v_pk_mul_f32 v[158:159], v[60:61], v[194:195]
	s_nop 1
	v_permlane32_swap_b32_e32 v152, v156
	v_permlane32_swap_b32_e32 v153, v157
	v_permlane32_swap_b32_e32 v154, v158
	v_permlane32_swap_b32_e32 v155, v159
	s_nop 0
	global_store_dwordx4 v[212:213], v[152:155], off
	global_store_dwordx4 v[212:213], v[156:159], off offset:64
	v_pk_mul_f32 v[160:161], v[54:55], v[196:197]
	v_pk_mul_f32 v[162:163], v[56:57], v[190:191]
	v_pk_mul_f32 v[164:165], v[50:51], v[192:193]
	v_pk_mul_f32 v[166:167], v[52:53], v[188:189]
	s_nop 1
	v_permlane32_swap_b32_e32 v160, v164
	v_permlane32_swap_b32_e32 v161, v165
	v_permlane32_swap_b32_e32 v162, v166
	v_permlane32_swap_b32_e32 v163, v167
	s_nop 0
	global_store_dwordx4 v[212:213], v[160:163], off offset:512
	global_store_dwordx4 v[212:213], v[164:167], off offset:576
	v_pk_mul_f32 v[168:169], v[46:47], v[202:203]
	v_pk_mul_f32 v[170:171], v[48:49], v[198:199]
	v_pk_mul_f32 v[172:173], v[42:43], v[200:201]
	v_pk_mul_f32 v[174:175], v[44:45], v[194:195]
	s_nop 1
	v_permlane32_swap_b32_e32 v168, v172
	v_permlane32_swap_b32_e32 v169, v173
	v_permlane32_swap_b32_e32 v170, v174
	v_permlane32_swap_b32_e32 v171, v175
	s_nop 0
	global_store_dwordx4 v[214:215], v[168:171], off
	global_store_dwordx4 v[214:215], v[172:175], off offset:64
	v_pk_mul_f32 v[176:177], v[38:39], v[196:197]
	v_pk_mul_f32 v[178:179], v[40:41], v[190:191]
	v_pk_mul_f32 v[180:181], v[34:35], v[192:193]
	v_pk_mul_f32 v[182:183], v[36:37], v[188:189]
	s_nop 1
	v_permlane32_swap_b32_e32 v176, v180
	v_permlane32_swap_b32_e32 v177, v181
	v_permlane32_swap_b32_e32 v178, v182
	v_permlane32_swap_b32_e32 v179, v183
	s_nop 0
	global_store_dwordx4 v[214:215], v[176:179], off offset:512
	global_store_dwordx4 v[214:215], v[180:183], off offset:576
	v_pk_mul_f32 v[152:153], v[28:29], v[202:203]
	v_pk_mul_f32 v[154:155], v[30:31], v[198:199]
	v_pk_mul_f32 v[156:157], v[24:25], v[200:201]
	v_pk_mul_f32 v[158:159], v[26:27], v[194:195]
	s_nop 1
	v_permlane32_swap_b32_e32 v152, v156
	v_permlane32_swap_b32_e32 v153, v157
	v_permlane32_swap_b32_e32 v154, v158
	v_permlane32_swap_b32_e32 v155, v159
	s_nop 0
	global_store_dwordx4 v[216:217], v[152:155], off
	global_store_dwordx4 v[216:217], v[156:159], off offset:64
	v_pk_mul_f32 v[160:161], v[20:21], v[196:197]
	v_pk_mul_f32 v[162:163], v[22:23], v[190:191]
	v_pk_mul_f32 v[164:165], v[16:17], v[192:193]
	v_pk_mul_f32 v[166:167], v[18:19], v[188:189]
	s_nop 1
	v_permlane32_swap_b32_e32 v160, v164
	v_permlane32_swap_b32_e32 v161, v165
	v_permlane32_swap_b32_e32 v162, v166
	v_permlane32_swap_b32_e32 v163, v167
	s_nop 0
	global_store_dwordx4 v[216:217], v[160:163], off offset:512
	global_store_dwordx4 v[216:217], v[164:167], off offset:576
	v_pk_mul_f32 v[168:169], v[12:13], v[202:203]
	v_pk_mul_f32 v[170:171], v[14:15], v[198:199]
	v_pk_mul_f32 v[172:173], v[8:9], v[200:201]
	v_pk_mul_f32 v[174:175], v[10:11], v[194:195]
	s_nop 1
	v_permlane32_swap_b32_e32 v168, v172
	v_permlane32_swap_b32_e32 v169, v173
	v_permlane32_swap_b32_e32 v170, v174
	v_permlane32_swap_b32_e32 v171, v175
	s_nop 0
	global_store_dwordx4 v[218:219], v[168:171], off
	global_store_dwordx4 v[218:219], v[172:175], off offset:64
	v_pk_mul_f32 v[176:177], v[4:5], v[196:197]
	v_pk_mul_f32 v[178:179], v[6:7], v[190:191]
	v_pk_mul_f32 v[180:181], v[0:1], v[192:193]
	v_pk_mul_f32 v[182:183], v[2:3], v[188:189]
	s_nop 1
	v_permlane32_swap_b32_e32 v176, v180
	v_permlane32_swap_b32_e32 v177, v181
	v_permlane32_swap_b32_e32 v178, v182
	v_permlane32_swap_b32_e32 v179, v183
	s_nop 0
	global_store_dwordx4 v[218:219], v[176:179], off offset:512
	global_store_dwordx4 v[218:219], v[180:183], off offset:576
	s_cbranch_execnz .LBB0_1352
	s_branch .LBB0_1351
